# v15 stack + GEMM K-loop LDS-DMA issues in saddr form (no 64-bit VALU address adds in the load segments)
# baseline (speedup 1.0000x reference)
; #define PG8_STAGE(bufoff, gbase, voff) do { _Pragma("unroll") for (int _i = 0; _i < 2; ++_i) \
;         __builtin_amdgcn_global_load_lds((const unsigned*)((const char*)(gbase) + (voff)[_i]), (PG8_LAS unsigned*)(lds + (bufoff) + ldsw + _i * 8192), 16, 0, 0); } while (0)
; #define PG8_LDA(dst, b, h) do { _Pragma("unroll") for (int m = 0; m < 4; ++m) _Pragma("unroll") for (int k = 0; k < 2; ++k) dst[m][k] = *(const PG8_LAS bf16x8*)(lds + PG8_SA(b, h) + aoff + m * 2048 + k * 1024); } while (0)
; template <class Epi, class Sched, bool ALIGN_EPI = false, bool SP2 = false>
; __device__ __forceinline__ void gemm_phase(PG8_LAS unsigned char* lds, const Gemm g, const Sched& S, const Epi& E) {
;     ...
;         const bool has_next = S.next(ui + 1, nxt);
;         const char* nA = has_next ? (const char*)g.A + (size_t)nxt.pm * tstepA : cA; const char* nB = has_next ? (const char*)g.Bt + (size_t)nxt.pn * tstepB : cB;
;         for (int t = 0; t < nt; t += 2) {
;             const bool last = (t == nt - 2);
;             const char* a1 = cA + (size_t)(t + 1) * kstep;
;             const char* a2 = last ? nA : cA + (size_t)(t + 2) * kstep; const char* b2 = last ? nB : cB + (size_t)(t + 2) * kstep;
;             const char* a3 = a2 + kstep; const char* b3 = b2 + kstep;
;             if (last && has_next) S.a_ready(nxt);
;             if constexpr (SP2) {
;             PG8_LDB(B0, 0, 0); PG8_LDB(B1, 0, 1); PG8_SCHED; PG8_LDA(At, 0, 0); PG8_STAGE(PG8_SA(1, 1), a1 + hstepA, voffA);
;             PG8_WAIT_V(8); PG8_WAIT_L(0); PG8_BAR; PG8_MMA(0, 0, At, B0); PG8_MMA(0, 1, At, B1); PG8_BAR; PG8_SCHED;
;             PG8_LDA(At, 0, 1); PG8_STAGE(PG8_SB(0, 0), b2, voffB); PG8_STAGE(PG8_SB(0, 1), b2 + hstepB, voffB); PG8_STAGE(PG8_SA(0, 0), a2, voffA);
;             PG8_WAIT_V(8); PG8_WAIT_L(0); PG8_BAR; PG8_MMA(1, 0, At, B0); PG8_MMA(1, 1, At, B1); PG8_BAR; PG8_SCHED;
;             PG8_LDB(B0, 1, 0); PG8_LDB(B1, 1, 1); PG8_SCHED; PG8_LDA(At, 1, 0); PG8_STAGE(PG8_SA(0, 1), a2 + hstepA, voffA);
;             PG8_WAIT_V(8); PG8_WAIT_L(0); PG8_BAR; PG8_MMA(0, 0, At, B0); PG8_MMA(0, 1, At, B1); PG8_BAR; PG8_SCHED;
;             PG8_LDA(At, 1, 1); PG8_STAGE(PG8_SB(1, 0), b3, voffB); PG8_STAGE(PG8_SB(1, 1), b3 + hstepB, voffB); PG8_STAGE(PG8_SA(1, 0), a3, voffA);
;             PG8_WAIT_V(8); PG8_WAIT_L(0); PG8_BAR; PG8_MMA(1, 0, At, B0); PG8_MMA(1, 1, At, B1); PG8_BAR; PG8_SCHED;
.LBB0_163:
	ds_read_b128 v[0:3], v143
	ds_read_b128 v[4:7], v143 offset:1024
	ds_read_b128 v[8:11], v143 offset:2048
	ds_read_b128 v[12:15], v143 offset:3072
	ds_read_b128 v[16:19], v144
	ds_read_b128 v[20:23], v144 offset:1024
	ds_read_b128 v[24:27], v144 offset:2048
	ds_read_b128 v[28:31], v144 offset:3072
	s_ashr_i32 s31, s30, 31
	s_lshl_b64 s[34:35], s[30:31], 17
	s_add_u32 s34, s54, s34
	s_addc_u32 s35, s55, s35
	s_and_b64 s[36:37], s[0:1], exec
	s_cselect_b32 s51, s35, s39
	s_cselect_b32 s50, s34, s38
	s_ashr_i32 s29, s28, 31
	s_lshl_b64 s[36:37], s[28:29], 17
	s_add_u32 s36, s2, s36
	s_addc_u32 s37, s3, s37
	s_and_b64 s[44:45], s[0:1], exec
	s_cselect_b32 s47, s37, s41
	s_cselect_b32 s46, s36, s40
	s_add_u32 s44, s38, 0x10080
	s_addc_u32 s45, s39, 0
	s_add_i32 s63, s9, 0xc000
	s_mov_b32 m0, s63
	s_add_i32 s29, s9, 0xe000
	ds_read_b128 v[32:35], v145
	ds_read_b128 v[36:39], v145 offset:1024
	ds_read_b128 v[40:43], v145 offset:2048
	ds_read_b128 v[44:47], v145 offset:3072
	ds_read_b128 v[48:51], v145 offset:4096
	ds_read_b128 v[52:55], v145 offset:5120
	ds_read_b128 v[56:59], v145 offset:6144
	ds_read_b128 v[60:63], v145 offset:7168
	global_load_lds_dwordx4 v128, s[44:45]
	s_mov_b32 m0, s29
	s_nop 0
	global_load_lds_dwordx4 v132, s[44:45]
	s_waitcnt vmcnt(8)
	s_waitcnt lgkmcnt(0)
	s_barrier
	s_waitcnt lgkmcnt(0)
	v_mfma_f32_16x16x32_bf16 v[64:67], v[0:3], v[32:35], 0
	v_mfma_f32_16x16x32_bf16 v[68:71], v[8:11], v[32:35], 0
	v_mfma_f32_16x16x32_bf16 v[72:75], v[0:3], v[40:43], 0
	v_mfma_f32_16x16x32_bf16 v[76:79], v[8:11], v[40:43], 0
	v_mfma_f32_16x16x32_bf16 v[80:83], v[0:3], v[48:51], 0
	v_mfma_f32_16x16x32_bf16 v[84:87], v[8:11], v[48:51], 0
	v_mfma_f32_16x16x32_bf16 v[88:91], v[0:3], v[56:59], 0
	v_mfma_f32_16x16x32_bf16 v[92:95], v[8:11], v[56:59], 0
	v_mfma_f32_16x16x32_bf16 v[64:67], v[4:7], v[36:39], v[64:67]
	v_mfma_f32_16x16x32_bf16 v[68:71], v[12:15], v[36:39], v[68:71]
	v_mfma_f32_16x16x32_bf16 v[72:75], v[4:7], v[44:47], v[72:75]
	v_mfma_f32_16x16x32_bf16 v[76:79], v[12:15], v[44:47], v[76:79]
	v_mfma_f32_16x16x32_bf16 v[80:83], v[4:7], v[52:55], v[80:83]
	v_mfma_f32_16x16x32_bf16 v[84:87], v[12:15], v[52:55], v[84:87]
	v_mfma_f32_16x16x32_bf16 v[88:91], v[4:7], v[60:63], v[88:91]
	v_mfma_f32_16x16x32_bf16 v[92:95], v[12:15], v[60:63], v[92:95]
	v_mfma_f32_16x16x32_bf16 v[96:99], v[16:19], v[32:35], 0
	v_mfma_f32_16x16x32_bf16 v[32:35], v[24:27], v[32:35], 0
	v_mfma_f32_16x16x32_bf16 v[96:99], v[20:23], v[36:39], v[96:99]
	v_mfma_f32_16x16x32_bf16 v[32:35], v[28:31], v[36:39], v[32:35]
	v_mfma_f32_16x16x32_bf16 v[36:39], v[16:19], v[40:43], 0
	v_mfma_f32_16x16x32_bf16 v[40:43], v[24:27], v[40:43], 0
	v_mfma_f32_16x16x32_bf16 v[36:39], v[20:23], v[44:47], v[36:39]
	v_mfma_f32_16x16x32_bf16 v[40:43], v[28:31], v[44:47], v[40:43]
	v_mfma_f32_16x16x32_bf16 v[44:47], v[16:19], v[48:51], 0
	v_mfma_f32_16x16x32_bf16 v[48:51], v[24:27], v[48:51], 0
	v_mfma_f32_16x16x32_bf16 v[44:47], v[20:23], v[52:55], v[44:47]
	v_mfma_f32_16x16x32_bf16 v[48:51], v[28:31], v[52:55], v[48:51]
	v_mfma_f32_16x16x32_bf16 v[52:55], v[16:19], v[56:59], 0
	v_mfma_f32_16x16x32_bf16 v[56:59], v[24:27], v[56:59], 0
	v_mfma_f32_16x16x32_bf16 v[52:55], v[20:23], v[60:63], v[52:55]
	v_mfma_f32_16x16x32_bf16 v[56:59], v[28:31], v[60:63], v[56:59]
	s_barrier
	s_add_i32 s48, s59, s8
	v_lshl_add_u64 v[190:191], s[40:41], 0, v[130:131]
	s_add_i32 s31, s48, 0x2000
	v_lshl_add_u64 v[146:147], v[190:191], 0, s[22:23]
	s_mov_b32 m0, s48
	v_lshl_add_u64 v[216:217], s[40:41], 0, v[134:135]
	s_add_u32 s64, s40, 0x10100
	ds_read_b128 v[60:63], v145 offset:16384
	ds_read_b128 v[100:103], v145 offset:17408
	ds_read_b128 v[104:107], v145 offset:18432
	ds_read_b128 v[108:111], v145 offset:19456
	ds_read_b128 v[112:115], v145 offset:20480
	ds_read_b128 v[116:119], v145 offset:21504
	ds_read_b128 v[120:123], v145 offset:22528
	ds_read_b128 v[124:127], v145 offset:23552
	global_load_lds_dwordx4 v[146:147], off
	v_lshl_add_u64 v[146:147], v[216:217], 0, s[22:23]
	s_mov_b32 m0, s31
	s_addc_u32 s65, s41, 0
	s_add_i32 s44, s60, s8
	global_load_lds_dwordx4 v[146:147], off
	s_mov_b32 m0, s44
	s_add_i32 s45, s44, 0x2000
	global_load_lds_dwordx4 v130, s[64:65]
	s_mov_b32 m0, s45
	v_lshl_add_u64 v[218:219], s[38:39], 0, v[128:129]
	global_load_lds_dwordx4 v134, s[64:65]
	v_lshl_add_u64 v[146:147], v[218:219], 0, s[22:23]
	s_mov_b32 m0, s9
	v_lshl_add_u64 v[220:221], s[38:39], 0, v[132:133]
	global_load_lds_dwordx4 v[146:147], off
	v_lshl_add_u64 v[146:147], v[220:221], 0, s[22:23]
	s_mov_b32 m0, s27
	s_nop 0
	global_load_lds_dwordx4 v[146:147], off
	s_waitcnt vmcnt(8)
	s_waitcnt lgkmcnt(0)
	s_barrier
; #define PG8_STAGE(bufoff, gbase, voff) do { _Pragma("unroll") for (int _i = 0; _i < 2; ++_i) \
;         __builtin_amdgcn_global_load_lds((const unsigned*)((const char*)(gbase) + (voff)[_i]), (PG8_LAS unsigned*)(lds + (bufoff) + ldsw + _i * 8192), 16, 0, 0); } while (0)
; #define PG8_LDA(dst, b, h) do { _Pragma("unroll") for (int m = 0; m < 4; ++m) _Pragma("unroll") for (int k = 0; k < 2; ++k) dst[m][k] = *(const PG8_LAS bf16x8*)(lds + PG8_SA(b, h) + aoff + m * 2048 + k * 1024); } while (0)
; #define PG8_LDB(dst, b, h) do { _Pragma("unroll") for (int n = 0; n < 2; ++n) _Pragma("unroll") for (int k = 0; k < 2; ++k) dst[n][k] = *(const PG8_LAS bf16x8*)(lds + PG8_SB(b, h) + boff + n * 2048 + k * 1024); } while (0)
; #define PG8_MMA(ai, bj, At, Bt) do { __builtin_amdgcn_s_setprio(1); _Pragma("unroll") for (int m = 0; m < 4; ++m) _Pragma("unroll") for (int n = 0; n < 2; ++n) _Pragma("unroll") for (int k = 0; k < 2; ++k) \
;         acc[ai][bj][m][n] = __builtin_amdgcn_mfma_f32_16x16x32_bf16(Bt[n][k], At[m][k], acc[ai][bj][m][n], 0, 0, 0); __builtin_amdgcn_s_setprio(0); } while (0)
; #define PG8_WAIT_V(n) asm volatile("s_waitcnt vmcnt(" #n ")" ::: "memory")
; template <class Epi, class Sched, bool ALIGN_EPI = false, bool SP2 = false>
; __device__ __forceinline__ void gemm_phase(PG8_LAS unsigned char* lds, const Gemm g, const Sched& S, const Epi& E) {
;     ...
;             PG8_LDB(B0, 0, 0); PG8_LDB(B1, 0, 1); PG8_SCHED; PG8_LDA(At, 0, 0); PG8_STAGE(PG8_SA(1, 1), a1 + hstepA, voffA);
;             PG8_WAIT_V(8); PG8_WAIT_L(0); PG8_BAR; PG8_MMA(0, 0, At, B0); PG8_MMA(0, 1, At, B1); PG8_BAR; PG8_SCHED;
;             PG8_LDA(At, 0, 1); PG8_STAGE(PG8_SB(0, 0), b2, voffB); PG8_STAGE(PG8_SB(0, 1), b2 + hstepB, voffB); PG8_STAGE(PG8_SA(0, 0), a2, voffA);
;             PG8_WAIT_V(8); PG8_WAIT_L(0); PG8_BAR; PG8_MMA(1, 0, At, B0); PG8_MMA(1, 1, At, B1); PG8_BAR; PG8_SCHED;
;             PG8_LDB(B0, 1, 0); PG8_LDB(B1, 1, 1); PG8_SCHED; PG8_LDA(At, 1, 0); PG8_STAGE(PG8_SA(0, 1), a2 + hstepA, voffA);
;             PG8_WAIT_V(8); PG8_WAIT_L(0); PG8_BAR; PG8_MMA(0, 0, At, B0); PG8_MMA(0, 1, At, B1); PG8_BAR; PG8_SCHED;
;             PG8_LDA(At, 1, 1); PG8_STAGE(PG8_SB(1, 0), b3, voffB); PG8_STAGE(PG8_SB(1, 1), b3 + hstepB, voffB); PG8_STAGE(PG8_SA(1, 0), a3, voffA);
;             PG8_WAIT_V(8); PG8_WAIT_L(0); PG8_BAR; PG8_MMA(1, 0, At, B0); PG8_MMA(1, 1, At, B1); PG8_BAR; PG8_SCHED;
	s_waitcnt lgkmcnt(0)
	v_mfma_f32_16x16x32_bf16 v[146:149], v[0:3], v[60:63], 0
	v_mfma_f32_16x16x32_bf16 v[154:157], v[0:3], v[104:107], 0
	v_mfma_f32_16x16x32_bf16 v[162:165], v[0:3], v[112:115], 0
	v_mfma_f32_16x16x32_bf16 v[0:3], v[0:3], v[120:123], 0
	v_mfma_f32_16x16x32_bf16 v[146:149], v[4:7], v[100:103], v[146:149]
	v_mfma_f32_16x16x32_bf16 v[154:157], v[4:7], v[108:111], v[154:157]
	v_mfma_f32_16x16x32_bf16 v[162:165], v[4:7], v[116:119], v[162:165]
	v_mfma_f32_16x16x32_bf16 v[0:3], v[4:7], v[124:127], v[0:3]
	v_mfma_f32_16x16x32_bf16 v[4:7], v[8:11], v[120:123], 0
	v_mfma_f32_16x16x32_bf16 v[150:153], v[8:11], v[60:63], 0
	v_mfma_f32_16x16x32_bf16 v[158:161], v[8:11], v[104:107], 0
	v_mfma_f32_16x16x32_bf16 v[166:169], v[8:11], v[112:115], 0
	v_mfma_f32_16x16x32_bf16 v[4:7], v[12:15], v[124:127], v[4:7]
	v_mfma_f32_16x16x32_bf16 v[150:153], v[12:15], v[100:103], v[150:153]
	v_mfma_f32_16x16x32_bf16 v[158:161], v[12:15], v[108:111], v[158:161]
	v_mfma_f32_16x16x32_bf16 v[166:169], v[12:15], v[116:119], v[166:169]
	v_mfma_f32_16x16x32_bf16 v[8:11], v[16:19], v[60:63], 0
	v_mfma_f32_16x16x32_bf16 v[12:15], v[24:27], v[60:63], 0
	v_mfma_f32_16x16x32_bf16 v[8:11], v[20:23], v[100:103], v[8:11]
	v_mfma_f32_16x16x32_bf16 v[12:15], v[28:31], v[100:103], v[12:15]
	v_mfma_f32_16x16x32_bf16 v[60:63], v[16:19], v[104:107], 0
	v_mfma_f32_16x16x32_bf16 v[100:103], v[24:27], v[104:107], 0
	v_mfma_f32_16x16x32_bf16 v[104:107], v[16:19], v[112:115], 0
	v_mfma_f32_16x16x32_bf16 v[16:19], v[16:19], v[120:123], 0
	v_mfma_f32_16x16x32_bf16 v[60:63], v[20:23], v[108:111], v[60:63]
	v_mfma_f32_16x16x32_bf16 v[100:103], v[28:31], v[108:111], v[100:103]
	v_mfma_f32_16x16x32_bf16 v[104:107], v[20:23], v[116:119], v[104:107]
	v_mfma_f32_16x16x32_bf16 v[108:111], v[24:27], v[112:115], 0
	v_mfma_f32_16x16x32_bf16 v[16:19], v[20:23], v[124:127], v[16:19]
	v_mfma_f32_16x16x32_bf16 v[20:23], v[24:27], v[120:123], 0
	v_mfma_f32_16x16x32_bf16 v[108:111], v[28:31], v[116:119], v[108:111]
	v_mfma_f32_16x16x32_bf16 v[20:23], v[28:31], v[124:127], v[20:23]
	s_barrier
	s_add_i32 s49, 0, 0x18000
	s_add_i32 s68, 0, 0x1c000
	v_add_u32_e32 v224, s49, v142
	v_add_u32_e32 v228, s68, v142
	ds_read_b128 v[24:27], v224
	ds_read_b128 v[28:31], v224 offset:1024
	ds_read_b128 v[112:115], v224 offset:2048
	ds_read_b128 v[116:119], v224 offset:3072
	ds_read_b128 v[120:123], v228
	ds_read_b128 v[124:127], v228 offset:1024
	ds_read_b128 v[170:173], v228 offset:2048
	ds_read_b128 v[174:177], v228 offset:3072
	s_add_u32 s64, s38, 0x10100
	s_addc_u32 s65, s39, 0
	s_mov_b32 m0, s33
	ds_read_b128 v[178:181], v145 offset:32768
	ds_read_b128 v[182:185], v145 offset:33792
	ds_read_b128 v[186:189], v145 offset:34816
	ds_read_b128 v[196:199], v145 offset:35840
	ds_read_b128 v[200:203], v145 offset:36864
	ds_read_b128 v[204:207], v145 offset:37888
	ds_read_b128 v[208:211], v145 offset:38912
	ds_read_b128 v[212:215], v145 offset:39936
	global_load_lds_dwordx4 v128, s[64:65]
	s_mov_b32 m0, s42
	s_nop 0
	global_load_lds_dwordx4 v132, s[64:65]
	s_waitcnt vmcnt(8)
	s_waitcnt lgkmcnt(0)
	s_barrier
	s_waitcnt lgkmcnt(0)
	v_mfma_f32_16x16x32_bf16 v[64:67], v[24:27], v[178:181], v[64:67]
	v_mfma_f32_16x16x32_bf16 v[68:71], v[112:115], v[178:181], v[68:71]
	v_mfma_f32_16x16x32_bf16 v[72:75], v[24:27], v[186:189], v[72:75]
	v_mfma_f32_16x16x32_bf16 v[76:79], v[112:115], v[186:189], v[76:79]
	v_mfma_f32_16x16x32_bf16 v[80:83], v[24:27], v[200:203], v[80:83]
	v_mfma_f32_16x16x32_bf16 v[84:87], v[112:115], v[200:203], v[84:87]
	v_mfma_f32_16x16x32_bf16 v[88:91], v[24:27], v[208:211], v[88:91]
	v_mfma_f32_16x16x32_bf16 v[92:95], v[112:115], v[208:211], v[92:95]
	v_mfma_f32_16x16x32_bf16 v[64:67], v[28:31], v[182:185], v[64:67]
	v_mfma_f32_16x16x32_bf16 v[68:71], v[116:119], v[182:185], v[68:71]
	v_mfma_f32_16x16x32_bf16 v[72:75], v[28:31], v[196:199], v[72:75]
	v_mfma_f32_16x16x32_bf16 v[76:79], v[116:119], v[196:199], v[76:79]
	v_mfma_f32_16x16x32_bf16 v[80:83], v[28:31], v[204:207], v[80:83]
	v_mfma_f32_16x16x32_bf16 v[84:87], v[116:119], v[204:207], v[84:87]
	v_mfma_f32_16x16x32_bf16 v[88:91], v[28:31], v[212:215], v[88:91]
	v_mfma_f32_16x16x32_bf16 v[92:95], v[116:119], v[212:215], v[92:95]
	v_mfma_f32_16x16x32_bf16 v[96:99], v[120:123], v[178:181], v[96:99]
	v_mfma_f32_16x16x32_bf16 v[32:35], v[170:173], v[178:181], v[32:35]
	v_mfma_f32_16x16x32_bf16 v[36:39], v[120:123], v[186:189], v[36:39]
	v_mfma_f32_16x16x32_bf16 v[40:43], v[170:173], v[186:189], v[40:43]
	v_mfma_f32_16x16x32_bf16 v[44:47], v[120:123], v[200:203], v[44:47]
	v_mfma_f32_16x16x32_bf16 v[48:51], v[170:173], v[200:203], v[48:51]
	v_mfma_f32_16x16x32_bf16 v[52:55], v[120:123], v[208:211], v[52:55]
	v_mfma_f32_16x16x32_bf16 v[56:59], v[170:173], v[208:211], v[56:59]
	v_mfma_f32_16x16x32_bf16 v[96:99], v[124:127], v[182:185], v[96:99]
	v_mfma_f32_16x16x32_bf16 v[32:35], v[174:177], v[182:185], v[32:35]
	v_mfma_f32_16x16x32_bf16 v[36:39], v[124:127], v[196:199], v[36:39]
	v_mfma_f32_16x16x32_bf16 v[40:43], v[174:177], v[196:199], v[40:43]
	v_mfma_f32_16x16x32_bf16 v[44:47], v[124:127], v[204:207], v[44:47]
	v_mfma_f32_16x16x32_bf16 v[48:51], v[174:177], v[204:207], v[48:51]
	v_mfma_f32_16x16x32_bf16 v[52:55], v[124:127], v[212:215], v[52:55]
	v_mfma_f32_16x16x32_bf16 v[56:59], v[174:177], v[212:215], v[56:59]
	s_barrier
; #define PG8_STAGE(bufoff, gbase, voff) do { _Pragma("unroll") for (int _i = 0; _i < 2; ++_i) \
;         __builtin_amdgcn_global_load_lds((const unsigned*)((const char*)(gbase) + (voff)[_i]), (PG8_LAS unsigned*)(lds + (bufoff) + ldsw + _i * 8192), 16, 0, 0); } while (0)
; #define PG8_LDA(dst, b, h) do { _Pragma("unroll") for (int m = 0; m < 4; ++m) _Pragma("unroll") for (int k = 0; k < 2; ++k) dst[m][k] = *(const PG8_LAS bf16x8*)(lds + PG8_SA(b, h) + aoff + m * 2048 + k * 1024); } while (0)
; #define PG8_LDB(dst, b, h) do { _Pragma("unroll") for (int n = 0; n < 2; ++n) _Pragma("unroll") for (int k = 0; k < 2; ++k) dst[n][k] = *(const PG8_LAS bf16x8*)(lds + PG8_SB(b, h) + boff + n * 2048 + k * 1024); } while (0)
; #define PG8_MMA(ai, bj, At, Bt) do { __builtin_amdgcn_s_setprio(1); _Pragma("unroll") for (int m = 0; m < 4; ++m) _Pragma("unroll") for (int n = 0; n < 2; ++n) _Pragma("unroll") for (int k = 0; k < 2; ++k) \
;         acc[ai][bj][m][n] = __builtin_amdgcn_mfma_f32_16x16x32_bf16(Bt[n][k], At[m][k], acc[ai][bj][m][n], 0, 0, 0); __builtin_amdgcn_s_setprio(0); } while (0)
; #define PG8_WAIT_V(n) asm volatile("s_waitcnt vmcnt(" #n ")" ::: "memory")
; #define PG8_WAIT_L(n) asm volatile("s_waitcnt lgkmcnt(" #n ")" ::: "memory")
; #define PG8_BAR __builtin_amdgcn_s_barrier()
; #define PG8_SCHED __builtin_amdgcn_sched_barrier(0)
; template <class Epi, class Sched, bool ALIGN_EPI = false, bool SP2 = false>
; __device__ __forceinline__ void gemm_phase(PG8_LAS unsigned char* lds, const Gemm g, const Sched& S, const Epi& E) {
;     ...
;             PG8_LDA(At, 0, 1); PG8_STAGE(PG8_SB(0, 0), b2, voffB); PG8_STAGE(PG8_SB(0, 1), b2 + hstepB, voffB); PG8_STAGE(PG8_SA(0, 0), a2, voffA);
;             PG8_WAIT_V(8); PG8_WAIT_L(0); PG8_BAR; PG8_MMA(1, 0, At, B0); PG8_MMA(1, 1, At, B1); PG8_BAR; PG8_SCHED;
;             PG8_LDB(B0, 1, 0); PG8_LDB(B1, 1, 1); PG8_SCHED; PG8_LDA(At, 1, 0); PG8_STAGE(PG8_SA(0, 1), a2 + hstepA, voffA);
;             PG8_WAIT_V(8); PG8_WAIT_L(0); PG8_BAR; PG8_MMA(0, 0, At, B0); PG8_MMA(0, 1, At, B1); PG8_BAR; PG8_SCHED;
;             PG8_LDA(At, 1, 1); PG8_STAGE(PG8_SB(1, 0), b3, voffB); PG8_STAGE(PG8_SB(1, 1), b3 + hstepB, voffB); PG8_STAGE(PG8_SA(1, 0), a3, voffA);
;             PG8_WAIT_V(8); PG8_WAIT_L(0); PG8_BAR; PG8_MMA(1, 0, At, B0); PG8_MMA(1, 1, At, B1); PG8_BAR; PG8_SCHED;
	s_add_i32 s64, s49, s8
	s_add_i32 s49, s64, 0x2000
	v_lshl_add_u64 v[190:191], v[190:191], 0, s[24:25]
	s_mov_b32 m0, s64
	s_add_u32 s66, s40, 0x10180
	ds_read_b128 v[178:181], v145 offset:49152
	ds_read_b128 v[182:185], v145 offset:50176
	ds_read_b128 v[186:189], v145 offset:51200
	ds_read_b128 v[196:199], v145 offset:52224
	ds_read_b128 v[200:203], v145 offset:53248
	ds_read_b128 v[204:207], v145 offset:54272
	ds_read_b128 v[208:211], v145 offset:55296
	ds_read_b128 v[212:215], v145 offset:56320
	global_load_lds_dwordx4 v[190:191], off
	v_lshl_add_u64 v[190:191], v[216:217], 0, s[24:25]
	s_mov_b32 m0, s49
	s_addc_u32 s67, s41, 0
	s_add_i32 s40, s68, s8
	global_load_lds_dwordx4 v[190:191], off
	s_mov_b32 m0, s40
	s_add_i32 s41, s40, 0x2000
	global_load_lds_dwordx4 v130, s[66:67]
	s_mov_b32 m0, s41
	s_nop 0
	global_load_lds_dwordx4 v134, s[66:67]
	v_lshl_add_u64 v[190:191], v[218:219], 0, s[24:25]
	s_mov_b32 m0, s53
	s_nop 0
	global_load_lds_dwordx4 v[190:191], off
	v_lshl_add_u64 v[190:191], v[220:221], 0, s[24:25]
	s_mov_b32 m0, s56
	s_nop 0
	global_load_lds_dwordx4 v[190:191], off
	s_waitcnt vmcnt(8)
	s_waitcnt lgkmcnt(0)
	s_barrier
	s_waitcnt lgkmcnt(0)
	v_mfma_f32_16x16x32_bf16 v[0:3], v[24:27], v[208:211], v[0:3]
	v_mfma_f32_16x16x32_bf16 v[4:7], v[112:115], v[208:211], v[4:7]
	v_mfma_f32_16x16x32_bf16 v[146:149], v[24:27], v[178:181], v[146:149]
	v_mfma_f32_16x16x32_bf16 v[150:153], v[112:115], v[178:181], v[150:153]
	v_mfma_f32_16x16x32_bf16 v[154:157], v[24:27], v[186:189], v[154:157]
	v_mfma_f32_16x16x32_bf16 v[158:161], v[112:115], v[186:189], v[158:161]
	v_mfma_f32_16x16x32_bf16 v[162:165], v[24:27], v[200:203], v[162:165]
	v_mfma_f32_16x16x32_bf16 v[166:169], v[112:115], v[200:203], v[166:169]
	v_mfma_f32_16x16x32_bf16 v[0:3], v[28:31], v[212:215], v[0:3]
	v_mfma_f32_16x16x32_bf16 v[4:7], v[116:119], v[212:215], v[4:7]
	v_mfma_f32_16x16x32_bf16 v[146:149], v[28:31], v[182:185], v[146:149]
	v_mfma_f32_16x16x32_bf16 v[150:153], v[116:119], v[182:185], v[150:153]
	v_mfma_f32_16x16x32_bf16 v[154:157], v[28:31], v[196:199], v[154:157]
	v_mfma_f32_16x16x32_bf16 v[158:161], v[116:119], v[196:199], v[158:161]
	v_mfma_f32_16x16x32_bf16 v[162:165], v[28:31], v[204:207], v[162:165]
	v_mfma_f32_16x16x32_bf16 v[166:169], v[116:119], v[204:207], v[166:169]
	v_mfma_f32_16x16x32_bf16 v[8:11], v[120:123], v[178:181], v[8:11]
	v_mfma_f32_16x16x32_bf16 v[12:15], v[170:173], v[178:181], v[12:15]
	v_mfma_f32_16x16x32_bf16 v[24:27], v[120:123], v[186:189], v[60:63]
	v_mfma_f32_16x16x32_bf16 v[28:31], v[170:173], v[186:189], v[100:103]
	v_mfma_f32_16x16x32_bf16 v[60:63], v[120:123], v[200:203], v[104:107]
	v_mfma_f32_16x16x32_bf16 v[100:103], v[170:173], v[200:203], v[108:111]
	v_mfma_f32_16x16x32_bf16 v[16:19], v[120:123], v[208:211], v[16:19]
	v_mfma_f32_16x16x32_bf16 v[20:23], v[170:173], v[208:211], v[20:23]
	v_mfma_f32_16x16x32_bf16 v[8:11], v[124:127], v[182:185], v[8:11]
	v_mfma_f32_16x16x32_bf16 v[12:15], v[174:177], v[182:185], v[12:15]
	v_mfma_f32_16x16x32_bf16 v[24:27], v[124:127], v[196:199], v[24:27]
	v_mfma_f32_16x16x32_bf16 v[28:31], v[174:177], v[196:199], v[28:31]
	v_mfma_f32_16x16x32_bf16 v[60:63], v[124:127], v[204:207], v[60:63]
	v_mfma_f32_16x16x32_bf16 v[100:103], v[174:177], v[204:207], v[100:103]
	v_mfma_f32_16x16x32_bf16 v[16:19], v[124:127], v[212:215], v[16:19]
	v_mfma_f32_16x16x32_bf16 v[20:23], v[174:177], v[212:215], v[20:23]
	s_barrier
	ds_read_b128 v[104:107], v143
	ds_read_b128 v[108:111], v143 offset:1024
	ds_read_b128 v[112:115], v143 offset:2048
	ds_read_b128 v[116:119], v143 offset:3072
	ds_read_b128 v[120:123], v144
	ds_read_b128 v[124:127], v144 offset:1024
	ds_read_b128 v[170:173], v144 offset:2048
	ds_read_b128 v[174:177], v144 offset:3072
	s_add_u32 s38, s38, 0x10180
	s_addc_u32 s39, s39, 0
	s_mov_b32 m0, s63
	ds_read_b128 v[178:181], v145
	ds_read_b128 v[182:185], v145 offset:1024
	ds_read_b128 v[186:189], v145 offset:2048
	ds_read_b128 v[196:199], v145 offset:3072
	ds_read_b128 v[200:203], v145 offset:4096
	ds_read_b128 v[204:207], v145 offset:5120
	ds_read_b128 v[208:211], v145 offset:6144
	ds_read_b128 v[212:215], v145 offset:7168
	global_load_lds_dwordx4 v128, s[38:39]
	s_mov_b32 m0, s29
	s_nop 0
	global_load_lds_dwordx4 v132, s[38:39]
	s_waitcnt vmcnt(8)
	s_waitcnt lgkmcnt(0)
	s_barrier
	s_waitcnt lgkmcnt(0)
	v_mfma_f32_16x16x32_bf16 v[64:67], v[104:107], v[178:181], v[64:67]
	v_mfma_f32_16x16x32_bf16 v[68:71], v[112:115], v[178:181], v[68:71]
	v_mfma_f32_16x16x32_bf16 v[72:75], v[104:107], v[186:189], v[72:75]
	v_mfma_f32_16x16x32_bf16 v[76:79], v[112:115], v[186:189], v[76:79]
	v_mfma_f32_16x16x32_bf16 v[80:83], v[104:107], v[200:203], v[80:83]
	v_mfma_f32_16x16x32_bf16 v[84:87], v[112:115], v[200:203], v[84:87]
	v_mfma_f32_16x16x32_bf16 v[88:91], v[104:107], v[208:211], v[88:91]
	v_mfma_f32_16x16x32_bf16 v[92:95], v[112:115], v[208:211], v[92:95]
	v_mfma_f32_16x16x32_bf16 v[64:67], v[108:111], v[182:185], v[64:67]
	v_mfma_f32_16x16x32_bf16 v[68:71], v[116:119], v[182:185], v[68:71]
	v_mfma_f32_16x16x32_bf16 v[72:75], v[108:111], v[196:199], v[72:75]
	v_mfma_f32_16x16x32_bf16 v[76:79], v[116:119], v[196:199], v[76:79]
	v_mfma_f32_16x16x32_bf16 v[80:83], v[108:111], v[204:207], v[80:83]
	v_mfma_f32_16x16x32_bf16 v[84:87], v[116:119], v[204:207], v[84:87]
	v_mfma_f32_16x16x32_bf16 v[88:91], v[108:111], v[212:215], v[88:91]
	v_mfma_f32_16x16x32_bf16 v[92:95], v[116:119], v[212:215], v[92:95]
	v_mfma_f32_16x16x32_bf16 v[32:35], v[170:173], v[178:181], v[32:35]
	v_mfma_f32_16x16x32_bf16 v[96:99], v[120:123], v[178:181], v[96:99]
	v_mfma_f32_16x16x32_bf16 v[178:181], v[174:177], v[182:185], v[32:35]
	v_mfma_f32_16x16x32_bf16 v[32:35], v[120:123], v[186:189], v[36:39]
	v_mfma_f32_16x16x32_bf16 v[216:219], v[124:127], v[182:185], v[96:99]
	v_mfma_f32_16x16x32_bf16 v[182:185], v[124:127], v[196:199], v[32:35]
	v_mfma_f32_16x16x32_bf16 v[32:35], v[170:173], v[186:189], v[40:43]
	v_mfma_f32_16x16x32_bf16 v[40:43], v[174:177], v[196:199], v[32:35]
	v_mfma_f32_16x16x32_bf16 v[32:35], v[120:123], v[200:203], v[44:47]
	v_mfma_f32_16x16x32_bf16 v[44:47], v[124:127], v[204:207], v[32:35]
	v_mfma_f32_16x16x32_bf16 v[32:35], v[170:173], v[200:203], v[48:51]
	v_mfma_f32_16x16x32_bf16 v[48:51], v[174:177], v[204:207], v[32:35]
	v_mfma_f32_16x16x32_bf16 v[32:35], v[120:123], v[208:211], v[52:55]
	v_mfma_f32_16x16x32_bf16 v[52:55], v[124:127], v[212:215], v[32:35]
	v_mfma_f32_16x16x32_bf16 v[32:35], v[170:173], v[208:211], v[56:59]
	v_mfma_f32_16x16x32_bf16 v[56:59], v[174:177], v[212:215], v[32:35]
	s_barrier
; #define PG8_STAGE(bufoff, gbase, voff) do { _Pragma("unroll") for (int _i = 0; _i < 2; ++_i) \
;         __builtin_amdgcn_global_load_lds((const unsigned*)((const char*)(gbase) + (voff)[_i]), (PG8_LAS unsigned*)(lds + (bufoff) + ldsw + _i * 8192), 16, 0, 0); } while (0)
; #define PG8_LDA(dst, b, h) do { _Pragma("unroll") for (int m = 0; m < 4; ++m) _Pragma("unroll") for (int k = 0; k < 2; ++k) dst[m][k] = *(const PG8_LAS bf16x8*)(lds + PG8_SA(b, h) + aoff + m * 2048 + k * 1024); } while (0)
; #define PG8_LDB(dst, b, h) do { _Pragma("unroll") for (int n = 0; n < 2; ++n) _Pragma("unroll") for (int k = 0; k < 2; ++k) dst[n][k] = *(const PG8_LAS bf16x8*)(lds + PG8_SB(b, h) + boff + n * 2048 + k * 1024); } while (0)
; #define PG8_MMA(ai, bj, At, Bt) do { __builtin_amdgcn_s_setprio(1); _Pragma("unroll") for (int m = 0; m < 4; ++m) _Pragma("unroll") for (int n = 0; n < 2; ++n) _Pragma("unroll") for (int k = 0; k < 2; ++k) \
;         acc[ai][bj][m][n] = __builtin_amdgcn_mfma_f32_16x16x32_bf16(Bt[n][k], At[m][k], acc[ai][bj][m][n], 0, 0, 0); __builtin_amdgcn_s_setprio(0); } while (0)
; #define PG8_WAIT_V(n) asm volatile("s_waitcnt vmcnt(" #n ")" ::: "memory")
; #define PG8_WAIT_L(n) asm volatile("s_waitcnt lgkmcnt(" #n ")" ::: "memory")
; #define PG8_BAR __builtin_amdgcn_s_barrier()
; #define PG8_SCHED __builtin_amdgcn_sched_barrier(0)
; template <class Epi, class Sched, bool ALIGN_EPI = false, bool SP2 = false>
; __device__ __forceinline__ void gemm_phase(PG8_LAS unsigned char* lds, const Gemm g, const Sched& S, const Epi& E) {
;     ...
;             PG8_LDA(At, 0, 1); PG8_STAGE(PG8_SB(0, 0), b2, voffB); PG8_STAGE(PG8_SB(0, 1), b2 + hstepB, voffB); PG8_STAGE(PG8_SA(0, 0), a2, voffA);
;             PG8_WAIT_V(8); PG8_WAIT_L(0); PG8_BAR; PG8_MMA(1, 0, At, B0); PG8_MMA(1, 1, At, B1); PG8_BAR; PG8_SCHED;
;             PG8_LDB(B0, 1, 0); PG8_LDB(B1, 1, 1); PG8_SCHED; PG8_LDA(At, 1, 0); PG8_STAGE(PG8_SA(0, 1), a2 + hstepA, voffA);
;             PG8_WAIT_V(8); PG8_WAIT_L(0); PG8_BAR; PG8_MMA(0, 0, At, B0); PG8_MMA(0, 1, At, B1); PG8_BAR; PG8_SCHED;
;             PG8_LDA(At, 1, 1); PG8_STAGE(PG8_SB(1, 0), b3, voffB); PG8_STAGE(PG8_SB(1, 1), b3 + hstepB, voffB); PG8_STAGE(PG8_SA(1, 0), a3, voffA);
;             PG8_WAIT_V(8); PG8_WAIT_L(0); PG8_BAR; PG8_MMA(1, 0, At, B0); PG8_MMA(1, 1, At, B1); PG8_BAR; PG8_SCHED;
	s_mov_b32 m0, s48
	v_lshl_add_u64 v[190:191], s[46:47], 0, v[130:131]
	s_add_u32 s38, s46, 0x10000
	s_nop 1
	ds_read_b128 v[32:35], v145 offset:16384
	ds_read_b128 v[36:39], v145 offset:17408
	ds_read_b128 v[96:99], v145 offset:18432
	ds_read_b128 v[186:189], v145 offset:19456
	ds_read_b128 v[196:199], v145 offset:20480
	ds_read_b128 v[200:203], v145 offset:21504
	ds_read_b128 v[204:207], v145 offset:22528
	ds_read_b128 v[208:211], v145 offset:23552
	global_load_lds_dwordx4 v[190:191], off
	v_lshl_add_u64 v[252:253], s[46:47], 0, v[134:135]
	s_mov_b32 m0, s31
	s_addc_u32 s39, s47, 0
	global_load_lds_dwordx4 v[252:253], off
	s_mov_b32 m0, s44
	v_lshl_add_u64 v[194:195], s[50:51], 0, v[128:129]
	global_load_lds_dwordx4 v130, s[38:39]
	s_mov_b32 m0, s45
	v_lshl_add_u64 v[192:193], s[50:51], 0, v[132:133]
	global_load_lds_dwordx4 v134, s[38:39]
	s_mov_b32 m0, s9
	s_nop 0
	global_load_lds_dwordx4 v[194:195], off
	s_mov_b32 m0, s27
	s_nop 0
	global_load_lds_dwordx4 v[192:193], off
	s_waitcnt vmcnt(8)
	s_waitcnt lgkmcnt(0)
	s_barrier
	s_waitcnt lgkmcnt(0)
	v_mfma_f32_16x16x32_bf16 v[0:3], v[104:107], v[204:207], v[0:3]
	v_mfma_f32_16x16x32_bf16 v[4:7], v[112:115], v[204:207], v[4:7]
	v_mfma_f32_16x16x32_bf16 v[146:149], v[104:107], v[32:35], v[146:149]
	v_mfma_f32_16x16x32_bf16 v[150:153], v[112:115], v[32:35], v[150:153]
	v_mfma_f32_16x16x32_bf16 v[154:157], v[104:107], v[96:99], v[154:157]
	v_mfma_f32_16x16x32_bf16 v[158:161], v[112:115], v[96:99], v[158:161]
	v_mfma_f32_16x16x32_bf16 v[162:165], v[104:107], v[196:199], v[162:165]
	v_mfma_f32_16x16x32_bf16 v[166:169], v[112:115], v[196:199], v[166:169]
	v_mfma_f32_16x16x32_bf16 v[0:3], v[108:111], v[208:211], v[0:3]
	v_mfma_f32_16x16x32_bf16 v[4:7], v[116:119], v[208:211], v[4:7]
	v_mfma_f32_16x16x32_bf16 v[146:149], v[108:111], v[36:39], v[146:149]
	v_mfma_f32_16x16x32_bf16 v[150:153], v[116:119], v[36:39], v[150:153]
	v_mfma_f32_16x16x32_bf16 v[154:157], v[108:111], v[186:189], v[154:157]
	v_mfma_f32_16x16x32_bf16 v[158:161], v[116:119], v[186:189], v[158:161]
	v_mfma_f32_16x16x32_bf16 v[162:165], v[108:111], v[200:203], v[162:165]
	v_mfma_f32_16x16x32_bf16 v[166:169], v[116:119], v[200:203], v[166:169]
	v_mfma_f32_16x16x32_bf16 v[8:11], v[120:123], v[32:35], v[8:11]
	v_mfma_f32_16x16x32_bf16 v[12:15], v[170:173], v[32:35], v[12:15]
	v_mfma_f32_16x16x32_bf16 v[24:27], v[120:123], v[96:99], v[24:27]
	v_mfma_f32_16x16x32_bf16 v[28:31], v[170:173], v[96:99], v[28:31]
	v_mfma_f32_16x16x32_bf16 v[32:35], v[120:123], v[196:199], v[60:63]
	v_mfma_f32_16x16x32_bf16 v[24:27], v[124:127], v[186:189], v[24:27]
	v_mfma_f32_16x16x32_bf16 v[28:31], v[174:177], v[186:189], v[28:31]
	v_mfma_f32_16x16x32_bf16 v[186:189], v[124:127], v[200:203], v[32:35]
	v_mfma_f32_16x16x32_bf16 v[32:35], v[170:173], v[196:199], v[100:103]
	v_mfma_f32_16x16x32_bf16 v[16:19], v[120:123], v[204:207], v[16:19]
	v_mfma_f32_16x16x32_bf16 v[8:11], v[124:127], v[36:39], v[8:11]
	v_mfma_f32_16x16x32_bf16 v[12:15], v[174:177], v[36:39], v[12:15]
	v_mfma_f32_16x16x32_bf16 v[196:199], v[174:177], v[200:203], v[32:35]
	v_mfma_f32_16x16x32_bf16 v[200:203], v[124:127], v[208:211], v[16:19]
	v_mfma_f32_16x16x32_bf16 v[16:19], v[170:173], v[204:207], v[20:23]
	v_mfma_f32_16x16x32_bf16 v[170:173], v[174:177], v[208:211], v[16:19]
	s_barrier
	ds_read_b128 v[60:63], v224
	ds_read_b128 v[174:177], v224 offset:1024
	ds_read_b128 v[204:207], v224 offset:2048
	ds_read_b128 v[208:211], v224 offset:3072
	ds_read_b128 v[212:215], v228
	ds_read_b128 v[220:223], v228 offset:1024
	ds_read_b128 v[224:227], v228 offset:2048
	ds_read_b128 v[228:231], v228 offset:3072
	s_add_u32 s38, s50, 0x10000
	s_addc_u32 s39, s51, 0
	s_mov_b32 m0, s33
	ds_read_b128 v[16:19], v145 offset:32768
	ds_read_b128 v[20:23], v145 offset:33792
	ds_read_b128 v[108:111], v145 offset:34816
	ds_read_b128 v[232:235], v145 offset:35840
	ds_read_b128 v[236:239], v145 offset:36864
	ds_read_b128 v[240:243], v145 offset:37888
	ds_read_b128 v[244:247], v145 offset:38912
	ds_read_b128 v[248:251], v145 offset:39936
	global_load_lds_dwordx4 v128, s[38:39]
	s_mov_b32 m0, s42
	s_nop 0
	global_load_lds_dwordx4 v132, s[38:39]
	s_waitcnt vmcnt(8)
	s_waitcnt lgkmcnt(0)
	s_barrier
; #define PG8_STAGE(bufoff, gbase, voff) do { _Pragma("unroll") for (int _i = 0; _i < 2; ++_i) \
;         __builtin_amdgcn_global_load_lds((const unsigned*)((const char*)(gbase) + (voff)[_i]), (PG8_LAS unsigned*)(lds + (bufoff) + ldsw + _i * 8192), 16, 0, 0); } while (0)
; #define PG8_LDA(dst, b, h) do { _Pragma("unroll") for (int m = 0; m < 4; ++m) _Pragma("unroll") for (int k = 0; k < 2; ++k) dst[m][k] = *(const PG8_LAS bf16x8*)(lds + PG8_SA(b, h) + aoff + m * 2048 + k * 1024); } while (0)
; #define PG8_LDB(dst, b, h) do { _Pragma("unroll") for (int n = 0; n < 2; ++n) _Pragma("unroll") for (int k = 0; k < 2; ++k) dst[n][k] = *(const PG8_LAS bf16x8*)(lds + PG8_SB(b, h) + boff + n * 2048 + k * 1024); } while (0)
; #define PG8_MMA(ai, bj, At, Bt) do { __builtin_amdgcn_s_setprio(1); _Pragma("unroll") for (int m = 0; m < 4; ++m) _Pragma("unroll") for (int n = 0; n < 2; ++n) _Pragma("unroll") for (int k = 0; k < 2; ++k) \
;         acc[ai][bj][m][n] = __builtin_amdgcn_mfma_f32_16x16x32_bf16(Bt[n][k], At[m][k], acc[ai][bj][m][n], 0, 0, 0); __builtin_amdgcn_s_setprio(0); } while (0)
; template <class Epi, class Sched, bool ALIGN_EPI = false, bool SP2 = false>
; __device__ __forceinline__ void gemm_phase(PG8_LAS unsigned char* lds, const Gemm g, const Sched& S, const Epi& E) {
;     ...
;             PG8_LDB(B0, 0, 0); PG8_LDB(B1, 0, 1); PG8_SCHED; PG8_LDA(At, 0, 0); PG8_STAGE(PG8_SA(1, 1), a1 + hstepA, voffA);
;             PG8_WAIT_V(8); PG8_WAIT_L(0); PG8_BAR; PG8_MMA(0, 0, At, B0); PG8_MMA(0, 1, At, B1); PG8_BAR; PG8_SCHED;
;             PG8_LDA(At, 0, 1); PG8_STAGE(PG8_SB(0, 0), b2, voffB); PG8_STAGE(PG8_SB(0, 1), b2 + hstepB, voffB); PG8_STAGE(PG8_SA(0, 0), a2, voffA);
;             PG8_WAIT_V(8); PG8_WAIT_L(0); PG8_BAR; PG8_MMA(1, 0, At, B0); PG8_MMA(1, 1, At, B1); PG8_BAR; PG8_SCHED;
;             PG8_LDB(B0, 1, 0); PG8_LDB(B1, 1, 1); PG8_SCHED; PG8_LDA(At, 1, 0); PG8_STAGE(PG8_SA(0, 1), a2 + hstepA, voffA);
;             PG8_WAIT_V(8); PG8_WAIT_L(0); PG8_BAR; PG8_MMA(0, 0, At, B0); PG8_MMA(0, 1, At, B1); PG8_BAR; PG8_SCHED;
;             PG8_LDA(At, 1, 1); PG8_STAGE(PG8_SB(1, 0), b3, voffB); PG8_STAGE(PG8_SB(1, 1), b3 + hstepB, voffB); PG8_STAGE(PG8_SA(1, 0), a3, voffA);
;             PG8_WAIT_V(8); PG8_WAIT_L(0); PG8_BAR; PG8_MMA(1, 0, At, B0); PG8_MMA(1, 1, At, B1); PG8_BAR; PG8_SCHED;
;     ...
;         if constexpr (ALIGN_EPI) { if (wr == 0) PG8_BAR; }
	s_waitcnt lgkmcnt(0)
	v_mfma_f32_16x16x32_bf16 v[32:35], v[60:63], v[16:19], v[64:67]
	v_mfma_f32_16x16x32_bf16 v[112:115], v[174:177], v[20:23], v[32:35]
	v_mfma_f32_16x16x32_bf16 v[32:35], v[204:207], v[16:19], v[68:71]
	v_mfma_f32_16x16x32_bf16 v[116:119], v[208:211], v[20:23], v[32:35]
	v_mfma_f32_16x16x32_bf16 v[32:35], v[60:63], v[108:111], v[72:75]
	v_mfma_f32_16x16x32_bf16 v[96:99], v[174:177], v[232:235], v[32:35]
	v_mfma_f32_16x16x32_bf16 v[32:35], v[204:207], v[108:111], v[76:79]
	v_mfma_f32_16x16x32_bf16 v[100:103], v[208:211], v[232:235], v[32:35]
	v_mfma_f32_16x16x32_bf16 v[32:35], v[60:63], v[236:239], v[80:83]
	v_mfma_f32_16x16x32_bf16 v[64:67], v[174:177], v[240:243], v[32:35]
	v_mfma_f32_16x16x32_bf16 v[32:35], v[204:207], v[236:239], v[84:87]
	v_mfma_f32_16x16x32_bf16 v[68:71], v[208:211], v[240:243], v[32:35]
	v_mfma_f32_16x16x32_bf16 v[32:35], v[60:63], v[244:247], v[88:91]
	v_mfma_f32_16x16x32_bf16 v[36:39], v[204:207], v[244:247], v[92:95]
	v_mfma_f32_16x16x32_bf16 v[32:35], v[174:177], v[248:251], v[32:35]
	v_mfma_f32_16x16x32_bf16 v[36:39], v[208:211], v[248:251], v[36:39]
	v_mfma_f32_16x16x32_bf16 v[72:75], v[212:215], v[16:19], v[216:219]
	v_mfma_f32_16x16x32_bf16 v[16:19], v[224:227], v[16:19], v[178:181]
	v_mfma_f32_16x16x32_bf16 v[124:127], v[228:231], v[20:23], v[16:19]
	v_mfma_f32_16x16x32_bf16 v[16:19], v[212:215], v[108:111], v[182:185]
	v_mfma_f32_16x16x32_bf16 v[104:107], v[220:223], v[232:235], v[16:19]
	v_mfma_f32_16x16x32_bf16 v[16:19], v[224:227], v[108:111], v[40:43]
	v_mfma_f32_16x16x32_bf16 v[108:111], v[228:231], v[232:235], v[16:19]
	v_mfma_f32_16x16x32_bf16 v[16:19], v[212:215], v[236:239], v[44:47]
	v_mfma_f32_16x16x32_bf16 v[120:123], v[220:223], v[20:23], v[72:75]
	v_mfma_f32_16x16x32_bf16 v[72:75], v[220:223], v[240:243], v[16:19]
	v_mfma_f32_16x16x32_bf16 v[16:19], v[224:227], v[236:239], v[48:51]
	v_mfma_f32_16x16x32_bf16 v[76:79], v[228:231], v[240:243], v[16:19]
	v_mfma_f32_16x16x32_bf16 v[16:19], v[212:215], v[244:247], v[52:55]
	v_mfma_f32_16x16x32_bf16 v[40:43], v[220:223], v[248:251], v[16:19]
	v_mfma_f32_16x16x32_bf16 v[16:19], v[224:227], v[244:247], v[56:59]
	v_mfma_f32_16x16x32_bf16 v[44:47], v[228:231], v[248:251], v[16:19]
	s_barrier
	s_mov_b32 m0, s64
	s_nop 3
	v_lshl_add_u64 v[16:17], v[190:191], 0, s[16:17]
	s_add_u32 s38, s46, 0x10080
	ds_read_b128 v[56:59], v145 offset:49152
	ds_read_b128 v[92:95], v145 offset:50176
	ds_read_b128 v[178:181], v145 offset:51200
	ds_read_b128 v[182:185], v145 offset:52224
	ds_read_b128 v[216:219], v145 offset:53248
	ds_read_b128 v[232:235], v145 offset:54272
	ds_read_b128 v[236:239], v145 offset:55296
	ds_read_b128 v[240:243], v145 offset:56320
	global_load_lds_dwordx4 v[16:17], off
	v_lshl_add_u64 v[16:17], v[252:253], 0, s[16:17]
	s_mov_b32 m0, s49
	s_addc_u32 s39, s47, 0
	global_load_lds_dwordx4 v[16:17], off
	s_mov_b32 m0, s40
	s_nop 0
	global_load_lds_dwordx4 v130, s[38:39]
	s_mov_b32 m0, s41
	s_nop 0
	global_load_lds_dwordx4 v134, s[38:39]
	v_lshl_add_u64 v[16:17], v[194:195], 0, s[16:17]
	s_mov_b32 m0, s53
	s_nop 0
	global_load_lds_dwordx4 v[16:17], off
	v_lshl_add_u64 v[16:17], v[192:193], 0, s[16:17]
	s_mov_b32 m0, s56
	s_nop 0
	global_load_lds_dwordx4 v[16:17], off
	s_waitcnt vmcnt(8)
	s_waitcnt lgkmcnt(0)
	s_barrier
	s_waitcnt lgkmcnt(0)
	v_mfma_f32_16x16x32_bf16 v[16:19], v[60:63], v[56:59], v[146:149]
	v_mfma_f32_16x16x32_bf16 v[80:83], v[174:177], v[92:95], v[16:19]
	v_mfma_f32_16x16x32_bf16 v[16:19], v[204:207], v[56:59], v[150:153]
	v_mfma_f32_16x16x32_bf16 v[84:87], v[208:211], v[92:95], v[16:19]
	v_mfma_f32_16x16x32_bf16 v[16:19], v[60:63], v[178:181], v[154:157]
	v_mfma_f32_16x16x32_bf16 v[48:51], v[174:177], v[182:185], v[16:19]
	v_mfma_f32_16x16x32_bf16 v[16:19], v[204:207], v[178:181], v[158:161]
	v_mfma_f32_16x16x32_bf16 v[52:55], v[208:211], v[182:185], v[16:19]
	v_mfma_f32_16x16x32_bf16 v[16:19], v[60:63], v[216:219], v[162:165]
	v_mfma_f32_16x16x32_bf16 v[20:23], v[204:207], v[216:219], v[166:169]
	v_mfma_f32_16x16x32_bf16 v[0:3], v[60:63], v[236:239], v[0:3]
	v_mfma_f32_16x16x32_bf16 v[4:7], v[204:207], v[236:239], v[4:7]
	v_mfma_f32_16x16x32_bf16 v[16:19], v[174:177], v[232:235], v[16:19]
	v_mfma_f32_16x16x32_bf16 v[20:23], v[208:211], v[232:235], v[20:23]
	v_mfma_f32_16x16x32_bf16 v[0:3], v[174:177], v[240:243], v[0:3]
	v_mfma_f32_16x16x32_bf16 v[4:7], v[208:211], v[240:243], v[4:7]
	v_mfma_f32_16x16x32_bf16 v[8:11], v[212:215], v[56:59], v[8:11]
	v_mfma_f32_16x16x32_bf16 v[88:91], v[220:223], v[92:95], v[8:11]
	v_mfma_f32_16x16x32_bf16 v[8:11], v[224:227], v[56:59], v[12:15]
	v_mfma_f32_16x16x32_bf16 v[92:95], v[228:231], v[92:95], v[8:11]
	v_mfma_f32_16x16x32_bf16 v[8:11], v[212:215], v[178:181], v[24:27]
	v_mfma_f32_16x16x32_bf16 v[56:59], v[220:223], v[182:185], v[8:11]
	v_mfma_f32_16x16x32_bf16 v[8:11], v[224:227], v[178:181], v[28:31]
	v_mfma_f32_16x16x32_bf16 v[60:63], v[228:231], v[182:185], v[8:11]
	v_mfma_f32_16x16x32_bf16 v[8:11], v[212:215], v[216:219], v[186:189]
	v_mfma_f32_16x16x32_bf16 v[24:27], v[220:223], v[232:235], v[8:11]
	v_mfma_f32_16x16x32_bf16 v[8:11], v[224:227], v[216:219], v[196:199]
	v_mfma_f32_16x16x32_bf16 v[28:31], v[228:231], v[232:235], v[8:11]
	v_mfma_f32_16x16x32_bf16 v[8:11], v[212:215], v[236:239], v[200:203]
	v_mfma_f32_16x16x32_bf16 v[12:15], v[224:227], v[236:239], v[170:173]
	v_mfma_f32_16x16x32_bf16 v[8:11], v[220:223], v[240:243], v[8:11]
	v_mfma_f32_16x16x32_bf16 v[12:15], v[228:231], v[240:243], v[12:15]
	s_barrier
	s_andn2_b64 vcc, exec, s[18:19]
	s_cbranch_vccnz .LBB0_165
	s_barrier

; #define PG8_STAGE(bufoff, gbase, voff) do { _Pragma("unroll") for (int _i = 0; _i < 2; ++_i) \
;         __builtin_amdgcn_global_load_lds((const unsigned*)((const char*)(gbase) + (voff)[_i]), (PG8_LAS unsigned*)(lds + (bufoff) + ldsw + _i * 8192), 16, 0, 0); } while (0)
; #define PG8_LDA(dst, b, h) do { _Pragma("unroll") for (int m = 0; m < 4; ++m) _Pragma("unroll") for (int k = 0; k < 2; ++k) dst[m][k] = *(const PG8_LAS bf16x8*)(lds + PG8_SA(b, h) + aoff + m * 2048 + k * 1024); } while (0)
; #define PG8_LDB(dst, b, h) do { _Pragma("unroll") for (int n = 0; n < 2; ++n) _Pragma("unroll") for (int k = 0; k < 2; ++k) dst[n][k] = *(const PG8_LAS bf16x8*)(lds + PG8_SB(b, h) + boff + n * 2048 + k * 1024); } while (0)
; #define PG8_WAIT_V(n) asm volatile("s_waitcnt vmcnt(" #n ")" ::: "memory")
; #define PG8_WAIT_L(n) asm volatile("s_waitcnt lgkmcnt(" #n ")" ::: "memory")
; #define PG8_BAR __builtin_amdgcn_s_barrier()
; #define PG8_SCHED __builtin_amdgcn_sched_barrier(0)
; template <class Epi, class Sched, bool ALIGN_EPI = false, bool SP2 = false>
; __device__ __forceinline__ void gemm_phase(PG8_LAS unsigned char* lds, const Gemm g, const Sched& S, const Epi& E) {
;     ...
;             const bool last = (t == nt - 2);
;             const char* a1 = cA + (size_t)(t + 1) * kstep;
;             const char* a2 = last ? nA : cA + (size_t)(t + 2) * kstep; const char* b2 = last ? nB : cB + (size_t)(t + 2) * kstep;
;             const char* a3 = a2 + kstep; const char* b3 = b2 + kstep;
;             if (last && has_next) S.a_ready(nxt);
;             if constexpr (SP2) {
;             PG8_LDB(B0, 0, 0); PG8_LDB(B1, 0, 1); PG8_SCHED; PG8_LDA(At, 0, 0); PG8_STAGE(PG8_SA(1, 1), a1 + hstepA, voffA);
;             PG8_WAIT_V(8); PG8_WAIT_L(0); PG8_BAR; PG8_MMA(0, 0, At, B0); PG8_MMA(0, 1, At, B1); PG8_BAR; PG8_SCHED;
;             PG8_LDA(At, 0, 1); PG8_STAGE(PG8_SB(0, 0), b2, voffB); PG8_STAGE(PG8_SB(0, 1), b2 + hstepB, voffB); PG8_STAGE(PG8_SA(0, 0), a2, voffA);
;             PG8_WAIT_V(8); PG8_WAIT_L(0); PG8_BAR; PG8_MMA(1, 0, At, B0); PG8_MMA(1, 1, At, B1); PG8_BAR; PG8_SCHED;
;             PG8_LDB(B0, 1, 0); PG8_LDB(B1, 1, 1); PG8_SCHED; PG8_LDA(At, 1, 0); PG8_STAGE(PG8_SA(0, 1), a2 + hstepA, voffA);
;             PG8_WAIT_V(8); PG8_WAIT_L(0); PG8_BAR; PG8_MMA(0, 0, At, B0); PG8_MMA(0, 1, At, B1); PG8_BAR; PG8_SCHED;
.LBB0_186:
	ds_read_b128 v[150:153], v147
	ds_read_b128 v[154:157], v147 offset:1024
	ds_read_b128 v[158:161], v147 offset:2048
	ds_read_b128 v[162:165], v147 offset:3072
	ds_read_b128 v[166:169], v148
	ds_read_b128 v[170:173], v148 offset:1024
	ds_read_b128 v[174:177], v148 offset:2048
	ds_read_b128 v[178:181], v148 offset:3072
	s_add_u32 s36, s34, 0xfffc0080
	s_addc_u32 s37, s35, -1
	s_cmp_eq_u32 s64, 12
	s_cselect_b32 s39, s27, s37
	s_cselect_b32 s38, s60, s36
	s_cselect_b32 s37, s25, s63
	s_cselect_b32 s36, s61, s62
	s_add_i32 m0, s8, 0xc000
	ds_read_b128 v[182:185], v149
	ds_read_b128 v[186:189], v149 offset:1024
	ds_read_b128 v[196:199], v149 offset:2048
	ds_read_b128 v[200:203], v149 offset:3072
	ds_read_b128 v[204:207], v149 offset:4096
	ds_read_b128 v[208:211], v149 offset:5120
	ds_read_b128 v[212:215], v149 offset:6144
	ds_read_b128 v[216:219], v149 offset:7168
	global_load_lds_dwordx4 v136, s[34:35]
	s_add_i32 m0, s8, 0xe000
	s_nop 0
	global_load_lds_dwordx4 v138, s[34:35]
	s_waitcnt vmcnt(8)
	s_waitcnt lgkmcnt(0)
	s_barrier
	s_waitcnt lgkmcnt(0)
	v_mfma_f32_16x16x32_bf16 v[124:127], v[150:153], v[182:185], v[124:127]
	v_mfma_f32_16x16x32_bf16 v[120:123], v[158:161], v[182:185], v[120:123]
	v_mfma_f32_16x16x32_bf16 v[116:119], v[150:153], v[196:199], v[116:119]
	v_mfma_f32_16x16x32_bf16 v[112:115], v[158:161], v[196:199], v[112:115]
	v_mfma_f32_16x16x32_bf16 v[100:103], v[150:153], v[204:207], v[100:103]
	v_mfma_f32_16x16x32_bf16 v[96:99], v[158:161], v[204:207], v[96:99]
	v_mfma_f32_16x16x32_bf16 v[84:87], v[150:153], v[212:215], v[84:87]
	v_mfma_f32_16x16x32_bf16 v[80:83], v[158:161], v[212:215], v[80:83]
	v_mfma_f32_16x16x32_bf16 v[124:127], v[154:157], v[186:189], v[124:127]
	v_mfma_f32_16x16x32_bf16 v[120:123], v[162:165], v[186:189], v[120:123]
	v_mfma_f32_16x16x32_bf16 v[116:119], v[154:157], v[200:203], v[116:119]
	v_mfma_f32_16x16x32_bf16 v[112:115], v[162:165], v[200:203], v[112:115]
	v_mfma_f32_16x16x32_bf16 v[100:103], v[154:157], v[208:211], v[100:103]
	v_mfma_f32_16x16x32_bf16 v[96:99], v[162:165], v[208:211], v[96:99]
	v_mfma_f32_16x16x32_bf16 v[84:87], v[154:157], v[216:219], v[84:87]
	v_mfma_f32_16x16x32_bf16 v[80:83], v[162:165], v[216:219], v[80:83]
	v_mfma_f32_16x16x32_bf16 v[108:111], v[166:169], v[182:185], v[108:111]
	v_mfma_f32_16x16x32_bf16 v[104:107], v[174:177], v[182:185], v[104:107]
	v_mfma_f32_16x16x32_bf16 v[92:95], v[166:169], v[196:199], v[92:95]
	v_mfma_f32_16x16x32_bf16 v[88:91], v[174:177], v[196:199], v[88:91]
	v_mfma_f32_16x16x32_bf16 v[76:79], v[166:169], v[204:207], v[76:79]
	v_mfma_f32_16x16x32_bf16 v[72:75], v[174:177], v[204:207], v[72:75]
	v_mfma_f32_16x16x32_bf16 v[68:71], v[166:169], v[212:215], v[68:71]
	v_mfma_f32_16x16x32_bf16 v[64:67], v[174:177], v[212:215], v[64:67]
	v_mfma_f32_16x16x32_bf16 v[108:111], v[170:173], v[186:189], v[108:111]
	v_mfma_f32_16x16x32_bf16 v[104:107], v[178:181], v[186:189], v[104:107]
	v_mfma_f32_16x16x32_bf16 v[92:95], v[170:173], v[200:203], v[92:95]
	v_mfma_f32_16x16x32_bf16 v[88:91], v[178:181], v[200:203], v[88:91]
	v_mfma_f32_16x16x32_bf16 v[76:79], v[170:173], v[208:211], v[76:79]
	v_mfma_f32_16x16x32_bf16 v[72:75], v[178:181], v[208:211], v[72:75]
	v_mfma_f32_16x16x32_bf16 v[68:71], v[170:173], v[216:219], v[68:71]
	v_mfma_f32_16x16x32_bf16 v[64:67], v[178:181], v[216:219], v[64:67]
	s_barrier
	s_add_i32 s44, s53, s3
	v_lshl_add_u64 v[190:191], s[36:37], 0, v[130:131]
	s_mov_b32 m0, s44
	ds_read_b128 v[182:185], v149 offset:16384
	ds_read_b128 v[186:189], v149 offset:17408
	ds_read_b128 v[196:199], v149 offset:18432
	ds_read_b128 v[200:203], v149 offset:19456
	ds_read_b128 v[204:207], v149 offset:20480
	ds_read_b128 v[208:211], v149 offset:21504
	ds_read_b128 v[212:215], v149 offset:22528
	ds_read_b128 v[216:219], v149 offset:23552
	global_load_lds_dwordx4 v[190:191], off
	s_add_i32 m0, s44, 0x2000
	s_add_u32 s44, s36, 0x40000
	v_lshl_add_u64 v[192:193], s[36:37], 0, v[134:135]
	s_addc_u32 s45, s37, 0
	s_add_i32 s48, s56, s3
	global_load_lds_dwordx4 v[192:193], off
	s_mov_b32 m0, s48
	v_lshl_add_u64 v[220:221], s[38:39], 0, v[132:133]
	global_load_lds_dwordx4 v130, s[44:45]
	s_add_i32 m0, s48, 0x2000
	s_nop 0
	global_load_lds_dwordx4 v134, s[44:45]
	v_lshl_add_u64 v[194:195], s[38:39], 0, v[128:129]
	s_mov_b32 m0, s8
	s_nop 0
	global_load_lds_dwordx4 v[194:195], off
	s_mov_b32 m0, s9
	s_nop 0
	global_load_lds_dwordx4 v[220:221], off
	s_waitcnt vmcnt(8)
	s_waitcnt lgkmcnt(0)
	s_barrier
	s_waitcnt lgkmcnt(0)
	v_mfma_f32_16x16x32_bf16 v[60:63], v[150:153], v[182:185], v[60:63]
	v_mfma_f32_16x16x32_bf16 v[56:59], v[158:161], v[182:185], v[56:59]
	v_mfma_f32_16x16x32_bf16 v[52:55], v[150:153], v[196:199], v[52:55]
	v_mfma_f32_16x16x32_bf16 v[48:51], v[158:161], v[196:199], v[48:51]
	v_mfma_f32_16x16x32_bf16 v[36:39], v[150:153], v[204:207], v[36:39]
	v_mfma_f32_16x16x32_bf16 v[32:35], v[158:161], v[204:207], v[32:35]
	v_mfma_f32_16x16x32_bf16 v[20:23], v[150:153], v[212:215], v[20:23]
	v_mfma_f32_16x16x32_bf16 v[16:19], v[158:161], v[212:215], v[16:19]
	v_mfma_f32_16x16x32_bf16 v[60:63], v[154:157], v[186:189], v[60:63]
	v_mfma_f32_16x16x32_bf16 v[56:59], v[162:165], v[186:189], v[56:59]
	v_mfma_f32_16x16x32_bf16 v[52:55], v[154:157], v[200:203], v[52:55]
	v_mfma_f32_16x16x32_bf16 v[48:51], v[162:165], v[200:203], v[48:51]
	v_mfma_f32_16x16x32_bf16 v[36:39], v[154:157], v[208:211], v[36:39]
	v_mfma_f32_16x16x32_bf16 v[32:35], v[162:165], v[208:211], v[32:35]
	v_mfma_f32_16x16x32_bf16 v[20:23], v[154:157], v[216:219], v[20:23]
	v_mfma_f32_16x16x32_bf16 v[16:19], v[162:165], v[216:219], v[16:19]
	v_mfma_f32_16x16x32_bf16 v[44:47], v[166:169], v[182:185], v[44:47]
	v_mfma_f32_16x16x32_bf16 v[40:43], v[174:177], v[182:185], v[40:43]
	v_mfma_f32_16x16x32_bf16 v[28:31], v[166:169], v[196:199], v[28:31]
	v_mfma_f32_16x16x32_bf16 v[24:27], v[174:177], v[196:199], v[24:27]
	v_mfma_f32_16x16x32_bf16 v[12:15], v[166:169], v[204:207], v[12:15]
	v_mfma_f32_16x16x32_bf16 v[8:11], v[174:177], v[204:207], v[8:11]
	v_mfma_f32_16x16x32_bf16 v[4:7], v[166:169], v[212:215], v[4:7]
	v_mfma_f32_16x16x32_bf16 v[0:3], v[174:177], v[212:215], v[0:3]
	v_mfma_f32_16x16x32_bf16 v[44:47], v[170:173], v[186:189], v[44:47]
	v_mfma_f32_16x16x32_bf16 v[40:43], v[178:181], v[186:189], v[40:43]
	v_mfma_f32_16x16x32_bf16 v[28:31], v[170:173], v[200:203], v[28:31]
	v_mfma_f32_16x16x32_bf16 v[24:27], v[178:181], v[200:203], v[24:27]
	v_mfma_f32_16x16x32_bf16 v[12:15], v[170:173], v[208:211], v[12:15]
	v_mfma_f32_16x16x32_bf16 v[8:11], v[178:181], v[208:211], v[8:11]
	v_mfma_f32_16x16x32_bf16 v[4:7], v[170:173], v[216:219], v[4:7]
	v_mfma_f32_16x16x32_bf16 v[0:3], v[178:181], v[216:219], v[0:3]
	s_barrier
; #define PG8_STAGE(bufoff, gbase, voff) do { _Pragma("unroll") for (int _i = 0; _i < 2; ++_i) \
;         __builtin_amdgcn_global_load_lds((const unsigned*)((const char*)(gbase) + (voff)[_i]), (PG8_LAS unsigned*)(lds + (bufoff) + ldsw + _i * 8192), 16, 0, 0); } while (0)
; #define PG8_LDA(dst, b, h) do { _Pragma("unroll") for (int m = 0; m < 4; ++m) _Pragma("unroll") for (int k = 0; k < 2; ++k) dst[m][k] = *(const PG8_LAS bf16x8*)(lds + PG8_SA(b, h) + aoff + m * 2048 + k * 1024); } while (0)
; #define PG8_LDB(dst, b, h) do { _Pragma("unroll") for (int n = 0; n < 2; ++n) _Pragma("unroll") for (int k = 0; k < 2; ++k) dst[n][k] = *(const PG8_LAS bf16x8*)(lds + PG8_SB(b, h) + boff + n * 2048 + k * 1024); } while (0)
; #define PG8_MMA(ai, bj, At, Bt) do { __builtin_amdgcn_s_setprio(1); _Pragma("unroll") for (int m = 0; m < 4; ++m) _Pragma("unroll") for (int n = 0; n < 2; ++n) _Pragma("unroll") for (int k = 0; k < 2; ++k) \
;         acc[ai][bj][m][n] = __builtin_amdgcn_mfma_f32_16x16x32_bf16(Bt[n][k], At[m][k], acc[ai][bj][m][n], 0, 0, 0); __builtin_amdgcn_s_setprio(0); } while (0)
; #define PG8_WAIT_V(n) asm volatile("s_waitcnt vmcnt(" #n ")" ::: "memory")
; #define PG8_WAIT_L(n) asm volatile("s_waitcnt lgkmcnt(" #n ")" ::: "memory")
; #define PG8_BAR __builtin_amdgcn_s_barrier()
; #define PG8_SCHED __builtin_amdgcn_sched_barrier(0)
; template <class Epi, class Sched, bool ALIGN_EPI = false, bool SP2 = false>
; __device__ __forceinline__ void gemm_phase(PG8_LAS unsigned char* lds, const Gemm g, const Sched& S, const Epi& E) {
;     ...
;             PG8_LDA(At, 0, 1); PG8_STAGE(PG8_SB(0, 0), b2, voffB); PG8_STAGE(PG8_SB(0, 1), b2 + hstepB, voffB); PG8_STAGE(PG8_SA(0, 0), a2, voffA);
;             PG8_WAIT_V(8); PG8_WAIT_L(0); PG8_BAR; PG8_MMA(1, 0, At, B0); PG8_MMA(1, 1, At, B1); PG8_BAR; PG8_SCHED;
;             PG8_LDB(B0, 1, 0); PG8_LDB(B1, 1, 1); PG8_SCHED; PG8_LDA(At, 1, 0); PG8_STAGE(PG8_SA(0, 1), a2 + hstepA, voffA);
;             PG8_WAIT_V(8); PG8_WAIT_L(0); PG8_BAR; PG8_MMA(0, 0, At, B0); PG8_MMA(0, 1, At, B1); PG8_BAR; PG8_SCHED;
;             PG8_LDA(At, 1, 1); PG8_STAGE(PG8_SB(1, 0), b3, voffB); PG8_STAGE(PG8_SB(1, 1), b3 + hstepB, voffB); PG8_STAGE(PG8_SA(1, 0), a3, voffA);
;             PG8_WAIT_V(8); PG8_WAIT_L(0); PG8_BAR; PG8_MMA(1, 0, At, B0); PG8_MMA(1, 1, At, B1); PG8_BAR; PG8_SCHED;
;     ...
;         if constexpr (ALIGN_EPI) { if (wr == 0) PG8_BAR; }
	s_add_i32 s44, 0, 0x18000
	s_add_i32 s45, 0, 0x1c000
	v_add_u32_e32 v162, s44, v146
	v_add_u32_e32 v178, s45, v146
	ds_read_b128 v[150:153], v162
	ds_read_b128 v[154:157], v162 offset:1024
	ds_read_b128 v[158:161], v162 offset:2048
	ds_read_b128 v[162:165], v162 offset:3072
	ds_read_b128 v[166:169], v178
	ds_read_b128 v[170:173], v178 offset:1024
	ds_read_b128 v[174:177], v178 offset:2048
	ds_read_b128 v[178:181], v178 offset:3072
	s_add_u32 s38, s38, 0x40000
	s_addc_u32 s39, s39, 0
	s_mov_b32 m0, s23
	ds_read_b128 v[182:185], v149 offset:32768
	ds_read_b128 v[186:189], v149 offset:33792
	ds_read_b128 v[196:199], v149 offset:34816
	ds_read_b128 v[200:203], v149 offset:35840
	ds_read_b128 v[204:207], v149 offset:36864
	ds_read_b128 v[208:211], v149 offset:37888
	ds_read_b128 v[212:215], v149 offset:38912
	ds_read_b128 v[216:219], v149 offset:39936
	global_load_lds_dwordx4 v128, s[38:39]
	s_mov_b32 m0, s33
	s_nop 0
	global_load_lds_dwordx4 v132, s[38:39]
	s_waitcnt vmcnt(8)
	s_waitcnt lgkmcnt(0)
	s_barrier
	s_waitcnt lgkmcnt(0)
	v_mfma_f32_16x16x32_bf16 v[124:127], v[150:153], v[182:185], v[124:127]
	v_mfma_f32_16x16x32_bf16 v[120:123], v[158:161], v[182:185], v[120:123]
	v_mfma_f32_16x16x32_bf16 v[116:119], v[150:153], v[196:199], v[116:119]
	v_mfma_f32_16x16x32_bf16 v[112:115], v[158:161], v[196:199], v[112:115]
	v_mfma_f32_16x16x32_bf16 v[100:103], v[150:153], v[204:207], v[100:103]
	v_mfma_f32_16x16x32_bf16 v[96:99], v[158:161], v[204:207], v[96:99]
	v_mfma_f32_16x16x32_bf16 v[84:87], v[150:153], v[212:215], v[84:87]
	v_mfma_f32_16x16x32_bf16 v[80:83], v[158:161], v[212:215], v[80:83]
	v_mfma_f32_16x16x32_bf16 v[124:127], v[154:157], v[186:189], v[124:127]
	v_mfma_f32_16x16x32_bf16 v[120:123], v[162:165], v[186:189], v[120:123]
	v_mfma_f32_16x16x32_bf16 v[116:119], v[154:157], v[200:203], v[116:119]
	v_mfma_f32_16x16x32_bf16 v[112:115], v[162:165], v[200:203], v[112:115]
	v_mfma_f32_16x16x32_bf16 v[100:103], v[154:157], v[208:211], v[100:103]
	v_mfma_f32_16x16x32_bf16 v[96:99], v[162:165], v[208:211], v[96:99]
	v_mfma_f32_16x16x32_bf16 v[84:87], v[154:157], v[216:219], v[84:87]
	v_mfma_f32_16x16x32_bf16 v[80:83], v[162:165], v[216:219], v[80:83]
	v_mfma_f32_16x16x32_bf16 v[108:111], v[166:169], v[182:185], v[108:111]
	v_mfma_f32_16x16x32_bf16 v[104:107], v[174:177], v[182:185], v[104:107]
	v_mfma_f32_16x16x32_bf16 v[92:95], v[166:169], v[196:199], v[92:95]
	v_mfma_f32_16x16x32_bf16 v[88:91], v[174:177], v[196:199], v[88:91]
	v_mfma_f32_16x16x32_bf16 v[76:79], v[166:169], v[204:207], v[76:79]
	v_mfma_f32_16x16x32_bf16 v[72:75], v[174:177], v[204:207], v[72:75]
	v_mfma_f32_16x16x32_bf16 v[68:71], v[166:169], v[212:215], v[68:71]
	v_mfma_f32_16x16x32_bf16 v[64:67], v[174:177], v[212:215], v[64:67]
	v_mfma_f32_16x16x32_bf16 v[108:111], v[170:173], v[186:189], v[108:111]
	v_mfma_f32_16x16x32_bf16 v[104:107], v[178:181], v[186:189], v[104:107]
	v_mfma_f32_16x16x32_bf16 v[92:95], v[170:173], v[200:203], v[92:95]
	v_mfma_f32_16x16x32_bf16 v[88:91], v[178:181], v[200:203], v[88:91]
	v_mfma_f32_16x16x32_bf16 v[76:79], v[170:173], v[208:211], v[76:79]
	v_mfma_f32_16x16x32_bf16 v[72:75], v[178:181], v[208:211], v[72:75]
	v_mfma_f32_16x16x32_bf16 v[68:71], v[170:173], v[216:219], v[68:71]
	v_mfma_f32_16x16x32_bf16 v[64:67], v[178:181], v[216:219], v[64:67]
	s_barrier
	s_add_i32 s38, s44, s3
	v_lshl_add_u64 v[190:191], v[190:191], 0, s[16:17]
	s_mov_b32 m0, s38
	ds_read_b128 v[182:185], v149 offset:49152
	ds_read_b128 v[186:189], v149 offset:50176
	ds_read_b128 v[196:199], v149 offset:51200
	ds_read_b128 v[200:203], v149 offset:52224
	ds_read_b128 v[204:207], v149 offset:53248
	ds_read_b128 v[208:211], v149 offset:54272
	ds_read_b128 v[212:215], v149 offset:55296
	ds_read_b128 v[216:219], v149 offset:56320
	global_load_lds_dwordx4 v[190:191], off
	s_add_i32 m0, s38, 0x2000
	s_add_u32 s36, s36, 0x40080
	v_lshl_add_u64 v[190:191], v[192:193], 0, s[16:17]
	s_addc_u32 s37, s37, 0
	s_add_i32 s38, s45, s3
	global_load_lds_dwordx4 v[190:191], off
	s_mov_b32 m0, s38
	s_nop 0
	global_load_lds_dwordx4 v130, s[36:37]
	s_add_i32 m0, s38, 0x2000
	s_nop 0
	global_load_lds_dwordx4 v134, s[36:37]
	v_lshl_add_u64 v[190:191], v[194:195], 0, s[16:17]
	s_mov_b32 m0, s43
	s_nop 0
	global_load_lds_dwordx4 v[190:191], off
	v_lshl_add_u64 v[190:191], v[220:221], 0, s[16:17]
	s_mov_b32 m0, s50
	s_nop 0
	global_load_lds_dwordx4 v[190:191], off
	s_waitcnt vmcnt(8)
	s_waitcnt lgkmcnt(0)
	s_barrier
	s_waitcnt lgkmcnt(0)
	v_mfma_f32_16x16x32_bf16 v[60:63], v[150:153], v[182:185], v[60:63]
	v_mfma_f32_16x16x32_bf16 v[56:59], v[158:161], v[182:185], v[56:59]
	v_mfma_f32_16x16x32_bf16 v[52:55], v[150:153], v[196:199], v[52:55]
	v_mfma_f32_16x16x32_bf16 v[48:51], v[158:161], v[196:199], v[48:51]
	v_mfma_f32_16x16x32_bf16 v[36:39], v[150:153], v[204:207], v[36:39]
	v_mfma_f32_16x16x32_bf16 v[32:35], v[158:161], v[204:207], v[32:35]
	v_mfma_f32_16x16x32_bf16 v[20:23], v[150:153], v[212:215], v[20:23]
	v_mfma_f32_16x16x32_bf16 v[16:19], v[158:161], v[212:215], v[16:19]
	v_mfma_f32_16x16x32_bf16 v[60:63], v[154:157], v[186:189], v[60:63]
	v_mfma_f32_16x16x32_bf16 v[56:59], v[162:165], v[186:189], v[56:59]
	v_mfma_f32_16x16x32_bf16 v[52:55], v[154:157], v[200:203], v[52:55]
	v_mfma_f32_16x16x32_bf16 v[48:51], v[162:165], v[200:203], v[48:51]
	v_mfma_f32_16x16x32_bf16 v[36:39], v[154:157], v[208:211], v[36:39]
	v_mfma_f32_16x16x32_bf16 v[32:35], v[162:165], v[208:211], v[32:35]
	v_mfma_f32_16x16x32_bf16 v[20:23], v[154:157], v[216:219], v[20:23]
	v_mfma_f32_16x16x32_bf16 v[16:19], v[162:165], v[216:219], v[16:19]
	v_mfma_f32_16x16x32_bf16 v[44:47], v[166:169], v[182:185], v[44:47]
	v_mfma_f32_16x16x32_bf16 v[40:43], v[174:177], v[182:185], v[40:43]
	v_mfma_f32_16x16x32_bf16 v[28:31], v[166:169], v[196:199], v[28:31]
	v_mfma_f32_16x16x32_bf16 v[24:27], v[174:177], v[196:199], v[24:27]
	v_mfma_f32_16x16x32_bf16 v[12:15], v[166:169], v[204:207], v[12:15]
	v_mfma_f32_16x16x32_bf16 v[8:11], v[174:177], v[204:207], v[8:11]
	v_mfma_f32_16x16x32_bf16 v[4:7], v[166:169], v[212:215], v[4:7]
	v_mfma_f32_16x16x32_bf16 v[0:3], v[174:177], v[212:215], v[0:3]
	v_mfma_f32_16x16x32_bf16 v[44:47], v[170:173], v[186:189], v[44:47]
	v_mfma_f32_16x16x32_bf16 v[40:43], v[178:181], v[186:189], v[40:43]
	v_mfma_f32_16x16x32_bf16 v[28:31], v[170:173], v[200:203], v[28:31]
	v_mfma_f32_16x16x32_bf16 v[24:27], v[178:181], v[200:203], v[24:27]
	v_mfma_f32_16x16x32_bf16 v[12:15], v[170:173], v[208:211], v[12:15]
	v_mfma_f32_16x16x32_bf16 v[8:11], v[178:181], v[208:211], v[8:11]
	v_mfma_f32_16x16x32_bf16 v[4:7], v[170:173], v[216:219], v[4:7]
	v_mfma_f32_16x16x32_bf16 v[0:3], v[178:181], v[216:219], v[0:3]
	s_barrier
	s_add_i32 s64, s64, 2
	s_add_u32 s34, s34, 0x100
	s_addc_u32 s35, s35, 0
	s_add_u32 s62, s62, 0x100
	s_addc_u32 s63, s63, 0
	s_cmp_gt_u32 s64, 13
	s_cbranch_scc0 .LBB0_186
	s_and_b64 vcc, exec, s[18:19]
	s_cbranch_vccz .LBB0_189
	s_barrier

; #define PG8_STAGE(bufoff, gbase, voff) do { _Pragma("unroll") for (int _i = 0; _i < 2; ++_i) \
;         __builtin_amdgcn_global_load_lds((const unsigned*)((const char*)(gbase) + (voff)[_i]), (PG8_LAS unsigned*)(lds + (bufoff) + ldsw + _i * 8192), 16, 0, 0); } while (0)
; #define PG8_LDA(dst, b, h) do { _Pragma("unroll") for (int m = 0; m < 4; ++m) _Pragma("unroll") for (int k = 0; k < 2; ++k) dst[m][k] = *(const PG8_LAS bf16x8*)(lds + PG8_SA(b, h) + aoff + m * 2048 + k * 1024); } while (0)
; #define PG8_LDB(dst, b, h) do { _Pragma("unroll") for (int n = 0; n < 2; ++n) _Pragma("unroll") for (int k = 0; k < 2; ++k) dst[n][k] = *(const PG8_LAS bf16x8*)(lds + PG8_SB(b, h) + boff + n * 2048 + k * 1024); } while (0)
; #define PG8_WAIT_V(n) asm volatile("s_waitcnt vmcnt(" #n ")" ::: "memory")
; #define PG8_WAIT_L(n) asm volatile("s_waitcnt lgkmcnt(" #n ")" ::: "memory")
; #define PG8_BAR __builtin_amdgcn_s_barrier()
; #define PG8_SCHED __builtin_amdgcn_sched_barrier(0)
; template <class Epi, class Sched, bool ALIGN_EPI = false, bool SP2 = false>
; __device__ __forceinline__ void gemm_phase(PG8_LAS unsigned char* lds, const Gemm g, const Sched& S, const Epi& E) {
;     ...
;             const bool last = (t == nt - 2);
;             const char* a1 = cA + (size_t)(t + 1) * kstep;
;             const char* a2 = last ? nA : cA + (size_t)(t + 2) * kstep; const char* b2 = last ? nB : cB + (size_t)(t + 2) * kstep;
;             const char* a3 = a2 + kstep; const char* b3 = b2 + kstep;
;             if (last && has_next) S.a_ready(nxt);
;             if constexpr (SP2) {
;             PG8_LDB(B0, 0, 0); PG8_LDB(B1, 0, 1); PG8_SCHED; PG8_LDA(At, 0, 0); PG8_STAGE(PG8_SA(1, 1), a1 + hstepA, voffA);
;             PG8_WAIT_V(8); PG8_WAIT_L(0); PG8_BAR; PG8_MMA(0, 0, At, B0); PG8_MMA(0, 1, At, B1); PG8_BAR; PG8_SCHED;
;             PG8_LDA(At, 0, 1); PG8_STAGE(PG8_SB(0, 0), b2, voffB); PG8_STAGE(PG8_SB(0, 1), b2 + hstepB, voffB); PG8_STAGE(PG8_SA(0, 0), a2, voffA);
;             PG8_WAIT_V(8); PG8_WAIT_L(0); PG8_BAR; PG8_MMA(1, 0, At, B0); PG8_MMA(1, 1, At, B1); PG8_BAR; PG8_SCHED;
;             PG8_LDB(B0, 1, 0); PG8_LDB(B1, 1, 1); PG8_SCHED; PG8_LDA(At, 1, 0); PG8_STAGE(PG8_SA(0, 1), a2 + hstepA, voffA);
;             PG8_WAIT_V(8); PG8_WAIT_L(0); PG8_BAR; PG8_MMA(0, 0, At, B0); PG8_MMA(0, 1, At, B1); PG8_BAR; PG8_SCHED;
.LBB0_210:
	ds_read_b128 v[146:149], v143
	ds_read_b128 v[150:153], v143 offset:1024
	ds_read_b128 v[154:157], v143 offset:2048
	ds_read_b128 v[158:161], v143 offset:3072
	ds_read_b128 v[162:165], v144
	ds_read_b128 v[166:169], v144 offset:1024
	ds_read_b128 v[170:173], v144 offset:2048
	ds_read_b128 v[174:177], v144 offset:3072
	s_add_u32 s36, s34, 0xfffc0080
	s_addc_u32 s37, s35, -1
	s_cmp_eq_u32 s64, 12
	s_cselect_b32 s39, s25, s37
	s_cselect_b32 s38, s60, s36
	s_cselect_b32 s37, s23, s63
	s_cselect_b32 s36, s61, s62
	s_add_i32 m0, s31, 0xc000
	ds_read_b128 v[178:181], v145
	ds_read_b128 v[182:185], v145 offset:1024
	ds_read_b128 v[186:189], v145 offset:2048
	ds_read_b128 v[196:199], v145 offset:3072
	ds_read_b128 v[200:203], v145 offset:4096
	ds_read_b128 v[204:207], v145 offset:5120
	ds_read_b128 v[208:211], v145 offset:6144
	ds_read_b128 v[212:215], v145 offset:7168
	global_load_lds_dwordx4 v132, s[34:35]
	s_add_i32 m0, s31, 0xe000
	s_nop 0
	global_load_lds_dwordx4 v134, s[34:35]
	s_waitcnt vmcnt(8)
	s_waitcnt lgkmcnt(0)
	s_barrier
	s_waitcnt lgkmcnt(0)
	v_mfma_f32_16x16x32_bf16 v[124:127], v[146:149], v[178:181], v[124:127]
	v_mfma_f32_16x16x32_bf16 v[120:123], v[154:157], v[178:181], v[120:123]
	v_mfma_f32_16x16x32_bf16 v[108:111], v[146:149], v[186:189], v[108:111]
	v_mfma_f32_16x16x32_bf16 v[104:107], v[154:157], v[186:189], v[104:107]
	v_mfma_f32_16x16x32_bf16 v[92:95], v[146:149], v[200:203], v[92:95]
	v_mfma_f32_16x16x32_bf16 v[88:91], v[154:157], v[200:203], v[88:91]
	v_mfma_f32_16x16x32_bf16 v[76:79], v[146:149], v[208:211], v[76:79]
	v_mfma_f32_16x16x32_bf16 v[72:75], v[154:157], v[208:211], v[72:75]
	v_mfma_f32_16x16x32_bf16 v[124:127], v[150:153], v[182:185], v[124:127]
	v_mfma_f32_16x16x32_bf16 v[120:123], v[158:161], v[182:185], v[120:123]
	v_mfma_f32_16x16x32_bf16 v[108:111], v[150:153], v[196:199], v[108:111]
	v_mfma_f32_16x16x32_bf16 v[104:107], v[158:161], v[196:199], v[104:107]
	v_mfma_f32_16x16x32_bf16 v[92:95], v[150:153], v[204:207], v[92:95]
	v_mfma_f32_16x16x32_bf16 v[88:91], v[158:161], v[204:207], v[88:91]
	v_mfma_f32_16x16x32_bf16 v[76:79], v[150:153], v[212:215], v[76:79]
	v_mfma_f32_16x16x32_bf16 v[72:75], v[158:161], v[212:215], v[72:75]
	v_mfma_f32_16x16x32_bf16 v[116:119], v[162:165], v[178:181], v[116:119]
	v_mfma_f32_16x16x32_bf16 v[112:115], v[170:173], v[178:181], v[112:115]
	v_mfma_f32_16x16x32_bf16 v[100:103], v[162:165], v[186:189], v[100:103]
	v_mfma_f32_16x16x32_bf16 v[96:99], v[170:173], v[186:189], v[96:99]
	v_mfma_f32_16x16x32_bf16 v[84:87], v[162:165], v[200:203], v[84:87]
	v_mfma_f32_16x16x32_bf16 v[80:83], v[170:173], v[200:203], v[80:83]
	v_mfma_f32_16x16x32_bf16 v[68:71], v[162:165], v[208:211], v[68:71]
	v_mfma_f32_16x16x32_bf16 v[64:67], v[170:173], v[208:211], v[64:67]
	v_mfma_f32_16x16x32_bf16 v[116:119], v[166:169], v[182:185], v[116:119]
	v_mfma_f32_16x16x32_bf16 v[112:115], v[174:177], v[182:185], v[112:115]
	v_mfma_f32_16x16x32_bf16 v[100:103], v[166:169], v[196:199], v[100:103]
	v_mfma_f32_16x16x32_bf16 v[96:99], v[174:177], v[196:199], v[96:99]
	v_mfma_f32_16x16x32_bf16 v[84:87], v[166:169], v[204:207], v[84:87]
	v_mfma_f32_16x16x32_bf16 v[80:83], v[174:177], v[204:207], v[80:83]
	v_mfma_f32_16x16x32_bf16 v[68:71], v[166:169], v[212:215], v[68:71]
	v_mfma_f32_16x16x32_bf16 v[64:67], v[174:177], v[212:215], v[64:67]
	s_barrier
	s_add_i32 s44, s57, s9
	v_lshl_add_u64 v[190:191], s[36:37], 0, v[128:129]
	s_mov_b32 m0, s44
	ds_read_b128 v[178:181], v145 offset:16384
	ds_read_b128 v[182:185], v145 offset:17408
	ds_read_b128 v[186:189], v145 offset:18432
	ds_read_b128 v[196:199], v145 offset:19456
	ds_read_b128 v[200:203], v145 offset:20480
	ds_read_b128 v[204:207], v145 offset:21504
	ds_read_b128 v[208:211], v145 offset:22528
	ds_read_b128 v[212:215], v145 offset:23552
	global_load_lds_dwordx4 v[190:191], off
	s_add_i32 m0, s44, 0x2000
	s_add_u32 s44, s36, 0x40000
	v_lshl_add_u64 v[192:193], s[36:37], 0, v[130:131]
	s_addc_u32 s45, s37, 0
	s_add_i32 s48, s58, s9
	global_load_lds_dwordx4 v[192:193], off
	s_mov_b32 m0, s48
	v_lshl_add_u64 v[216:217], s[38:39], 0, v[130:131]
	global_load_lds_dwordx4 v128, s[44:45]
	s_add_i32 m0, s48, 0x2000
	s_nop 0
	global_load_lds_dwordx4 v130, s[44:45]
	v_lshl_add_u64 v[194:195], s[38:39], 0, v[128:129]
	s_mov_b32 m0, s31
	s_nop 0
	global_load_lds_dwordx4 v[194:195], off
	s_mov_b32 m0, s33
	s_nop 0
	global_load_lds_dwordx4 v[216:217], off
	s_waitcnt vmcnt(8)
	s_waitcnt lgkmcnt(0)
	s_barrier
	s_waitcnt lgkmcnt(0)
	v_mfma_f32_16x16x32_bf16 v[60:63], v[146:149], v[178:181], v[60:63]
	v_mfma_f32_16x16x32_bf16 v[56:59], v[154:157], v[178:181], v[56:59]
	v_mfma_f32_16x16x32_bf16 v[44:47], v[146:149], v[186:189], v[44:47]
	v_mfma_f32_16x16x32_bf16 v[40:43], v[154:157], v[186:189], v[40:43]
	v_mfma_f32_16x16x32_bf16 v[28:31], v[146:149], v[200:203], v[28:31]
	v_mfma_f32_16x16x32_bf16 v[24:27], v[154:157], v[200:203], v[24:27]
	v_mfma_f32_16x16x32_bf16 v[12:15], v[146:149], v[208:211], v[12:15]
	v_mfma_f32_16x16x32_bf16 v[8:11], v[154:157], v[208:211], v[8:11]
	v_mfma_f32_16x16x32_bf16 v[60:63], v[150:153], v[182:185], v[60:63]
	v_mfma_f32_16x16x32_bf16 v[56:59], v[158:161], v[182:185], v[56:59]
	v_mfma_f32_16x16x32_bf16 v[44:47], v[150:153], v[196:199], v[44:47]
	v_mfma_f32_16x16x32_bf16 v[40:43], v[158:161], v[196:199], v[40:43]
	v_mfma_f32_16x16x32_bf16 v[28:31], v[150:153], v[204:207], v[28:31]
	v_mfma_f32_16x16x32_bf16 v[24:27], v[158:161], v[204:207], v[24:27]
	v_mfma_f32_16x16x32_bf16 v[12:15], v[150:153], v[212:215], v[12:15]
	v_mfma_f32_16x16x32_bf16 v[8:11], v[158:161], v[212:215], v[8:11]
	v_mfma_f32_16x16x32_bf16 v[52:55], v[162:165], v[178:181], v[52:55]
	v_mfma_f32_16x16x32_bf16 v[48:51], v[170:173], v[178:181], v[48:51]
	v_mfma_f32_16x16x32_bf16 v[36:39], v[162:165], v[186:189], v[36:39]
	v_mfma_f32_16x16x32_bf16 v[32:35], v[170:173], v[186:189], v[32:35]
	v_mfma_f32_16x16x32_bf16 v[20:23], v[162:165], v[200:203], v[20:23]
	v_mfma_f32_16x16x32_bf16 v[16:19], v[170:173], v[200:203], v[16:19]
	v_mfma_f32_16x16x32_bf16 v[4:7], v[162:165], v[208:211], v[4:7]
	v_mfma_f32_16x16x32_bf16 v[0:3], v[170:173], v[208:211], v[0:3]
	v_mfma_f32_16x16x32_bf16 v[52:55], v[166:169], v[182:185], v[52:55]
	v_mfma_f32_16x16x32_bf16 v[48:51], v[174:177], v[182:185], v[48:51]
	v_mfma_f32_16x16x32_bf16 v[36:39], v[166:169], v[196:199], v[36:39]
	v_mfma_f32_16x16x32_bf16 v[32:35], v[174:177], v[196:199], v[32:35]
	v_mfma_f32_16x16x32_bf16 v[20:23], v[166:169], v[204:207], v[20:23]
	v_mfma_f32_16x16x32_bf16 v[16:19], v[174:177], v[204:207], v[16:19]
	v_mfma_f32_16x16x32_bf16 v[4:7], v[166:169], v[212:215], v[4:7]
	v_mfma_f32_16x16x32_bf16 v[0:3], v[174:177], v[212:215], v[0:3]
	s_barrier
; #define PG8_STAGE(bufoff, gbase, voff) do { _Pragma("unroll") for (int _i = 0; _i < 2; ++_i) \
;         __builtin_amdgcn_global_load_lds((const unsigned*)((const char*)(gbase) + (voff)[_i]), (PG8_LAS unsigned*)(lds + (bufoff) + ldsw + _i * 8192), 16, 0, 0); } while (0)
; #define PG8_LDA(dst, b, h) do { _Pragma("unroll") for (int m = 0; m < 4; ++m) _Pragma("unroll") for (int k = 0; k < 2; ++k) dst[m][k] = *(const PG8_LAS bf16x8*)(lds + PG8_SA(b, h) + aoff + m * 2048 + k * 1024); } while (0)
; #define PG8_LDB(dst, b, h) do { _Pragma("unroll") for (int n = 0; n < 2; ++n) _Pragma("unroll") for (int k = 0; k < 2; ++k) dst[n][k] = *(const PG8_LAS bf16x8*)(lds + PG8_SB(b, h) + boff + n * 2048 + k * 1024); } while (0)
; #define PG8_MMA(ai, bj, At, Bt) do { __builtin_amdgcn_s_setprio(1); _Pragma("unroll") for (int m = 0; m < 4; ++m) _Pragma("unroll") for (int n = 0; n < 2; ++n) _Pragma("unroll") for (int k = 0; k < 2; ++k) \
;         acc[ai][bj][m][n] = __builtin_amdgcn_mfma_f32_16x16x32_bf16(Bt[n][k], At[m][k], acc[ai][bj][m][n], 0, 0, 0); __builtin_amdgcn_s_setprio(0); } while (0)
; #define PG8_WAIT_V(n) asm volatile("s_waitcnt vmcnt(" #n ")" ::: "memory")
; #define PG8_WAIT_L(n) asm volatile("s_waitcnt lgkmcnt(" #n ")" ::: "memory")
; #define PG8_BAR __builtin_amdgcn_s_barrier()
; #define PG8_SCHED __builtin_amdgcn_sched_barrier(0)
; template <class Epi, class Sched, bool ALIGN_EPI = false, bool SP2 = false>
; __device__ __forceinline__ void gemm_phase(PG8_LAS unsigned char* lds, const Gemm g, const Sched& S, const Epi& E) {
;     ...
;             PG8_LDA(At, 0, 1); PG8_STAGE(PG8_SB(0, 0), b2, voffB); PG8_STAGE(PG8_SB(0, 1), b2 + hstepB, voffB); PG8_STAGE(PG8_SA(0, 0), a2, voffA);
;             PG8_WAIT_V(8); PG8_WAIT_L(0); PG8_BAR; PG8_MMA(1, 0, At, B0); PG8_MMA(1, 1, At, B1); PG8_BAR; PG8_SCHED;
;             PG8_LDB(B0, 1, 0); PG8_LDB(B1, 1, 1); PG8_SCHED; PG8_LDA(At, 1, 0); PG8_STAGE(PG8_SA(0, 1), a2 + hstepA, voffA);
;             PG8_WAIT_V(8); PG8_WAIT_L(0); PG8_BAR; PG8_MMA(0, 0, At, B0); PG8_MMA(0, 1, At, B1); PG8_BAR; PG8_SCHED;
;             PG8_LDA(At, 1, 1); PG8_STAGE(PG8_SB(1, 0), b3, voffB); PG8_STAGE(PG8_SB(1, 1), b3 + hstepB, voffB); PG8_STAGE(PG8_SA(1, 0), a3, voffA);
;             PG8_WAIT_V(8); PG8_WAIT_L(0); PG8_BAR; PG8_MMA(1, 0, At, B0); PG8_MMA(1, 1, At, B1); PG8_BAR; PG8_SCHED;
;     ...
;         if constexpr (ALIGN_EPI) { if (wr == 0) PG8_BAR; }
	s_add_i32 s44, 0, 0x18000
	s_add_i32 s45, 0, 0x1c000
	v_add_u32_e32 v158, s44, v142
	v_add_u32_e32 v174, s45, v142
	ds_read_b128 v[146:149], v158
	ds_read_b128 v[150:153], v158 offset:1024
	ds_read_b128 v[154:157], v158 offset:2048
	ds_read_b128 v[158:161], v158 offset:3072
	ds_read_b128 v[162:165], v174
	ds_read_b128 v[166:169], v174 offset:1024
	ds_read_b128 v[170:173], v174 offset:2048
	ds_read_b128 v[174:177], v174 offset:3072
	s_add_u32 s38, s38, 0x40000
	s_addc_u32 s39, s39, 0
	s_mov_b32 m0, s40
	ds_read_b128 v[178:181], v145 offset:32768
	ds_read_b128 v[182:185], v145 offset:33792
	ds_read_b128 v[186:189], v145 offset:34816
	ds_read_b128 v[196:199], v145 offset:35840
	ds_read_b128 v[200:203], v145 offset:36864
	ds_read_b128 v[204:207], v145 offset:37888
	ds_read_b128 v[208:211], v145 offset:38912
	ds_read_b128 v[212:215], v145 offset:39936
	global_load_lds_dwordx4 v128, s[38:39]
	s_mov_b32 m0, s41
	s_nop 0
	global_load_lds_dwordx4 v130, s[38:39]
	s_waitcnt vmcnt(8)
	s_waitcnt lgkmcnt(0)
	s_barrier
	s_waitcnt lgkmcnt(0)
	v_mfma_f32_16x16x32_bf16 v[124:127], v[146:149], v[178:181], v[124:127]
	v_mfma_f32_16x16x32_bf16 v[120:123], v[154:157], v[178:181], v[120:123]
	v_mfma_f32_16x16x32_bf16 v[108:111], v[146:149], v[186:189], v[108:111]
	v_mfma_f32_16x16x32_bf16 v[104:107], v[154:157], v[186:189], v[104:107]
	v_mfma_f32_16x16x32_bf16 v[92:95], v[146:149], v[200:203], v[92:95]
	v_mfma_f32_16x16x32_bf16 v[88:91], v[154:157], v[200:203], v[88:91]
	v_mfma_f32_16x16x32_bf16 v[76:79], v[146:149], v[208:211], v[76:79]
	v_mfma_f32_16x16x32_bf16 v[72:75], v[154:157], v[208:211], v[72:75]
	v_mfma_f32_16x16x32_bf16 v[124:127], v[150:153], v[182:185], v[124:127]
	v_mfma_f32_16x16x32_bf16 v[120:123], v[158:161], v[182:185], v[120:123]
	v_mfma_f32_16x16x32_bf16 v[108:111], v[150:153], v[196:199], v[108:111]
	v_mfma_f32_16x16x32_bf16 v[104:107], v[158:161], v[196:199], v[104:107]
	v_mfma_f32_16x16x32_bf16 v[92:95], v[150:153], v[204:207], v[92:95]
	v_mfma_f32_16x16x32_bf16 v[88:91], v[158:161], v[204:207], v[88:91]
	v_mfma_f32_16x16x32_bf16 v[76:79], v[150:153], v[212:215], v[76:79]
	v_mfma_f32_16x16x32_bf16 v[72:75], v[158:161], v[212:215], v[72:75]
	v_mfma_f32_16x16x32_bf16 v[116:119], v[162:165], v[178:181], v[116:119]
	v_mfma_f32_16x16x32_bf16 v[112:115], v[170:173], v[178:181], v[112:115]
	v_mfma_f32_16x16x32_bf16 v[100:103], v[162:165], v[186:189], v[100:103]
	v_mfma_f32_16x16x32_bf16 v[96:99], v[170:173], v[186:189], v[96:99]
	v_mfma_f32_16x16x32_bf16 v[84:87], v[162:165], v[200:203], v[84:87]
	v_mfma_f32_16x16x32_bf16 v[80:83], v[170:173], v[200:203], v[80:83]
	v_mfma_f32_16x16x32_bf16 v[68:71], v[162:165], v[208:211], v[68:71]
	v_mfma_f32_16x16x32_bf16 v[64:67], v[170:173], v[208:211], v[64:67]
	v_mfma_f32_16x16x32_bf16 v[116:119], v[166:169], v[182:185], v[116:119]
	v_mfma_f32_16x16x32_bf16 v[112:115], v[174:177], v[182:185], v[112:115]
	v_mfma_f32_16x16x32_bf16 v[100:103], v[166:169], v[196:199], v[100:103]
	v_mfma_f32_16x16x32_bf16 v[96:99], v[174:177], v[196:199], v[96:99]
	v_mfma_f32_16x16x32_bf16 v[84:87], v[166:169], v[204:207], v[84:87]
	v_mfma_f32_16x16x32_bf16 v[80:83], v[174:177], v[204:207], v[80:83]
	v_mfma_f32_16x16x32_bf16 v[68:71], v[166:169], v[212:215], v[68:71]
	v_mfma_f32_16x16x32_bf16 v[64:67], v[174:177], v[212:215], v[64:67]
	s_barrier
	s_add_i32 s38, s44, s9
	v_lshl_add_u64 v[190:191], v[190:191], 0, s[16:17]
	s_mov_b32 m0, s38
	ds_read_b128 v[178:181], v145 offset:49152
	ds_read_b128 v[182:185], v145 offset:50176
	ds_read_b128 v[186:189], v145 offset:51200
	ds_read_b128 v[196:199], v145 offset:52224
	ds_read_b128 v[200:203], v145 offset:53248
	ds_read_b128 v[204:207], v145 offset:54272
	ds_read_b128 v[208:211], v145 offset:55296
	ds_read_b128 v[212:215], v145 offset:56320
	global_load_lds_dwordx4 v[190:191], off
	s_add_i32 m0, s38, 0x2000
	s_add_u32 s36, s36, 0x40080
	v_lshl_add_u64 v[190:191], v[192:193], 0, s[16:17]
	s_addc_u32 s37, s37, 0
	s_add_i32 s38, s45, s9
	global_load_lds_dwordx4 v[190:191], off
	s_mov_b32 m0, s38
	s_nop 0
	global_load_lds_dwordx4 v128, s[36:37]
	s_add_i32 m0, s38, 0x2000
	s_nop 0
	global_load_lds_dwordx4 v130, s[36:37]
	v_lshl_add_u64 v[190:191], v[194:195], 0, s[16:17]
	s_mov_b32 m0, s50
	s_nop 0
	global_load_lds_dwordx4 v[190:191], off
	v_lshl_add_u64 v[190:191], v[216:217], 0, s[16:17]
	s_mov_b32 m0, s51
	s_nop 0
	global_load_lds_dwordx4 v[190:191], off
	s_waitcnt vmcnt(8)
	s_waitcnt lgkmcnt(0)
	s_barrier
	s_waitcnt lgkmcnt(0)
	v_mfma_f32_16x16x32_bf16 v[60:63], v[146:149], v[178:181], v[60:63]
	v_mfma_f32_16x16x32_bf16 v[56:59], v[154:157], v[178:181], v[56:59]
	v_mfma_f32_16x16x32_bf16 v[44:47], v[146:149], v[186:189], v[44:47]
	v_mfma_f32_16x16x32_bf16 v[40:43], v[154:157], v[186:189], v[40:43]
	v_mfma_f32_16x16x32_bf16 v[28:31], v[146:149], v[200:203], v[28:31]
	v_mfma_f32_16x16x32_bf16 v[24:27], v[154:157], v[200:203], v[24:27]
	v_mfma_f32_16x16x32_bf16 v[12:15], v[146:149], v[208:211], v[12:15]
	v_mfma_f32_16x16x32_bf16 v[8:11], v[154:157], v[208:211], v[8:11]
	v_mfma_f32_16x16x32_bf16 v[60:63], v[150:153], v[182:185], v[60:63]
	v_mfma_f32_16x16x32_bf16 v[56:59], v[158:161], v[182:185], v[56:59]
	v_mfma_f32_16x16x32_bf16 v[44:47], v[150:153], v[196:199], v[44:47]
	v_mfma_f32_16x16x32_bf16 v[40:43], v[158:161], v[196:199], v[40:43]
	v_mfma_f32_16x16x32_bf16 v[28:31], v[150:153], v[204:207], v[28:31]
	v_mfma_f32_16x16x32_bf16 v[24:27], v[158:161], v[204:207], v[24:27]
	v_mfma_f32_16x16x32_bf16 v[12:15], v[150:153], v[212:215], v[12:15]
	v_mfma_f32_16x16x32_bf16 v[8:11], v[158:161], v[212:215], v[8:11]
	v_mfma_f32_16x16x32_bf16 v[52:55], v[162:165], v[178:181], v[52:55]
	v_mfma_f32_16x16x32_bf16 v[48:51], v[170:173], v[178:181], v[48:51]
	v_mfma_f32_16x16x32_bf16 v[36:39], v[162:165], v[186:189], v[36:39]
	v_mfma_f32_16x16x32_bf16 v[32:35], v[170:173], v[186:189], v[32:35]
	v_mfma_f32_16x16x32_bf16 v[20:23], v[162:165], v[200:203], v[20:23]
	v_mfma_f32_16x16x32_bf16 v[16:19], v[170:173], v[200:203], v[16:19]
	v_mfma_f32_16x16x32_bf16 v[4:7], v[162:165], v[208:211], v[4:7]
	v_mfma_f32_16x16x32_bf16 v[0:3], v[170:173], v[208:211], v[0:3]
	v_mfma_f32_16x16x32_bf16 v[52:55], v[166:169], v[182:185], v[52:55]
	v_mfma_f32_16x16x32_bf16 v[48:51], v[174:177], v[182:185], v[48:51]
	v_mfma_f32_16x16x32_bf16 v[36:39], v[166:169], v[196:199], v[36:39]
	v_mfma_f32_16x16x32_bf16 v[32:35], v[174:177], v[196:199], v[32:35]
	v_mfma_f32_16x16x32_bf16 v[20:23], v[166:169], v[204:207], v[20:23]
	v_mfma_f32_16x16x32_bf16 v[16:19], v[174:177], v[204:207], v[16:19]
	v_mfma_f32_16x16x32_bf16 v[4:7], v[166:169], v[212:215], v[4:7]
	v_mfma_f32_16x16x32_bf16 v[0:3], v[174:177], v[212:215], v[0:3]
	s_barrier
	s_add_i32 s64, s64, 2
	s_add_u32 s34, s34, 0x100
	s_addc_u32 s35, s35, 0
	s_add_u32 s62, s62, 0x100
	s_addc_u32 s63, s63, 0
	s_cmp_gt_u32 s64, 13
	s_cbranch_scc0 .LBB0_210
	s_and_b64 vcc, exec, s[18:19]
	s_cbranch_vccz .LBB0_213
	s_barrier

; #define PG8_STAGE(bufoff, gbase, voff) do { _Pragma("unroll") for (int _i = 0; _i < 2; ++_i) \
;         __builtin_amdgcn_global_load_lds((const unsigned*)((const char*)(gbase) + (voff)[_i]), (PG8_LAS unsigned*)(lds + (bufoff) + ldsw + _i * 8192), 16, 0, 0); } while (0)
; #define PG8_LDA(dst, b, h) do { _Pragma("unroll") for (int m = 0; m < 4; ++m) _Pragma("unroll") for (int k = 0; k < 2; ++k) dst[m][k] = *(const PG8_LAS bf16x8*)(lds + PG8_SA(b, h) + aoff + m * 2048 + k * 1024); } while (0)
; template <class Epi, class Sched, bool ALIGN_EPI = false, bool SP2 = false>
; __device__ __forceinline__ void gemm_phase(PG8_LAS unsigned char* lds, const Gemm g, const Sched& S, const Epi& E) {
;     ...
;         const bool has_next = S.next(ui + 1, nxt);
;         const char* nA = has_next ? (const char*)g.A + (size_t)nxt.pm * tstepA : cA; const char* nB = has_next ? (const char*)g.Bt + (size_t)nxt.pn * tstepB : cB;
;         for (int t = 0; t < nt; t += 2) {
;             const bool last = (t == nt - 2);
;             const char* a1 = cA + (size_t)(t + 1) * kstep;
;             const char* a2 = last ? nA : cA + (size_t)(t + 2) * kstep; const char* b2 = last ? nB : cB + (size_t)(t + 2) * kstep;
;             const char* a3 = a2 + kstep; const char* b3 = b2 + kstep;
;             if (last && has_next) S.a_ready(nxt);
;             if constexpr (SP2) {
;             PG8_LDB(B0, 0, 0); PG8_LDB(B1, 0, 1); PG8_SCHED; PG8_LDA(At, 0, 0); PG8_STAGE(PG8_SA(1, 1), a1 + hstepA, voffA);
;             PG8_WAIT_V(8); PG8_WAIT_L(0); PG8_BAR; PG8_MMA(0, 0, At, B0); PG8_MMA(0, 1, At, B1); PG8_BAR; PG8_SCHED;
;             PG8_LDA(At, 0, 1); PG8_STAGE(PG8_SB(0, 0), b2, voffB); PG8_STAGE(PG8_SB(0, 1), b2 + hstepB, voffB); PG8_STAGE(PG8_SA(0, 0), a2, voffA);
;             PG8_WAIT_V(8); PG8_WAIT_L(0); PG8_BAR; PG8_MMA(1, 0, At, B0); PG8_MMA(1, 1, At, B1); PG8_BAR; PG8_SCHED;
;             PG8_LDB(B0, 1, 0); PG8_LDB(B1, 1, 1); PG8_SCHED; PG8_LDA(At, 1, 0); PG8_STAGE(PG8_SA(0, 1), a2 + hstepA, voffA);
;             PG8_WAIT_V(8); PG8_WAIT_L(0); PG8_BAR; PG8_MMA(0, 0, At, B0); PG8_MMA(0, 1, At, B1); PG8_BAR; PG8_SCHED;
;             PG8_LDA(At, 1, 1); PG8_STAGE(PG8_SB(1, 0), b3, voffB); PG8_STAGE(PG8_SB(1, 1), b3 + hstepB, voffB); PG8_STAGE(PG8_SA(1, 0), a3, voffA);
;             PG8_WAIT_V(8); PG8_WAIT_L(0); PG8_BAR; PG8_MMA(1, 0, At, B0); PG8_MMA(1, 1, At, B1); PG8_BAR; PG8_SCHED;
.LBB0_234:
	ds_read_b128 v[0:3], v143
	ds_read_b128 v[4:7], v143 offset:1024
	ds_read_b128 v[8:11], v143 offset:2048
	ds_read_b128 v[12:15], v143 offset:3072
	ds_read_b128 v[16:19], v144
	ds_read_b128 v[20:23], v144 offset:1024
	ds_read_b128 v[24:27], v144 offset:2048
	ds_read_b128 v[28:31], v144 offset:3072
	s_ashr_i32 s31, s30, 31
	s_lshl_b64 s[34:35], s[30:31], 17
	s_add_u32 s34, s54, s34
	s_addc_u32 s35, s55, s35
	s_and_b64 s[36:37], s[4:5], exec
	s_cselect_b32 s53, s35, s39
	s_cselect_b32 s52, s34, s38
	s_ashr_i32 s29, s28, 31
	s_lshl_b64 s[36:37], s[28:29], 17
	s_add_u32 s36, s2, s36
	s_addc_u32 s37, s3, s37
	s_and_b64 s[44:45], s[4:5], exec
	s_cselect_b32 s51, s37, s41
	s_cselect_b32 s50, s36, s40
	s_add_u32 s44, s38, 0x10080
	s_addc_u32 s45, s39, 0
	s_add_i32 s62, s9, 0xc000
	s_mov_b32 m0, s62
	s_add_i32 s29, s9, 0xe000
	ds_read_b128 v[32:35], v145
	ds_read_b128 v[36:39], v145 offset:1024
	ds_read_b128 v[40:43], v145 offset:2048
	ds_read_b128 v[44:47], v145 offset:3072
	ds_read_b128 v[48:51], v145 offset:4096
	ds_read_b128 v[52:55], v145 offset:5120
	ds_read_b128 v[56:59], v145 offset:6144
	ds_read_b128 v[60:63], v145 offset:7168
	global_load_lds_dwordx4 v128, s[44:45]
	s_mov_b32 m0, s29
	s_nop 0
	global_load_lds_dwordx4 v132, s[44:45]
	s_waitcnt vmcnt(8)
	s_waitcnt lgkmcnt(0)
	s_barrier
	s_waitcnt lgkmcnt(0)
	v_mfma_f32_16x16x32_bf16 v[64:67], v[0:3], v[32:35], 0
	v_mfma_f32_16x16x32_bf16 v[68:71], v[8:11], v[32:35], 0
	v_mfma_f32_16x16x32_bf16 v[72:75], v[0:3], v[40:43], 0
	v_mfma_f32_16x16x32_bf16 v[76:79], v[8:11], v[40:43], 0
	v_mfma_f32_16x16x32_bf16 v[80:83], v[0:3], v[48:51], 0
	v_mfma_f32_16x16x32_bf16 v[84:87], v[8:11], v[48:51], 0
	v_mfma_f32_16x16x32_bf16 v[88:91], v[0:3], v[56:59], 0
	v_mfma_f32_16x16x32_bf16 v[92:95], v[8:11], v[56:59], 0
	v_mfma_f32_16x16x32_bf16 v[64:67], v[4:7], v[36:39], v[64:67]
	v_mfma_f32_16x16x32_bf16 v[68:71], v[12:15], v[36:39], v[68:71]
	v_mfma_f32_16x16x32_bf16 v[72:75], v[4:7], v[44:47], v[72:75]
	v_mfma_f32_16x16x32_bf16 v[76:79], v[12:15], v[44:47], v[76:79]
	v_mfma_f32_16x16x32_bf16 v[80:83], v[4:7], v[52:55], v[80:83]
	v_mfma_f32_16x16x32_bf16 v[84:87], v[12:15], v[52:55], v[84:87]
	v_mfma_f32_16x16x32_bf16 v[88:91], v[4:7], v[60:63], v[88:91]
	v_mfma_f32_16x16x32_bf16 v[92:95], v[12:15], v[60:63], v[92:95]
	v_mfma_f32_16x16x32_bf16 v[96:99], v[16:19], v[32:35], 0
	v_mfma_f32_16x16x32_bf16 v[32:35], v[24:27], v[32:35], 0
	v_mfma_f32_16x16x32_bf16 v[96:99], v[20:23], v[36:39], v[96:99]
	v_mfma_f32_16x16x32_bf16 v[32:35], v[28:31], v[36:39], v[32:35]
	v_mfma_f32_16x16x32_bf16 v[36:39], v[16:19], v[40:43], 0
	v_mfma_f32_16x16x32_bf16 v[40:43], v[24:27], v[40:43], 0
	v_mfma_f32_16x16x32_bf16 v[36:39], v[20:23], v[44:47], v[36:39]
	v_mfma_f32_16x16x32_bf16 v[40:43], v[28:31], v[44:47], v[40:43]
	v_mfma_f32_16x16x32_bf16 v[44:47], v[16:19], v[48:51], 0
	v_mfma_f32_16x16x32_bf16 v[48:51], v[24:27], v[48:51], 0
	v_mfma_f32_16x16x32_bf16 v[44:47], v[20:23], v[52:55], v[44:47]
	v_mfma_f32_16x16x32_bf16 v[48:51], v[28:31], v[52:55], v[48:51]
	v_mfma_f32_16x16x32_bf16 v[52:55], v[16:19], v[56:59], 0
	v_mfma_f32_16x16x32_bf16 v[56:59], v[24:27], v[56:59], 0
	v_mfma_f32_16x16x32_bf16 v[52:55], v[20:23], v[60:63], v[52:55]
	v_mfma_f32_16x16x32_bf16 v[56:59], v[28:31], v[60:63], v[56:59]
	s_barrier
	s_add_i32 s48, s59, s8
	v_lshl_add_u64 v[190:191], s[40:41], 0, v[130:131]
	s_add_i32 s31, s48, 0x2000
	v_lshl_add_u64 v[146:147], v[190:191], 0, s[22:23]
	s_mov_b32 m0, s48
	v_lshl_add_u64 v[192:193], s[40:41], 0, v[134:135]
	s_add_u32 s64, s40, 0x10100
	ds_read_b128 v[60:63], v145 offset:16384
	ds_read_b128 v[100:103], v145 offset:17408
	ds_read_b128 v[104:107], v145 offset:18432
	ds_read_b128 v[108:111], v145 offset:19456
	ds_read_b128 v[112:115], v145 offset:20480
	ds_read_b128 v[116:119], v145 offset:21504
	ds_read_b128 v[120:123], v145 offset:22528
	ds_read_b128 v[124:127], v145 offset:23552
	global_load_lds_dwordx4 v[146:147], off
	v_lshl_add_u64 v[146:147], v[192:193], 0, s[22:23]
	s_mov_b32 m0, s31
	s_addc_u32 s65, s41, 0
	s_add_i32 s44, s60, s8
	global_load_lds_dwordx4 v[146:147], off
	s_mov_b32 m0, s44
	s_add_i32 s45, s44, 0x2000
	global_load_lds_dwordx4 v130, s[64:65]
	s_mov_b32 m0, s45
	v_lshl_add_u64 v[194:195], s[38:39], 0, v[128:129]
	global_load_lds_dwordx4 v134, s[64:65]
	v_lshl_add_u64 v[146:147], v[194:195], 0, s[22:23]
	s_mov_b32 m0, s9
	v_lshl_add_u64 v[216:217], s[38:39], 0, v[132:133]
	global_load_lds_dwordx4 v[146:147], off
	v_lshl_add_u64 v[146:147], v[216:217], 0, s[22:23]
	s_mov_b32 m0, s10
	s_nop 0
	global_load_lds_dwordx4 v[146:147], off
	s_waitcnt vmcnt(8)
	s_waitcnt lgkmcnt(0)
	s_barrier
; #define PG8_STAGE(bufoff, gbase, voff) do { _Pragma("unroll") for (int _i = 0; _i < 2; ++_i) \
;         __builtin_amdgcn_global_load_lds((const unsigned*)((const char*)(gbase) + (voff)[_i]), (PG8_LAS unsigned*)(lds + (bufoff) + ldsw + _i * 8192), 16, 0, 0); } while (0)
; #define PG8_LDA(dst, b, h) do { _Pragma("unroll") for (int m = 0; m < 4; ++m) _Pragma("unroll") for (int k = 0; k < 2; ++k) dst[m][k] = *(const PG8_LAS bf16x8*)(lds + PG8_SA(b, h) + aoff + m * 2048 + k * 1024); } while (0)
; #define PG8_LDB(dst, b, h) do { _Pragma("unroll") for (int n = 0; n < 2; ++n) _Pragma("unroll") for (int k = 0; k < 2; ++k) dst[n][k] = *(const PG8_LAS bf16x8*)(lds + PG8_SB(b, h) + boff + n * 2048 + k * 1024); } while (0)
; #define PG8_MMA(ai, bj, At, Bt) do { __builtin_amdgcn_s_setprio(1); _Pragma("unroll") for (int m = 0; m < 4; ++m) _Pragma("unroll") for (int n = 0; n < 2; ++n) _Pragma("unroll") for (int k = 0; k < 2; ++k) \
;         acc[ai][bj][m][n] = __builtin_amdgcn_mfma_f32_16x16x32_bf16(Bt[n][k], At[m][k], acc[ai][bj][m][n], 0, 0, 0); __builtin_amdgcn_s_setprio(0); } while (0)
; #define PG8_WAIT_V(n) asm volatile("s_waitcnt vmcnt(" #n ")" ::: "memory")
; template <class Epi, class Sched, bool ALIGN_EPI = false, bool SP2 = false>
; __device__ __forceinline__ void gemm_phase(PG8_LAS unsigned char* lds, const Gemm g, const Sched& S, const Epi& E) {
;     ...
;             PG8_LDB(B0, 0, 0); PG8_LDB(B1, 0, 1); PG8_SCHED; PG8_LDA(At, 0, 0); PG8_STAGE(PG8_SA(1, 1), a1 + hstepA, voffA);
;             PG8_WAIT_V(8); PG8_WAIT_L(0); PG8_BAR; PG8_MMA(0, 0, At, B0); PG8_MMA(0, 1, At, B1); PG8_BAR; PG8_SCHED;
;             PG8_LDA(At, 0, 1); PG8_STAGE(PG8_SB(0, 0), b2, voffB); PG8_STAGE(PG8_SB(0, 1), b2 + hstepB, voffB); PG8_STAGE(PG8_SA(0, 0), a2, voffA);
;             PG8_WAIT_V(8); PG8_WAIT_L(0); PG8_BAR; PG8_MMA(1, 0, At, B0); PG8_MMA(1, 1, At, B1); PG8_BAR; PG8_SCHED;
;             PG8_LDB(B0, 1, 0); PG8_LDB(B1, 1, 1); PG8_SCHED; PG8_LDA(At, 1, 0); PG8_STAGE(PG8_SA(0, 1), a2 + hstepA, voffA);
;             PG8_WAIT_V(8); PG8_WAIT_L(0); PG8_BAR; PG8_MMA(0, 0, At, B0); PG8_MMA(0, 1, At, B1); PG8_BAR; PG8_SCHED;
;             PG8_LDA(At, 1, 1); PG8_STAGE(PG8_SB(1, 0), b3, voffB); PG8_STAGE(PG8_SB(1, 1), b3 + hstepB, voffB); PG8_STAGE(PG8_SA(1, 0), a3, voffA);
;             PG8_WAIT_V(8); PG8_WAIT_L(0); PG8_BAR; PG8_MMA(1, 0, At, B0); PG8_MMA(1, 1, At, B1); PG8_BAR; PG8_SCHED;
	s_waitcnt lgkmcnt(0)
	v_mfma_f32_16x16x32_bf16 v[146:149], v[0:3], v[60:63], 0
	v_mfma_f32_16x16x32_bf16 v[154:157], v[0:3], v[104:107], 0
	v_mfma_f32_16x16x32_bf16 v[162:165], v[0:3], v[112:115], 0
	v_mfma_f32_16x16x32_bf16 v[0:3], v[0:3], v[120:123], 0
	v_mfma_f32_16x16x32_bf16 v[146:149], v[4:7], v[100:103], v[146:149]
	v_mfma_f32_16x16x32_bf16 v[154:157], v[4:7], v[108:111], v[154:157]
	v_mfma_f32_16x16x32_bf16 v[162:165], v[4:7], v[116:119], v[162:165]
	v_mfma_f32_16x16x32_bf16 v[0:3], v[4:7], v[124:127], v[0:3]
	v_mfma_f32_16x16x32_bf16 v[4:7], v[8:11], v[120:123], 0
	v_mfma_f32_16x16x32_bf16 v[150:153], v[8:11], v[60:63], 0
	v_mfma_f32_16x16x32_bf16 v[158:161], v[8:11], v[104:107], 0
	v_mfma_f32_16x16x32_bf16 v[166:169], v[8:11], v[112:115], 0
	v_mfma_f32_16x16x32_bf16 v[4:7], v[12:15], v[124:127], v[4:7]
	v_mfma_f32_16x16x32_bf16 v[150:153], v[12:15], v[100:103], v[150:153]
	v_mfma_f32_16x16x32_bf16 v[158:161], v[12:15], v[108:111], v[158:161]
	v_mfma_f32_16x16x32_bf16 v[166:169], v[12:15], v[116:119], v[166:169]
	v_mfma_f32_16x16x32_bf16 v[8:11], v[16:19], v[60:63], 0
	v_mfma_f32_16x16x32_bf16 v[12:15], v[24:27], v[60:63], 0
	v_mfma_f32_16x16x32_bf16 v[8:11], v[20:23], v[100:103], v[8:11]
	v_mfma_f32_16x16x32_bf16 v[12:15], v[28:31], v[100:103], v[12:15]
	v_mfma_f32_16x16x32_bf16 v[60:63], v[16:19], v[104:107], 0
	v_mfma_f32_16x16x32_bf16 v[100:103], v[24:27], v[104:107], 0
	v_mfma_f32_16x16x32_bf16 v[104:107], v[16:19], v[112:115], 0
	v_mfma_f32_16x16x32_bf16 v[16:19], v[16:19], v[120:123], 0
	v_mfma_f32_16x16x32_bf16 v[60:63], v[20:23], v[108:111], v[60:63]
	v_mfma_f32_16x16x32_bf16 v[100:103], v[28:31], v[108:111], v[100:103]
	v_mfma_f32_16x16x32_bf16 v[104:107], v[20:23], v[116:119], v[104:107]
	v_mfma_f32_16x16x32_bf16 v[108:111], v[24:27], v[112:115], 0
	v_mfma_f32_16x16x32_bf16 v[16:19], v[20:23], v[124:127], v[16:19]
	v_mfma_f32_16x16x32_bf16 v[20:23], v[24:27], v[120:123], 0
	v_mfma_f32_16x16x32_bf16 v[108:111], v[28:31], v[116:119], v[108:111]
	v_mfma_f32_16x16x32_bf16 v[20:23], v[28:31], v[124:127], v[20:23]
	s_barrier
	s_add_i32 s63, 0, 0x18000
	s_add_i32 s66, 0, 0x1c000
	v_add_u32_e32 v220, s63, v142
	v_add_u32_e32 v228, s66, v142
	ds_read_b128 v[24:27], v220
	ds_read_b128 v[28:31], v220 offset:1024
	ds_read_b128 v[112:115], v220 offset:2048
	ds_read_b128 v[116:119], v220 offset:3072
	ds_read_b128 v[120:123], v228
	ds_read_b128 v[124:127], v228 offset:1024
	ds_read_b128 v[170:173], v228 offset:2048
	ds_read_b128 v[174:177], v228 offset:3072
	s_add_u32 s64, s38, 0x10100
	s_addc_u32 s65, s39, 0
	s_mov_b32 m0, s11
	ds_read_b128 v[178:181], v145 offset:32768
	ds_read_b128 v[182:185], v145 offset:33792
	ds_read_b128 v[186:189], v145 offset:34816
	ds_read_b128 v[196:199], v145 offset:35840
	ds_read_b128 v[200:203], v145 offset:36864
	ds_read_b128 v[204:207], v145 offset:37888
	ds_read_b128 v[208:211], v145 offset:38912
	ds_read_b128 v[212:215], v145 offset:39936
	global_load_lds_dwordx4 v128, s[64:65]
	s_mov_b32 m0, s27
	s_nop 0
	global_load_lds_dwordx4 v132, s[64:65]
	s_waitcnt vmcnt(8)
	s_waitcnt lgkmcnt(0)
	s_barrier
	s_waitcnt lgkmcnt(0)
	v_mfma_f32_16x16x32_bf16 v[64:67], v[24:27], v[178:181], v[64:67]
	v_mfma_f32_16x16x32_bf16 v[68:71], v[112:115], v[178:181], v[68:71]
	v_mfma_f32_16x16x32_bf16 v[72:75], v[24:27], v[186:189], v[72:75]
	v_mfma_f32_16x16x32_bf16 v[76:79], v[112:115], v[186:189], v[76:79]
	v_mfma_f32_16x16x32_bf16 v[80:83], v[24:27], v[200:203], v[80:83]
	v_mfma_f32_16x16x32_bf16 v[84:87], v[112:115], v[200:203], v[84:87]
	v_mfma_f32_16x16x32_bf16 v[88:91], v[24:27], v[208:211], v[88:91]
	v_mfma_f32_16x16x32_bf16 v[92:95], v[112:115], v[208:211], v[92:95]
	v_mfma_f32_16x16x32_bf16 v[64:67], v[28:31], v[182:185], v[64:67]
	v_mfma_f32_16x16x32_bf16 v[68:71], v[116:119], v[182:185], v[68:71]
	v_mfma_f32_16x16x32_bf16 v[72:75], v[28:31], v[196:199], v[72:75]
	v_mfma_f32_16x16x32_bf16 v[76:79], v[116:119], v[196:199], v[76:79]
	v_mfma_f32_16x16x32_bf16 v[80:83], v[28:31], v[204:207], v[80:83]
	v_mfma_f32_16x16x32_bf16 v[84:87], v[116:119], v[204:207], v[84:87]
	v_mfma_f32_16x16x32_bf16 v[88:91], v[28:31], v[212:215], v[88:91]
	v_mfma_f32_16x16x32_bf16 v[92:95], v[116:119], v[212:215], v[92:95]
	v_mfma_f32_16x16x32_bf16 v[96:99], v[120:123], v[178:181], v[96:99]
	v_mfma_f32_16x16x32_bf16 v[32:35], v[170:173], v[178:181], v[32:35]
	v_mfma_f32_16x16x32_bf16 v[36:39], v[120:123], v[186:189], v[36:39]
	v_mfma_f32_16x16x32_bf16 v[40:43], v[170:173], v[186:189], v[40:43]
	v_mfma_f32_16x16x32_bf16 v[44:47], v[120:123], v[200:203], v[44:47]
	v_mfma_f32_16x16x32_bf16 v[48:51], v[170:173], v[200:203], v[48:51]
	v_mfma_f32_16x16x32_bf16 v[52:55], v[120:123], v[208:211], v[52:55]
	v_mfma_f32_16x16x32_bf16 v[56:59], v[170:173], v[208:211], v[56:59]
	v_mfma_f32_16x16x32_bf16 v[96:99], v[124:127], v[182:185], v[96:99]
	v_mfma_f32_16x16x32_bf16 v[32:35], v[174:177], v[182:185], v[32:35]
	v_mfma_f32_16x16x32_bf16 v[36:39], v[124:127], v[196:199], v[36:39]
	v_mfma_f32_16x16x32_bf16 v[40:43], v[174:177], v[196:199], v[40:43]
	v_mfma_f32_16x16x32_bf16 v[44:47], v[124:127], v[204:207], v[44:47]
	v_mfma_f32_16x16x32_bf16 v[48:51], v[174:177], v[204:207], v[48:51]
	v_mfma_f32_16x16x32_bf16 v[52:55], v[124:127], v[212:215], v[52:55]
	v_mfma_f32_16x16x32_bf16 v[56:59], v[174:177], v[212:215], v[56:59]
	s_barrier
; #define PG8_STAGE(bufoff, gbase, voff) do { _Pragma("unroll") for (int _i = 0; _i < 2; ++_i) \
;         __builtin_amdgcn_global_load_lds((const unsigned*)((const char*)(gbase) + (voff)[_i]), (PG8_LAS unsigned*)(lds + (bufoff) + ldsw + _i * 8192), 16, 0, 0); } while (0)
; #define PG8_LDA(dst, b, h) do { _Pragma("unroll") for (int m = 0; m < 4; ++m) _Pragma("unroll") for (int k = 0; k < 2; ++k) dst[m][k] = *(const PG8_LAS bf16x8*)(lds + PG8_SA(b, h) + aoff + m * 2048 + k * 1024); } while (0)
; #define PG8_LDB(dst, b, h) do { _Pragma("unroll") for (int n = 0; n < 2; ++n) _Pragma("unroll") for (int k = 0; k < 2; ++k) dst[n][k] = *(const PG8_LAS bf16x8*)(lds + PG8_SB(b, h) + boff + n * 2048 + k * 1024); } while (0)
; #define PG8_MMA(ai, bj, At, Bt) do { __builtin_amdgcn_s_setprio(1); _Pragma("unroll") for (int m = 0; m < 4; ++m) _Pragma("unroll") for (int n = 0; n < 2; ++n) _Pragma("unroll") for (int k = 0; k < 2; ++k) \
;         acc[ai][bj][m][n] = __builtin_amdgcn_mfma_f32_16x16x32_bf16(Bt[n][k], At[m][k], acc[ai][bj][m][n], 0, 0, 0); __builtin_amdgcn_s_setprio(0); } while (0)
; #define PG8_WAIT_V(n) asm volatile("s_waitcnt vmcnt(" #n ")" ::: "memory")
; #define PG8_WAIT_L(n) asm volatile("s_waitcnt lgkmcnt(" #n ")" ::: "memory")
; #define PG8_BAR __builtin_amdgcn_s_barrier()
; #define PG8_SCHED __builtin_amdgcn_sched_barrier(0)
; template <class Epi, class Sched, bool ALIGN_EPI = false, bool SP2 = false>
; __device__ __forceinline__ void gemm_phase(PG8_LAS unsigned char* lds, const Gemm g, const Sched& S, const Epi& E) {
;     ...
;             PG8_LDA(At, 0, 1); PG8_STAGE(PG8_SB(0, 0), b2, voffB); PG8_STAGE(PG8_SB(0, 1), b2 + hstepB, voffB); PG8_STAGE(PG8_SA(0, 0), a2, voffA);
;             PG8_WAIT_V(8); PG8_WAIT_L(0); PG8_BAR; PG8_MMA(1, 0, At, B0); PG8_MMA(1, 1, At, B1); PG8_BAR; PG8_SCHED;
;             PG8_LDB(B0, 1, 0); PG8_LDB(B1, 1, 1); PG8_SCHED; PG8_LDA(At, 1, 0); PG8_STAGE(PG8_SA(0, 1), a2 + hstepA, voffA);
;             PG8_WAIT_V(8); PG8_WAIT_L(0); PG8_BAR; PG8_MMA(0, 0, At, B0); PG8_MMA(0, 1, At, B1); PG8_BAR; PG8_SCHED;
;             PG8_LDA(At, 1, 1); PG8_STAGE(PG8_SB(1, 0), b3, voffB); PG8_STAGE(PG8_SB(1, 1), b3 + hstepB, voffB); PG8_STAGE(PG8_SA(1, 0), a3, voffA);
;             PG8_WAIT_V(8); PG8_WAIT_L(0); PG8_BAR; PG8_MMA(1, 0, At, B0); PG8_MMA(1, 1, At, B1); PG8_BAR; PG8_SCHED;
	s_add_i32 s63, s63, s8
	s_add_i32 s49, s63, 0x2000
	v_lshl_add_u64 v[190:191], v[190:191], 0, s[24:25]
	s_mov_b32 m0, s63
	s_add_u32 s64, s40, 0x10180
	ds_read_b128 v[178:181], v145 offset:49152
	ds_read_b128 v[182:185], v145 offset:50176
	ds_read_b128 v[186:189], v145 offset:51200
	ds_read_b128 v[196:199], v145 offset:52224
	ds_read_b128 v[200:203], v145 offset:53248
	ds_read_b128 v[204:207], v145 offset:54272
	ds_read_b128 v[208:211], v145 offset:55296
	ds_read_b128 v[212:215], v145 offset:56320
	global_load_lds_dwordx4 v[190:191], off
	v_lshl_add_u64 v[190:191], v[192:193], 0, s[24:25]
	s_mov_b32 m0, s49
	s_addc_u32 s65, s41, 0
	s_add_i32 s40, s66, s8
	global_load_lds_dwordx4 v[190:191], off
	s_mov_b32 m0, s40
	s_add_i32 s41, s40, 0x2000
	global_load_lds_dwordx4 v130, s[64:65]
	s_mov_b32 m0, s41
	s_nop 0
	global_load_lds_dwordx4 v134, s[64:65]
	v_lshl_add_u64 v[190:191], v[194:195], 0, s[24:25]
	s_mov_b32 m0, s43
	s_nop 0
	global_load_lds_dwordx4 v[190:191], off
	v_lshl_add_u64 v[190:191], v[216:217], 0, s[24:25]
	s_mov_b32 m0, s56
	s_nop 0
	global_load_lds_dwordx4 v[190:191], off
	s_waitcnt vmcnt(8)
	s_waitcnt lgkmcnt(0)
	s_barrier
	s_waitcnt lgkmcnt(0)
	v_mfma_f32_16x16x32_bf16 v[0:3], v[24:27], v[208:211], v[0:3]
	v_mfma_f32_16x16x32_bf16 v[4:7], v[112:115], v[208:211], v[4:7]
	v_mfma_f32_16x16x32_bf16 v[146:149], v[24:27], v[178:181], v[146:149]
	v_mfma_f32_16x16x32_bf16 v[150:153], v[112:115], v[178:181], v[150:153]
	v_mfma_f32_16x16x32_bf16 v[154:157], v[24:27], v[186:189], v[154:157]
	v_mfma_f32_16x16x32_bf16 v[158:161], v[112:115], v[186:189], v[158:161]
	v_mfma_f32_16x16x32_bf16 v[162:165], v[24:27], v[200:203], v[162:165]
	v_mfma_f32_16x16x32_bf16 v[166:169], v[112:115], v[200:203], v[166:169]
	v_mfma_f32_16x16x32_bf16 v[0:3], v[28:31], v[212:215], v[0:3]
	v_mfma_f32_16x16x32_bf16 v[4:7], v[116:119], v[212:215], v[4:7]
	v_mfma_f32_16x16x32_bf16 v[146:149], v[28:31], v[182:185], v[146:149]
	v_mfma_f32_16x16x32_bf16 v[150:153], v[116:119], v[182:185], v[150:153]
	v_mfma_f32_16x16x32_bf16 v[154:157], v[28:31], v[196:199], v[154:157]
	v_mfma_f32_16x16x32_bf16 v[158:161], v[116:119], v[196:199], v[158:161]
	v_mfma_f32_16x16x32_bf16 v[162:165], v[28:31], v[204:207], v[162:165]
	v_mfma_f32_16x16x32_bf16 v[166:169], v[116:119], v[204:207], v[166:169]
	v_mfma_f32_16x16x32_bf16 v[8:11], v[120:123], v[178:181], v[8:11]
	v_mfma_f32_16x16x32_bf16 v[12:15], v[170:173], v[178:181], v[12:15]
	v_mfma_f32_16x16x32_bf16 v[24:27], v[120:123], v[186:189], v[60:63]
	v_mfma_f32_16x16x32_bf16 v[28:31], v[170:173], v[186:189], v[100:103]
	v_mfma_f32_16x16x32_bf16 v[60:63], v[120:123], v[200:203], v[104:107]
	v_mfma_f32_16x16x32_bf16 v[100:103], v[170:173], v[200:203], v[108:111]
	v_mfma_f32_16x16x32_bf16 v[16:19], v[120:123], v[208:211], v[16:19]
	v_mfma_f32_16x16x32_bf16 v[20:23], v[170:173], v[208:211], v[20:23]
	v_mfma_f32_16x16x32_bf16 v[8:11], v[124:127], v[182:185], v[8:11]
	v_mfma_f32_16x16x32_bf16 v[12:15], v[174:177], v[182:185], v[12:15]
	v_mfma_f32_16x16x32_bf16 v[24:27], v[124:127], v[196:199], v[24:27]
	v_mfma_f32_16x16x32_bf16 v[28:31], v[174:177], v[196:199], v[28:31]
	v_mfma_f32_16x16x32_bf16 v[60:63], v[124:127], v[204:207], v[60:63]
	v_mfma_f32_16x16x32_bf16 v[100:103], v[174:177], v[204:207], v[100:103]
	v_mfma_f32_16x16x32_bf16 v[16:19], v[124:127], v[212:215], v[16:19]
	v_mfma_f32_16x16x32_bf16 v[20:23], v[174:177], v[212:215], v[20:23]
	s_barrier
	ds_read_b128 v[104:107], v143
	ds_read_b128 v[108:111], v143 offset:1024
	ds_read_b128 v[112:115], v143 offset:2048
	ds_read_b128 v[116:119], v143 offset:3072
	ds_read_b128 v[120:123], v144
	ds_read_b128 v[124:127], v144 offset:1024
	ds_read_b128 v[170:173], v144 offset:2048
	ds_read_b128 v[174:177], v144 offset:3072
	s_add_u32 s38, s38, 0x10180
	s_addc_u32 s39, s39, 0
	s_mov_b32 m0, s62
	ds_read_b128 v[178:181], v145
	ds_read_b128 v[182:185], v145 offset:1024
	ds_read_b128 v[186:189], v145 offset:2048
	ds_read_b128 v[196:199], v145 offset:3072
	ds_read_b128 v[200:203], v145 offset:4096
	ds_read_b128 v[204:207], v145 offset:5120
	ds_read_b128 v[208:211], v145 offset:6144
	ds_read_b128 v[212:215], v145 offset:7168
	global_load_lds_dwordx4 v128, s[38:39]
	s_mov_b32 m0, s29
	s_nop 0
	global_load_lds_dwordx4 v132, s[38:39]
	s_waitcnt vmcnt(8)
	s_waitcnt lgkmcnt(0)
	s_barrier
	s_waitcnt lgkmcnt(0)
	v_mfma_f32_16x16x32_bf16 v[64:67], v[104:107], v[178:181], v[64:67]
	v_mfma_f32_16x16x32_bf16 v[68:71], v[112:115], v[178:181], v[68:71]
	v_mfma_f32_16x16x32_bf16 v[72:75], v[104:107], v[186:189], v[72:75]
	v_mfma_f32_16x16x32_bf16 v[76:79], v[112:115], v[186:189], v[76:79]
	v_mfma_f32_16x16x32_bf16 v[80:83], v[104:107], v[200:203], v[80:83]
	v_mfma_f32_16x16x32_bf16 v[84:87], v[112:115], v[200:203], v[84:87]
	v_mfma_f32_16x16x32_bf16 v[88:91], v[104:107], v[208:211], v[88:91]
	v_mfma_f32_16x16x32_bf16 v[92:95], v[112:115], v[208:211], v[92:95]
	v_mfma_f32_16x16x32_bf16 v[64:67], v[108:111], v[182:185], v[64:67]
	v_mfma_f32_16x16x32_bf16 v[68:71], v[116:119], v[182:185], v[68:71]
	v_mfma_f32_16x16x32_bf16 v[72:75], v[108:111], v[196:199], v[72:75]
	v_mfma_f32_16x16x32_bf16 v[76:79], v[116:119], v[196:199], v[76:79]
	v_mfma_f32_16x16x32_bf16 v[80:83], v[108:111], v[204:207], v[80:83]
	v_mfma_f32_16x16x32_bf16 v[84:87], v[116:119], v[204:207], v[84:87]
	v_mfma_f32_16x16x32_bf16 v[88:91], v[108:111], v[212:215], v[88:91]
	v_mfma_f32_16x16x32_bf16 v[92:95], v[116:119], v[212:215], v[92:95]
	v_mfma_f32_16x16x32_bf16 v[32:35], v[170:173], v[178:181], v[32:35]
	v_mfma_f32_16x16x32_bf16 v[96:99], v[120:123], v[178:181], v[96:99]
	v_mfma_f32_16x16x32_bf16 v[178:181], v[174:177], v[182:185], v[32:35]
	v_mfma_f32_16x16x32_bf16 v[32:35], v[120:123], v[186:189], v[36:39]
	v_mfma_f32_16x16x32_bf16 v[216:219], v[124:127], v[182:185], v[96:99]
	v_mfma_f32_16x16x32_bf16 v[182:185], v[124:127], v[196:199], v[32:35]
	v_mfma_f32_16x16x32_bf16 v[32:35], v[170:173], v[186:189], v[40:43]
	v_mfma_f32_16x16x32_bf16 v[40:43], v[174:177], v[196:199], v[32:35]
	v_mfma_f32_16x16x32_bf16 v[32:35], v[120:123], v[200:203], v[44:47]
	v_mfma_f32_16x16x32_bf16 v[44:47], v[124:127], v[204:207], v[32:35]
	v_mfma_f32_16x16x32_bf16 v[32:35], v[170:173], v[200:203], v[48:51]
	v_mfma_f32_16x16x32_bf16 v[48:51], v[174:177], v[204:207], v[32:35]
	v_mfma_f32_16x16x32_bf16 v[32:35], v[120:123], v[208:211], v[52:55]
	v_mfma_f32_16x16x32_bf16 v[52:55], v[124:127], v[212:215], v[32:35]
	v_mfma_f32_16x16x32_bf16 v[32:35], v[170:173], v[208:211], v[56:59]
	v_mfma_f32_16x16x32_bf16 v[56:59], v[174:177], v[212:215], v[32:35]
	s_barrier
; #define PG8_STAGE(bufoff, gbase, voff) do { _Pragma("unroll") for (int _i = 0; _i < 2; ++_i) \
;         __builtin_amdgcn_global_load_lds((const unsigned*)((const char*)(gbase) + (voff)[_i]), (PG8_LAS unsigned*)(lds + (bufoff) + ldsw + _i * 8192), 16, 0, 0); } while (0)
; #define PG8_LDA(dst, b, h) do { _Pragma("unroll") for (int m = 0; m < 4; ++m) _Pragma("unroll") for (int k = 0; k < 2; ++k) dst[m][k] = *(const PG8_LAS bf16x8*)(lds + PG8_SA(b, h) + aoff + m * 2048 + k * 1024); } while (0)
; #define PG8_LDB(dst, b, h) do { _Pragma("unroll") for (int n = 0; n < 2; ++n) _Pragma("unroll") for (int k = 0; k < 2; ++k) dst[n][k] = *(const PG8_LAS bf16x8*)(lds + PG8_SB(b, h) + boff + n * 2048 + k * 1024); } while (0)
; #define PG8_MMA(ai, bj, At, Bt) do { __builtin_amdgcn_s_setprio(1); _Pragma("unroll") for (int m = 0; m < 4; ++m) _Pragma("unroll") for (int n = 0; n < 2; ++n) _Pragma("unroll") for (int k = 0; k < 2; ++k) \
;         acc[ai][bj][m][n] = __builtin_amdgcn_mfma_f32_16x16x32_bf16(Bt[n][k], At[m][k], acc[ai][bj][m][n], 0, 0, 0); __builtin_amdgcn_s_setprio(0); } while (0)
; #define PG8_WAIT_V(n) asm volatile("s_waitcnt vmcnt(" #n ")" ::: "memory")
; #define PG8_WAIT_L(n) asm volatile("s_waitcnt lgkmcnt(" #n ")" ::: "memory")
; #define PG8_BAR __builtin_amdgcn_s_barrier()
; #define PG8_SCHED __builtin_amdgcn_sched_barrier(0)
; template <class Epi, class Sched, bool ALIGN_EPI = false, bool SP2 = false>
; __device__ __forceinline__ void gemm_phase(PG8_LAS unsigned char* lds, const Gemm g, const Sched& S, const Epi& E) {
;     ...
;             PG8_LDA(At, 0, 1); PG8_STAGE(PG8_SB(0, 0), b2, voffB); PG8_STAGE(PG8_SB(0, 1), b2 + hstepB, voffB); PG8_STAGE(PG8_SA(0, 0), a2, voffA);
;             PG8_WAIT_V(8); PG8_WAIT_L(0); PG8_BAR; PG8_MMA(1, 0, At, B0); PG8_MMA(1, 1, At, B1); PG8_BAR; PG8_SCHED;
;             PG8_LDB(B0, 1, 0); PG8_LDB(B1, 1, 1); PG8_SCHED; PG8_LDA(At, 1, 0); PG8_STAGE(PG8_SA(0, 1), a2 + hstepA, voffA);
;             PG8_WAIT_V(8); PG8_WAIT_L(0); PG8_BAR; PG8_MMA(0, 0, At, B0); PG8_MMA(0, 1, At, B1); PG8_BAR; PG8_SCHED;
;             PG8_LDA(At, 1, 1); PG8_STAGE(PG8_SB(1, 0), b3, voffB); PG8_STAGE(PG8_SB(1, 1), b3 + hstepB, voffB); PG8_STAGE(PG8_SA(1, 0), a3, voffA);
;             PG8_WAIT_V(8); PG8_WAIT_L(0); PG8_BAR; PG8_MMA(1, 0, At, B0); PG8_MMA(1, 1, At, B1); PG8_BAR; PG8_SCHED;
	s_mov_b32 m0, s48
	v_lshl_add_u64 v[190:191], s[50:51], 0, v[130:131]
	s_add_u32 s38, s50, 0x10000
	s_nop 1
	ds_read_b128 v[32:35], v145 offset:16384
	ds_read_b128 v[36:39], v145 offset:17408
	ds_read_b128 v[96:99], v145 offset:18432
	ds_read_b128 v[186:189], v145 offset:19456
	ds_read_b128 v[196:199], v145 offset:20480
	ds_read_b128 v[200:203], v145 offset:21504
	ds_read_b128 v[204:207], v145 offset:22528
	ds_read_b128 v[208:211], v145 offset:23552
	global_load_lds_dwordx4 v[190:191], off
	v_lshl_add_u64 v[192:193], s[50:51], 0, v[134:135]
	s_mov_b32 m0, s31
	s_addc_u32 s39, s51, 0
	global_load_lds_dwordx4 v[192:193], off
	s_mov_b32 m0, s44
	v_lshl_add_u64 v[252:253], s[52:53], 0, v[132:133]
	global_load_lds_dwordx4 v130, s[38:39]
	s_mov_b32 m0, s45
	s_nop 0
	global_load_lds_dwordx4 v134, s[38:39]
	v_lshl_add_u64 v[194:195], s[52:53], 0, v[128:129]
	s_mov_b32 m0, s9
	s_nop 0
	global_load_lds_dwordx4 v[194:195], off
	s_mov_b32 m0, s10
	s_nop 0
	global_load_lds_dwordx4 v[252:253], off
	s_waitcnt vmcnt(8)
	s_waitcnt lgkmcnt(0)
	s_barrier
	s_waitcnt lgkmcnt(0)
	v_mfma_f32_16x16x32_bf16 v[0:3], v[104:107], v[204:207], v[0:3]
	v_mfma_f32_16x16x32_bf16 v[4:7], v[112:115], v[204:207], v[4:7]
	v_mfma_f32_16x16x32_bf16 v[146:149], v[104:107], v[32:35], v[146:149]
	v_mfma_f32_16x16x32_bf16 v[150:153], v[112:115], v[32:35], v[150:153]
	v_mfma_f32_16x16x32_bf16 v[154:157], v[104:107], v[96:99], v[154:157]
	v_mfma_f32_16x16x32_bf16 v[158:161], v[112:115], v[96:99], v[158:161]
	v_mfma_f32_16x16x32_bf16 v[162:165], v[104:107], v[196:199], v[162:165]
	v_mfma_f32_16x16x32_bf16 v[166:169], v[112:115], v[196:199], v[166:169]
	v_mfma_f32_16x16x32_bf16 v[0:3], v[108:111], v[208:211], v[0:3]
	v_mfma_f32_16x16x32_bf16 v[4:7], v[116:119], v[208:211], v[4:7]
	v_mfma_f32_16x16x32_bf16 v[146:149], v[108:111], v[36:39], v[146:149]
	v_mfma_f32_16x16x32_bf16 v[150:153], v[116:119], v[36:39], v[150:153]
	v_mfma_f32_16x16x32_bf16 v[154:157], v[108:111], v[186:189], v[154:157]
	v_mfma_f32_16x16x32_bf16 v[158:161], v[116:119], v[186:189], v[158:161]
	v_mfma_f32_16x16x32_bf16 v[162:165], v[108:111], v[200:203], v[162:165]
	v_mfma_f32_16x16x32_bf16 v[166:169], v[116:119], v[200:203], v[166:169]
	v_mfma_f32_16x16x32_bf16 v[8:11], v[120:123], v[32:35], v[8:11]
	v_mfma_f32_16x16x32_bf16 v[12:15], v[170:173], v[32:35], v[12:15]
	v_mfma_f32_16x16x32_bf16 v[24:27], v[120:123], v[96:99], v[24:27]
	v_mfma_f32_16x16x32_bf16 v[28:31], v[170:173], v[96:99], v[28:31]
	v_mfma_f32_16x16x32_bf16 v[32:35], v[120:123], v[196:199], v[60:63]
	v_mfma_f32_16x16x32_bf16 v[24:27], v[124:127], v[186:189], v[24:27]
	v_mfma_f32_16x16x32_bf16 v[28:31], v[174:177], v[186:189], v[28:31]
	v_mfma_f32_16x16x32_bf16 v[186:189], v[124:127], v[200:203], v[32:35]
	v_mfma_f32_16x16x32_bf16 v[32:35], v[170:173], v[196:199], v[100:103]
	v_mfma_f32_16x16x32_bf16 v[16:19], v[120:123], v[204:207], v[16:19]
	v_mfma_f32_16x16x32_bf16 v[8:11], v[124:127], v[36:39], v[8:11]
	v_mfma_f32_16x16x32_bf16 v[12:15], v[174:177], v[36:39], v[12:15]
	v_mfma_f32_16x16x32_bf16 v[196:199], v[174:177], v[200:203], v[32:35]
	v_mfma_f32_16x16x32_bf16 v[200:203], v[124:127], v[208:211], v[16:19]
	v_mfma_f32_16x16x32_bf16 v[16:19], v[170:173], v[204:207], v[20:23]
	v_mfma_f32_16x16x32_bf16 v[170:173], v[174:177], v[208:211], v[16:19]
	s_barrier
	ds_read_b128 v[60:63], v220
	ds_read_b128 v[174:177], v220 offset:1024
	ds_read_b128 v[204:207], v220 offset:2048
	ds_read_b128 v[208:211], v220 offset:3072
	ds_read_b128 v[212:215], v228
	ds_read_b128 v[220:223], v228 offset:1024
	ds_read_b128 v[224:227], v228 offset:2048
	ds_read_b128 v[228:231], v228 offset:3072
	s_add_u32 s38, s52, 0x10000
	s_addc_u32 s39, s53, 0
	s_mov_b32 m0, s11
	ds_read_b128 v[16:19], v145 offset:32768
	ds_read_b128 v[20:23], v145 offset:33792
	ds_read_b128 v[108:111], v145 offset:34816
	ds_read_b128 v[232:235], v145 offset:35840
	ds_read_b128 v[236:239], v145 offset:36864
	ds_read_b128 v[240:243], v145 offset:37888
	ds_read_b128 v[244:247], v145 offset:38912
	ds_read_b128 v[248:251], v145 offset:39936
	global_load_lds_dwordx4 v128, s[38:39]
	s_mov_b32 m0, s27
	s_nop 0
	global_load_lds_dwordx4 v132, s[38:39]
	s_waitcnt vmcnt(8)
	s_waitcnt lgkmcnt(0)
	s_barrier
; #define PG8_STAGE(bufoff, gbase, voff) do { _Pragma("unroll") for (int _i = 0; _i < 2; ++_i) \
;         __builtin_amdgcn_global_load_lds((const unsigned*)((const char*)(gbase) + (voff)[_i]), (PG8_LAS unsigned*)(lds + (bufoff) + ldsw + _i * 8192), 16, 0, 0); } while (0)
; #define PG8_LDA(dst, b, h) do { _Pragma("unroll") for (int m = 0; m < 4; ++m) _Pragma("unroll") for (int k = 0; k < 2; ++k) dst[m][k] = *(const PG8_LAS bf16x8*)(lds + PG8_SA(b, h) + aoff + m * 2048 + k * 1024); } while (0)
; #define PG8_LDB(dst, b, h) do { _Pragma("unroll") for (int n = 0; n < 2; ++n) _Pragma("unroll") for (int k = 0; k < 2; ++k) dst[n][k] = *(const PG8_LAS bf16x8*)(lds + PG8_SB(b, h) + boff + n * 2048 + k * 1024); } while (0)
; #define PG8_MMA(ai, bj, At, Bt) do { __builtin_amdgcn_s_setprio(1); _Pragma("unroll") for (int m = 0; m < 4; ++m) _Pragma("unroll") for (int n = 0; n < 2; ++n) _Pragma("unroll") for (int k = 0; k < 2; ++k) \
;         acc[ai][bj][m][n] = __builtin_amdgcn_mfma_f32_16x16x32_bf16(Bt[n][k], At[m][k], acc[ai][bj][m][n], 0, 0, 0); __builtin_amdgcn_s_setprio(0); } while (0)
; template <class Epi, class Sched, bool ALIGN_EPI = false, bool SP2 = false>
; __device__ __forceinline__ void gemm_phase(PG8_LAS unsigned char* lds, const Gemm g, const Sched& S, const Epi& E) {
;     ...
;             PG8_LDB(B0, 0, 0); PG8_LDB(B1, 0, 1); PG8_SCHED; PG8_LDA(At, 0, 0); PG8_STAGE(PG8_SA(1, 1), a1 + hstepA, voffA);
;             PG8_WAIT_V(8); PG8_WAIT_L(0); PG8_BAR; PG8_MMA(0, 0, At, B0); PG8_MMA(0, 1, At, B1); PG8_BAR; PG8_SCHED;
;             PG8_LDA(At, 0, 1); PG8_STAGE(PG8_SB(0, 0), b2, voffB); PG8_STAGE(PG8_SB(0, 1), b2 + hstepB, voffB); PG8_STAGE(PG8_SA(0, 0), a2, voffA);
;             PG8_WAIT_V(8); PG8_WAIT_L(0); PG8_BAR; PG8_MMA(1, 0, At, B0); PG8_MMA(1, 1, At, B1); PG8_BAR; PG8_SCHED;
;             PG8_LDB(B0, 1, 0); PG8_LDB(B1, 1, 1); PG8_SCHED; PG8_LDA(At, 1, 0); PG8_STAGE(PG8_SA(0, 1), a2 + hstepA, voffA);
;             PG8_WAIT_V(8); PG8_WAIT_L(0); PG8_BAR; PG8_MMA(0, 0, At, B0); PG8_MMA(0, 1, At, B1); PG8_BAR; PG8_SCHED;
;             PG8_LDA(At, 1, 1); PG8_STAGE(PG8_SB(1, 0), b3, voffB); PG8_STAGE(PG8_SB(1, 1), b3 + hstepB, voffB); PG8_STAGE(PG8_SA(1, 0), a3, voffA);
;             PG8_WAIT_V(8); PG8_WAIT_L(0); PG8_BAR; PG8_MMA(1, 0, At, B0); PG8_MMA(1, 1, At, B1); PG8_BAR; PG8_SCHED;
;     ...
;         if constexpr (ALIGN_EPI) { if (wr == 0) PG8_BAR; }
	s_waitcnt lgkmcnt(0)
	v_mfma_f32_16x16x32_bf16 v[32:35], v[60:63], v[16:19], v[64:67]
	v_mfma_f32_16x16x32_bf16 v[112:115], v[174:177], v[20:23], v[32:35]
	v_mfma_f32_16x16x32_bf16 v[32:35], v[204:207], v[16:19], v[68:71]
	v_mfma_f32_16x16x32_bf16 v[116:119], v[208:211], v[20:23], v[32:35]
	v_mfma_f32_16x16x32_bf16 v[32:35], v[60:63], v[108:111], v[72:75]
	v_mfma_f32_16x16x32_bf16 v[96:99], v[174:177], v[232:235], v[32:35]
	v_mfma_f32_16x16x32_bf16 v[32:35], v[204:207], v[108:111], v[76:79]
	v_mfma_f32_16x16x32_bf16 v[100:103], v[208:211], v[232:235], v[32:35]
	v_mfma_f32_16x16x32_bf16 v[32:35], v[60:63], v[236:239], v[80:83]
	v_mfma_f32_16x16x32_bf16 v[64:67], v[174:177], v[240:243], v[32:35]
	v_mfma_f32_16x16x32_bf16 v[32:35], v[204:207], v[236:239], v[84:87]
	v_mfma_f32_16x16x32_bf16 v[68:71], v[208:211], v[240:243], v[32:35]
	v_mfma_f32_16x16x32_bf16 v[32:35], v[60:63], v[244:247], v[88:91]
	v_mfma_f32_16x16x32_bf16 v[36:39], v[204:207], v[244:247], v[92:95]
	v_mfma_f32_16x16x32_bf16 v[32:35], v[174:177], v[248:251], v[32:35]
	v_mfma_f32_16x16x32_bf16 v[36:39], v[208:211], v[248:251], v[36:39]
	v_mfma_f32_16x16x32_bf16 v[72:75], v[212:215], v[16:19], v[216:219]
	v_mfma_f32_16x16x32_bf16 v[16:19], v[224:227], v[16:19], v[178:181]
	v_mfma_f32_16x16x32_bf16 v[124:127], v[228:231], v[20:23], v[16:19]
	v_mfma_f32_16x16x32_bf16 v[16:19], v[212:215], v[108:111], v[182:185]
	v_mfma_f32_16x16x32_bf16 v[104:107], v[220:223], v[232:235], v[16:19]
	v_mfma_f32_16x16x32_bf16 v[16:19], v[224:227], v[108:111], v[40:43]
	v_mfma_f32_16x16x32_bf16 v[108:111], v[228:231], v[232:235], v[16:19]
	v_mfma_f32_16x16x32_bf16 v[16:19], v[212:215], v[236:239], v[44:47]
	v_mfma_f32_16x16x32_bf16 v[120:123], v[220:223], v[20:23], v[72:75]
	v_mfma_f32_16x16x32_bf16 v[72:75], v[220:223], v[240:243], v[16:19]
	v_mfma_f32_16x16x32_bf16 v[16:19], v[224:227], v[236:239], v[48:51]
	v_mfma_f32_16x16x32_bf16 v[76:79], v[228:231], v[240:243], v[16:19]
	v_mfma_f32_16x16x32_bf16 v[16:19], v[212:215], v[244:247], v[52:55]
	v_mfma_f32_16x16x32_bf16 v[40:43], v[220:223], v[248:251], v[16:19]
	v_mfma_f32_16x16x32_bf16 v[16:19], v[224:227], v[244:247], v[56:59]
	v_mfma_f32_16x16x32_bf16 v[44:47], v[228:231], v[248:251], v[16:19]
	s_barrier
	s_mov_b32 m0, s63
	s_nop 3
	v_lshl_add_u64 v[16:17], v[190:191], 0, s[16:17]
	s_add_u32 s38, s50, 0x10080
	ds_read_b128 v[56:59], v145 offset:49152
	ds_read_b128 v[92:95], v145 offset:50176
	ds_read_b128 v[178:181], v145 offset:51200
	ds_read_b128 v[182:185], v145 offset:52224
	ds_read_b128 v[216:219], v145 offset:53248
	ds_read_b128 v[232:235], v145 offset:54272
	ds_read_b128 v[236:239], v145 offset:55296
	ds_read_b128 v[240:243], v145 offset:56320
	global_load_lds_dwordx4 v[16:17], off
	v_lshl_add_u64 v[16:17], v[192:193], 0, s[16:17]
	s_mov_b32 m0, s49
	s_addc_u32 s39, s51, 0
	global_load_lds_dwordx4 v[16:17], off
	s_mov_b32 m0, s40
	s_nop 0
	global_load_lds_dwordx4 v130, s[38:39]
	s_mov_b32 m0, s41
	s_nop 0
	global_load_lds_dwordx4 v134, s[38:39]
	v_lshl_add_u64 v[16:17], v[194:195], 0, s[16:17]
	s_mov_b32 m0, s43
	s_nop 0
	global_load_lds_dwordx4 v[16:17], off
	v_lshl_add_u64 v[16:17], v[252:253], 0, s[16:17]
	s_mov_b32 m0, s56
	s_nop 0
	global_load_lds_dwordx4 v[16:17], off
	s_waitcnt vmcnt(8)
	s_waitcnt lgkmcnt(0)
	s_barrier
	s_waitcnt lgkmcnt(0)
	v_mfma_f32_16x16x32_bf16 v[16:19], v[60:63], v[56:59], v[146:149]
	v_mfma_f32_16x16x32_bf16 v[80:83], v[174:177], v[92:95], v[16:19]
	v_mfma_f32_16x16x32_bf16 v[16:19], v[204:207], v[56:59], v[150:153]
	v_mfma_f32_16x16x32_bf16 v[84:87], v[208:211], v[92:95], v[16:19]
	v_mfma_f32_16x16x32_bf16 v[16:19], v[60:63], v[178:181], v[154:157]
	v_mfma_f32_16x16x32_bf16 v[48:51], v[174:177], v[182:185], v[16:19]
	v_mfma_f32_16x16x32_bf16 v[16:19], v[204:207], v[178:181], v[158:161]
	v_mfma_f32_16x16x32_bf16 v[52:55], v[208:211], v[182:185], v[16:19]
	v_mfma_f32_16x16x32_bf16 v[16:19], v[60:63], v[216:219], v[162:165]
	v_mfma_f32_16x16x32_bf16 v[20:23], v[204:207], v[216:219], v[166:169]
	v_mfma_f32_16x16x32_bf16 v[0:3], v[60:63], v[236:239], v[0:3]
	v_mfma_f32_16x16x32_bf16 v[4:7], v[204:207], v[236:239], v[4:7]
	v_mfma_f32_16x16x32_bf16 v[16:19], v[174:177], v[232:235], v[16:19]
	v_mfma_f32_16x16x32_bf16 v[20:23], v[208:211], v[232:235], v[20:23]
	v_mfma_f32_16x16x32_bf16 v[0:3], v[174:177], v[240:243], v[0:3]
	v_mfma_f32_16x16x32_bf16 v[4:7], v[208:211], v[240:243], v[4:7]
	v_mfma_f32_16x16x32_bf16 v[8:11], v[212:215], v[56:59], v[8:11]
	v_mfma_f32_16x16x32_bf16 v[88:91], v[220:223], v[92:95], v[8:11]
	v_mfma_f32_16x16x32_bf16 v[8:11], v[224:227], v[56:59], v[12:15]
	v_mfma_f32_16x16x32_bf16 v[92:95], v[228:231], v[92:95], v[8:11]
	v_mfma_f32_16x16x32_bf16 v[8:11], v[212:215], v[178:181], v[24:27]
	v_mfma_f32_16x16x32_bf16 v[56:59], v[220:223], v[182:185], v[8:11]
	v_mfma_f32_16x16x32_bf16 v[8:11], v[224:227], v[178:181], v[28:31]
	v_mfma_f32_16x16x32_bf16 v[60:63], v[228:231], v[182:185], v[8:11]
	v_mfma_f32_16x16x32_bf16 v[8:11], v[212:215], v[216:219], v[186:189]
	v_mfma_f32_16x16x32_bf16 v[24:27], v[220:223], v[232:235], v[8:11]
	v_mfma_f32_16x16x32_bf16 v[8:11], v[224:227], v[216:219], v[196:199]
	v_mfma_f32_16x16x32_bf16 v[28:31], v[228:231], v[232:235], v[8:11]
	v_mfma_f32_16x16x32_bf16 v[8:11], v[212:215], v[236:239], v[200:203]
	v_mfma_f32_16x16x32_bf16 v[12:15], v[224:227], v[236:239], v[170:173]
	v_mfma_f32_16x16x32_bf16 v[8:11], v[220:223], v[240:243], v[8:11]
	v_mfma_f32_16x16x32_bf16 v[12:15], v[228:231], v[240:243], v[12:15]
	s_barrier
	s_andn2_b64 vcc, exec, s[18:19]
	s_cbranch_vccnz .LBB0_236
	s_barrier

; #define PG8_STAGE(bufoff, gbase, voff) do { _Pragma("unroll") for (int _i = 0; _i < 2; ++_i) \
;         __builtin_amdgcn_global_load_lds((const unsigned*)((const char*)(gbase) + (voff)[_i]), (PG8_LAS unsigned*)(lds + (bufoff) + ldsw + _i * 8192), 16, 0, 0); } while (0)
; #define PG8_LDA(dst, b, h) do { _Pragma("unroll") for (int m = 0; m < 4; ++m) _Pragma("unroll") for (int k = 0; k < 2; ++k) dst[m][k] = *(const PG8_LAS bf16x8*)(lds + PG8_SA(b, h) + aoff + m * 2048 + k * 1024); } while (0)
; #define PG8_LDB(dst, b, h) do { _Pragma("unroll") for (int n = 0; n < 2; ++n) _Pragma("unroll") for (int k = 0; k < 2; ++k) dst[n][k] = *(const PG8_LAS bf16x8*)(lds + PG8_SB(b, h) + boff + n * 2048 + k * 1024); } while (0)
; #define PG8_WAIT_V(n) asm volatile("s_waitcnt vmcnt(" #n ")" ::: "memory")
; #define PG8_WAIT_L(n) asm volatile("s_waitcnt lgkmcnt(" #n ")" ::: "memory")
; #define PG8_BAR __builtin_amdgcn_s_barrier()
; #define PG8_SCHED __builtin_amdgcn_sched_barrier(0)
; template <class Epi, class Sched, bool ALIGN_EPI = false, bool SP2 = false>
; __device__ __forceinline__ void gemm_phase(PG8_LAS unsigned char* lds, const Gemm g, const Sched& S, const Epi& E) {
;     ...
;         for (int t = 0; t < nt; t += 2) {
;             const bool last = (t == nt - 2);
;             const char* a1 = cA + (size_t)(t + 1) * kstep;
;             const char* a2 = last ? nA : cA + (size_t)(t + 2) * kstep; const char* b2 = last ? nB : cB + (size_t)(t + 2) * kstep;
;             const char* a3 = a2 + kstep; const char* b3 = b2 + kstep;
;             if (last && has_next) S.a_ready(nxt);
;             if constexpr (SP2) {
;             PG8_LDB(B0, 0, 0); PG8_LDB(B1, 0, 1); PG8_SCHED; PG8_LDA(At, 0, 0); PG8_STAGE(PG8_SA(1, 1), a1 + hstepA, voffA);
;             PG8_WAIT_V(8); PG8_WAIT_L(0); PG8_BAR; PG8_MMA(0, 0, At, B0); PG8_MMA(0, 1, At, B1); PG8_BAR; PG8_SCHED;
;             PG8_LDA(At, 0, 1); PG8_STAGE(PG8_SB(0, 0), b2, voffB); PG8_STAGE(PG8_SB(0, 1), b2 + hstepB, voffB); PG8_STAGE(PG8_SA(0, 0), a2, voffA);
;             PG8_WAIT_V(8); PG8_WAIT_L(0); PG8_BAR; PG8_MMA(1, 0, At, B0); PG8_MMA(1, 1, At, B1); PG8_BAR; PG8_SCHED;
;             PG8_LDB(B0, 1, 0); PG8_LDB(B1, 1, 1); PG8_SCHED; PG8_LDA(At, 1, 0); PG8_STAGE(PG8_SA(0, 1), a2 + hstepA, voffA);
;             PG8_WAIT_V(8); PG8_WAIT_L(0); PG8_BAR; PG8_MMA(0, 0, At, B0); PG8_MMA(0, 1, At, B1); PG8_BAR; PG8_SCHED;
.LBB0_303:
	ds_read_b128 v[150:153], v147
	ds_read_b128 v[154:157], v147 offset:1024
	ds_read_b128 v[158:161], v147 offset:2048
	ds_read_b128 v[162:165], v147 offset:3072
	ds_read_b128 v[166:169], v148
	ds_read_b128 v[170:173], v148 offset:1024
	ds_read_b128 v[174:177], v148 offset:2048
	ds_read_b128 v[178:181], v148 offset:3072
	s_add_u32 s28, s0, 0xfff80080
	s_addc_u32 s29, s1, -1
	s_cmp_eq_u32 s53, 2
	s_cselect_b32 s31, s23, s29
	s_cselect_b32 s30, s50, s28
	s_cselect_b32 s29, s25, s52
	s_cselect_b32 s28, s24, s51
	s_add_i32 m0, s8, 0xc000
	ds_read_b128 v[182:185], v149
	ds_read_b128 v[186:189], v149 offset:1024
	ds_read_b128 v[196:199], v149 offset:2048
	ds_read_b128 v[200:203], v149 offset:3072
	ds_read_b128 v[204:207], v149 offset:4096
	ds_read_b128 v[208:211], v149 offset:5120
	ds_read_b128 v[212:215], v149 offset:6144
	ds_read_b128 v[216:219], v149 offset:7168
	global_load_lds_dwordx4 v136, s[0:1]
	s_add_i32 m0, s8, 0xe000
	s_nop 0
	global_load_lds_dwordx4 v138, s[0:1]
	s_waitcnt vmcnt(8)
	s_waitcnt lgkmcnt(0)
	s_barrier
	s_waitcnt lgkmcnt(0)
	v_mfma_f32_16x16x32_bf16 v[124:127], v[150:153], v[182:185], v[124:127]
	v_mfma_f32_16x16x32_bf16 v[120:123], v[158:161], v[182:185], v[120:123]
	v_mfma_f32_16x16x32_bf16 v[116:119], v[150:153], v[196:199], v[116:119]
	v_mfma_f32_16x16x32_bf16 v[112:115], v[158:161], v[196:199], v[112:115]
	v_mfma_f32_16x16x32_bf16 v[100:103], v[150:153], v[204:207], v[100:103]
	v_mfma_f32_16x16x32_bf16 v[96:99], v[158:161], v[204:207], v[96:99]
	v_mfma_f32_16x16x32_bf16 v[84:87], v[150:153], v[212:215], v[84:87]
	v_mfma_f32_16x16x32_bf16 v[80:83], v[158:161], v[212:215], v[80:83]
	v_mfma_f32_16x16x32_bf16 v[124:127], v[154:157], v[186:189], v[124:127]
	v_mfma_f32_16x16x32_bf16 v[120:123], v[162:165], v[186:189], v[120:123]
	v_mfma_f32_16x16x32_bf16 v[116:119], v[154:157], v[200:203], v[116:119]
	v_mfma_f32_16x16x32_bf16 v[112:115], v[162:165], v[200:203], v[112:115]
	v_mfma_f32_16x16x32_bf16 v[100:103], v[154:157], v[208:211], v[100:103]
	v_mfma_f32_16x16x32_bf16 v[96:99], v[162:165], v[208:211], v[96:99]
	v_mfma_f32_16x16x32_bf16 v[84:87], v[154:157], v[216:219], v[84:87]
	v_mfma_f32_16x16x32_bf16 v[80:83], v[162:165], v[216:219], v[80:83]
	v_mfma_f32_16x16x32_bf16 v[108:111], v[166:169], v[182:185], v[108:111]
	v_mfma_f32_16x16x32_bf16 v[104:107], v[174:177], v[182:185], v[104:107]
	v_mfma_f32_16x16x32_bf16 v[92:95], v[166:169], v[196:199], v[92:95]
	v_mfma_f32_16x16x32_bf16 v[88:91], v[174:177], v[196:199], v[88:91]
	v_mfma_f32_16x16x32_bf16 v[76:79], v[166:169], v[204:207], v[76:79]
	v_mfma_f32_16x16x32_bf16 v[72:75], v[174:177], v[204:207], v[72:75]
	v_mfma_f32_16x16x32_bf16 v[68:71], v[166:169], v[212:215], v[68:71]
	v_mfma_f32_16x16x32_bf16 v[64:67], v[174:177], v[212:215], v[64:67]
	v_mfma_f32_16x16x32_bf16 v[108:111], v[170:173], v[186:189], v[108:111]
	v_mfma_f32_16x16x32_bf16 v[104:107], v[178:181], v[186:189], v[104:107]
	v_mfma_f32_16x16x32_bf16 v[92:95], v[170:173], v[200:203], v[92:95]
	v_mfma_f32_16x16x32_bf16 v[88:91], v[178:181], v[200:203], v[88:91]
	v_mfma_f32_16x16x32_bf16 v[76:79], v[170:173], v[208:211], v[76:79]
	v_mfma_f32_16x16x32_bf16 v[72:75], v[178:181], v[208:211], v[72:75]
	v_mfma_f32_16x16x32_bf16 v[68:71], v[170:173], v[216:219], v[68:71]
	v_mfma_f32_16x16x32_bf16 v[64:67], v[178:181], v[216:219], v[64:67]
	s_barrier
	s_add_i32 s44, s39, s2
	v_lshl_add_u64 v[190:191], s[28:29], 0, v[132:133]
	s_mov_b32 m0, s44
	ds_read_b128 v[182:185], v149 offset:16384
	ds_read_b128 v[186:189], v149 offset:17408
	ds_read_b128 v[196:199], v149 offset:18432
	ds_read_b128 v[200:203], v149 offset:19456
	ds_read_b128 v[204:207], v149 offset:20480
	ds_read_b128 v[208:211], v149 offset:21504
	ds_read_b128 v[212:215], v149 offset:22528
	ds_read_b128 v[216:219], v149 offset:23552
	global_load_lds_dwordx4 v[190:191], off
	s_add_i32 m0, s44, 0x2000
	s_add_u32 s44, s28, 0x18000
	v_lshl_add_u64 v[192:193], s[28:29], 0, v[128:129]
	s_addc_u32 s45, s29, 0
	s_add_i32 s48, s40, s2
	global_load_lds_dwordx4 v[192:193], off
	s_mov_b32 m0, s48
	v_lshl_add_u64 v[220:221], s[30:31], 0, v[130:131]
	global_load_lds_dwordx4 v132, s[44:45]
	s_add_i32 m0, s48, 0x2000
	s_nop 0
	global_load_lds_dwordx4 v128, s[44:45]
	v_lshl_add_u64 v[194:195], s[30:31], 0, v[134:135]
	s_mov_b32 m0, s8
	s_nop 0
	global_load_lds_dwordx4 v[194:195], off
	s_mov_b32 m0, s9
	s_nop 0
	global_load_lds_dwordx4 v[220:221], off
	s_waitcnt vmcnt(8)
	s_waitcnt lgkmcnt(0)
	s_barrier
	s_waitcnt lgkmcnt(0)
	v_mfma_f32_16x16x32_bf16 v[60:63], v[150:153], v[182:185], v[60:63]
	v_mfma_f32_16x16x32_bf16 v[56:59], v[158:161], v[182:185], v[56:59]
	v_mfma_f32_16x16x32_bf16 v[52:55], v[150:153], v[196:199], v[52:55]
	v_mfma_f32_16x16x32_bf16 v[48:51], v[158:161], v[196:199], v[48:51]
	v_mfma_f32_16x16x32_bf16 v[36:39], v[150:153], v[204:207], v[36:39]
	v_mfma_f32_16x16x32_bf16 v[32:35], v[158:161], v[204:207], v[32:35]
	v_mfma_f32_16x16x32_bf16 v[20:23], v[150:153], v[212:215], v[20:23]
	v_mfma_f32_16x16x32_bf16 v[16:19], v[158:161], v[212:215], v[16:19]
	v_mfma_f32_16x16x32_bf16 v[60:63], v[154:157], v[186:189], v[60:63]
	v_mfma_f32_16x16x32_bf16 v[56:59], v[162:165], v[186:189], v[56:59]
	v_mfma_f32_16x16x32_bf16 v[52:55], v[154:157], v[200:203], v[52:55]
	v_mfma_f32_16x16x32_bf16 v[48:51], v[162:165], v[200:203], v[48:51]
	v_mfma_f32_16x16x32_bf16 v[36:39], v[154:157], v[208:211], v[36:39]
	v_mfma_f32_16x16x32_bf16 v[32:35], v[162:165], v[208:211], v[32:35]
	v_mfma_f32_16x16x32_bf16 v[20:23], v[154:157], v[216:219], v[20:23]
	v_mfma_f32_16x16x32_bf16 v[16:19], v[162:165], v[216:219], v[16:19]
	v_mfma_f32_16x16x32_bf16 v[44:47], v[166:169], v[182:185], v[44:47]
	v_mfma_f32_16x16x32_bf16 v[40:43], v[174:177], v[182:185], v[40:43]
	v_mfma_f32_16x16x32_bf16 v[28:31], v[166:169], v[196:199], v[28:31]
	v_mfma_f32_16x16x32_bf16 v[24:27], v[174:177], v[196:199], v[24:27]
	v_mfma_f32_16x16x32_bf16 v[12:15], v[166:169], v[204:207], v[12:15]
	v_mfma_f32_16x16x32_bf16 v[8:11], v[174:177], v[204:207], v[8:11]
	v_mfma_f32_16x16x32_bf16 v[4:7], v[166:169], v[212:215], v[4:7]
	v_mfma_f32_16x16x32_bf16 v[0:3], v[174:177], v[212:215], v[0:3]
	v_mfma_f32_16x16x32_bf16 v[44:47], v[170:173], v[186:189], v[44:47]
	v_mfma_f32_16x16x32_bf16 v[40:43], v[178:181], v[186:189], v[40:43]
	v_mfma_f32_16x16x32_bf16 v[28:31], v[170:173], v[200:203], v[28:31]
	v_mfma_f32_16x16x32_bf16 v[24:27], v[178:181], v[200:203], v[24:27]
	v_mfma_f32_16x16x32_bf16 v[12:15], v[170:173], v[208:211], v[12:15]
	v_mfma_f32_16x16x32_bf16 v[8:11], v[178:181], v[208:211], v[8:11]
	v_mfma_f32_16x16x32_bf16 v[4:7], v[170:173], v[216:219], v[4:7]
	v_mfma_f32_16x16x32_bf16 v[0:3], v[178:181], v[216:219], v[0:3]
	s_barrier
; #define PG8_STAGE(bufoff, gbase, voff) do { _Pragma("unroll") for (int _i = 0; _i < 2; ++_i) \
;         __builtin_amdgcn_global_load_lds((const unsigned*)((const char*)(gbase) + (voff)[_i]), (PG8_LAS unsigned*)(lds + (bufoff) + ldsw + _i * 8192), 16, 0, 0); } while (0)
; #define PG8_LDA(dst, b, h) do { _Pragma("unroll") for (int m = 0; m < 4; ++m) _Pragma("unroll") for (int k = 0; k < 2; ++k) dst[m][k] = *(const PG8_LAS bf16x8*)(lds + PG8_SA(b, h) + aoff + m * 2048 + k * 1024); } while (0)
; #define PG8_LDB(dst, b, h) do { _Pragma("unroll") for (int n = 0; n < 2; ++n) _Pragma("unroll") for (int k = 0; k < 2; ++k) dst[n][k] = *(const PG8_LAS bf16x8*)(lds + PG8_SB(b, h) + boff + n * 2048 + k * 1024); } while (0)
; #define PG8_MMA(ai, bj, At, Bt) do { __builtin_amdgcn_s_setprio(1); _Pragma("unroll") for (int m = 0; m < 4; ++m) _Pragma("unroll") for (int n = 0; n < 2; ++n) _Pragma("unroll") for (int k = 0; k < 2; ++k) \
;         acc[ai][bj][m][n] = __builtin_amdgcn_mfma_f32_16x16x32_bf16(Bt[n][k], At[m][k], acc[ai][bj][m][n], 0, 0, 0); __builtin_amdgcn_s_setprio(0); } while (0)
; #define PG8_WAIT_V(n) asm volatile("s_waitcnt vmcnt(" #n ")" ::: "memory")
; #define PG8_WAIT_L(n) asm volatile("s_waitcnt lgkmcnt(" #n ")" ::: "memory")
; #define PG8_BAR __builtin_amdgcn_s_barrier()
; #define PG8_SCHED __builtin_amdgcn_sched_barrier(0)
; template <class Epi, class Sched, bool ALIGN_EPI = false, bool SP2 = false>
; __device__ __forceinline__ void gemm_phase(PG8_LAS unsigned char* lds, const Gemm g, const Sched& S, const Epi& E) {
;     ...
;             PG8_LDB(B0, 1, 0); PG8_LDB(B1, 1, 1); PG8_SCHED; PG8_LDA(At, 1, 0); PG8_STAGE(PG8_SA(0, 1), a2 + hstepA, voffA);
;             PG8_WAIT_V(8); PG8_WAIT_L(0); PG8_BAR; PG8_MMA(0, 0, At, B0); PG8_MMA(0, 1, At, B1); PG8_BAR; PG8_SCHED;
;             PG8_LDA(At, 1, 1); PG8_STAGE(PG8_SB(1, 0), b3, voffB); PG8_STAGE(PG8_SB(1, 1), b3 + hstepB, voffB); PG8_STAGE(PG8_SA(1, 0), a3, voffA);
;             PG8_WAIT_V(8); PG8_WAIT_L(0); PG8_BAR; PG8_MMA(1, 0, At, B0); PG8_MMA(1, 1, At, B1); PG8_BAR; PG8_SCHED;
	s_add_i32 s44, 0, 0x18000
	s_add_i32 s45, 0, 0x1c000
	v_add_u32_e32 v162, s44, v146
	v_add_u32_e32 v178, s45, v146
	ds_read_b128 v[150:153], v162
	ds_read_b128 v[154:157], v162 offset:1024
	ds_read_b128 v[158:161], v162 offset:2048
	ds_read_b128 v[162:165], v162 offset:3072
	ds_read_b128 v[166:169], v178
	ds_read_b128 v[170:173], v178 offset:1024
	ds_read_b128 v[174:177], v178 offset:2048
	ds_read_b128 v[178:181], v178 offset:3072
	s_add_u32 s30, s30, 0x80000
	s_addc_u32 s31, s31, 0
	s_mov_b32 m0, s10
	ds_read_b128 v[182:185], v149 offset:32768
	ds_read_b128 v[186:189], v149 offset:33792
	ds_read_b128 v[196:199], v149 offset:34816
	ds_read_b128 v[200:203], v149 offset:35840
	ds_read_b128 v[204:207], v149 offset:36864
	ds_read_b128 v[208:211], v149 offset:37888
	ds_read_b128 v[212:215], v149 offset:38912
	ds_read_b128 v[216:219], v149 offset:39936
	global_load_lds_dwordx4 v134, s[30:31]
	s_mov_b32 m0, s11
	s_nop 0
	global_load_lds_dwordx4 v130, s[30:31]
	s_waitcnt vmcnt(8)
	s_waitcnt lgkmcnt(0)
	s_barrier
	s_waitcnt lgkmcnt(0)
	v_mfma_f32_16x16x32_bf16 v[124:127], v[150:153], v[182:185], v[124:127]
	v_mfma_f32_16x16x32_bf16 v[120:123], v[158:161], v[182:185], v[120:123]
	v_mfma_f32_16x16x32_bf16 v[116:119], v[150:153], v[196:199], v[116:119]
	v_mfma_f32_16x16x32_bf16 v[112:115], v[158:161], v[196:199], v[112:115]
	v_mfma_f32_16x16x32_bf16 v[100:103], v[150:153], v[204:207], v[100:103]
	v_mfma_f32_16x16x32_bf16 v[96:99], v[158:161], v[204:207], v[96:99]
	v_mfma_f32_16x16x32_bf16 v[84:87], v[150:153], v[212:215], v[84:87]
	v_mfma_f32_16x16x32_bf16 v[80:83], v[158:161], v[212:215], v[80:83]
	v_mfma_f32_16x16x32_bf16 v[124:127], v[154:157], v[186:189], v[124:127]
	v_mfma_f32_16x16x32_bf16 v[120:123], v[162:165], v[186:189], v[120:123]
	v_mfma_f32_16x16x32_bf16 v[116:119], v[154:157], v[200:203], v[116:119]
	v_mfma_f32_16x16x32_bf16 v[112:115], v[162:165], v[200:203], v[112:115]
	v_mfma_f32_16x16x32_bf16 v[100:103], v[154:157], v[208:211], v[100:103]
	v_mfma_f32_16x16x32_bf16 v[96:99], v[162:165], v[208:211], v[96:99]
	v_mfma_f32_16x16x32_bf16 v[84:87], v[154:157], v[216:219], v[84:87]
	v_mfma_f32_16x16x32_bf16 v[80:83], v[162:165], v[216:219], v[80:83]
	v_mfma_f32_16x16x32_bf16 v[108:111], v[166:169], v[182:185], v[108:111]
	v_mfma_f32_16x16x32_bf16 v[104:107], v[174:177], v[182:185], v[104:107]
	v_mfma_f32_16x16x32_bf16 v[92:95], v[166:169], v[196:199], v[92:95]
	v_mfma_f32_16x16x32_bf16 v[88:91], v[174:177], v[196:199], v[88:91]
	v_mfma_f32_16x16x32_bf16 v[76:79], v[166:169], v[204:207], v[76:79]
	v_mfma_f32_16x16x32_bf16 v[72:75], v[174:177], v[204:207], v[72:75]
	v_mfma_f32_16x16x32_bf16 v[68:71], v[166:169], v[212:215], v[68:71]
	v_mfma_f32_16x16x32_bf16 v[64:67], v[174:177], v[212:215], v[64:67]
	v_mfma_f32_16x16x32_bf16 v[108:111], v[170:173], v[186:189], v[108:111]
	v_mfma_f32_16x16x32_bf16 v[104:107], v[178:181], v[186:189], v[104:107]
	v_mfma_f32_16x16x32_bf16 v[92:95], v[170:173], v[200:203], v[92:95]
	v_mfma_f32_16x16x32_bf16 v[88:91], v[178:181], v[200:203], v[88:91]
	v_mfma_f32_16x16x32_bf16 v[76:79], v[170:173], v[208:211], v[76:79]
	v_mfma_f32_16x16x32_bf16 v[72:75], v[178:181], v[208:211], v[72:75]
	v_mfma_f32_16x16x32_bf16 v[68:71], v[170:173], v[216:219], v[68:71]
	v_mfma_f32_16x16x32_bf16 v[64:67], v[178:181], v[216:219], v[64:67]
	s_barrier
	s_add_i32 s30, s44, s2
	v_lshl_add_u64 v[190:191], v[190:191], 0, s[16:17]
	s_mov_b32 m0, s30
	ds_read_b128 v[182:185], v149 offset:49152
	ds_read_b128 v[186:189], v149 offset:50176
	ds_read_b128 v[196:199], v149 offset:51200
	ds_read_b128 v[200:203], v149 offset:52224
	ds_read_b128 v[204:207], v149 offset:53248
	ds_read_b128 v[208:211], v149 offset:54272
	ds_read_b128 v[212:215], v149 offset:55296
	ds_read_b128 v[216:219], v149 offset:56320
	global_load_lds_dwordx4 v[190:191], off
	s_add_i32 m0, s30, 0x2000
	s_add_u32 s28, s28, 0x18080
	v_lshl_add_u64 v[190:191], v[192:193], 0, s[16:17]
	s_addc_u32 s29, s29, 0
	s_add_i32 s30, s45, s2
	global_load_lds_dwordx4 v[190:191], off
	s_mov_b32 m0, s30
	s_nop 0
	global_load_lds_dwordx4 v132, s[28:29]
	s_add_i32 m0, s30, 0x2000
	s_nop 0
	global_load_lds_dwordx4 v128, s[28:29]
	v_lshl_add_u64 v[190:191], v[194:195], 0, s[16:17]
	s_mov_b32 m0, s35
	s_nop 0
	global_load_lds_dwordx4 v[190:191], off
	v_lshl_add_u64 v[190:191], v[220:221], 0, s[16:17]
	s_mov_b32 m0, s36
	s_nop 0
	global_load_lds_dwordx4 v[190:191], off
	s_waitcnt vmcnt(8)
	s_waitcnt lgkmcnt(0)
	s_barrier
	s_waitcnt lgkmcnt(0)
	v_mfma_f32_16x16x32_bf16 v[60:63], v[150:153], v[182:185], v[60:63]
	v_mfma_f32_16x16x32_bf16 v[56:59], v[158:161], v[182:185], v[56:59]
	v_mfma_f32_16x16x32_bf16 v[52:55], v[150:153], v[196:199], v[52:55]
	v_mfma_f32_16x16x32_bf16 v[48:51], v[158:161], v[196:199], v[48:51]
	v_mfma_f32_16x16x32_bf16 v[36:39], v[150:153], v[204:207], v[36:39]
	v_mfma_f32_16x16x32_bf16 v[32:35], v[158:161], v[204:207], v[32:35]
	v_mfma_f32_16x16x32_bf16 v[20:23], v[150:153], v[212:215], v[20:23]
	v_mfma_f32_16x16x32_bf16 v[16:19], v[158:161], v[212:215], v[16:19]
	v_mfma_f32_16x16x32_bf16 v[60:63], v[154:157], v[186:189], v[60:63]
	v_mfma_f32_16x16x32_bf16 v[56:59], v[162:165], v[186:189], v[56:59]
	v_mfma_f32_16x16x32_bf16 v[52:55], v[154:157], v[200:203], v[52:55]
	v_mfma_f32_16x16x32_bf16 v[48:51], v[162:165], v[200:203], v[48:51]
	v_mfma_f32_16x16x32_bf16 v[36:39], v[154:157], v[208:211], v[36:39]
	v_mfma_f32_16x16x32_bf16 v[32:35], v[162:165], v[208:211], v[32:35]
	v_mfma_f32_16x16x32_bf16 v[20:23], v[154:157], v[216:219], v[20:23]
	v_mfma_f32_16x16x32_bf16 v[16:19], v[162:165], v[216:219], v[16:19]
	v_mfma_f32_16x16x32_bf16 v[44:47], v[166:169], v[182:185], v[44:47]
	v_mfma_f32_16x16x32_bf16 v[40:43], v[174:177], v[182:185], v[40:43]
	v_mfma_f32_16x16x32_bf16 v[28:31], v[166:169], v[196:199], v[28:31]
	v_mfma_f32_16x16x32_bf16 v[24:27], v[174:177], v[196:199], v[24:27]
	v_mfma_f32_16x16x32_bf16 v[12:15], v[166:169], v[204:207], v[12:15]
	v_mfma_f32_16x16x32_bf16 v[8:11], v[174:177], v[204:207], v[8:11]
	v_mfma_f32_16x16x32_bf16 v[4:7], v[166:169], v[212:215], v[4:7]
	v_mfma_f32_16x16x32_bf16 v[0:3], v[174:177], v[212:215], v[0:3]
	v_mfma_f32_16x16x32_bf16 v[44:47], v[170:173], v[186:189], v[44:47]
	v_mfma_f32_16x16x32_bf16 v[40:43], v[178:181], v[186:189], v[40:43]
	v_mfma_f32_16x16x32_bf16 v[28:31], v[170:173], v[200:203], v[28:31]
	v_mfma_f32_16x16x32_bf16 v[24:27], v[178:181], v[200:203], v[24:27]
	v_mfma_f32_16x16x32_bf16 v[12:15], v[170:173], v[208:211], v[12:15]
	v_mfma_f32_16x16x32_bf16 v[8:11], v[178:181], v[208:211], v[8:11]
	v_mfma_f32_16x16x32_bf16 v[4:7], v[170:173], v[216:219], v[4:7]
	v_mfma_f32_16x16x32_bf16 v[0:3], v[178:181], v[216:219], v[0:3]
	s_barrier
	s_add_i32 s53, s53, 2
	s_add_u32 s0, s0, 0x100
	s_addc_u32 s1, s1, 0
	s_add_u32 s51, s51, 0x100
	s_addc_u32 s52, s52, 0
	s_cmp_gt_u32 s53, 3
	s_cbranch_scc0 .LBB0_303
	s_and_b64 vcc, exec, s[18:19]
	s_cbranch_vccz .LBB0_306
	s_barrier

; #define PG8_STAGE(bufoff, gbase, voff) do { _Pragma("unroll") for (int _i = 0; _i < 2; ++_i) \
;         __builtin_amdgcn_global_load_lds((const unsigned*)((const char*)(gbase) + (voff)[_i]), (PG8_LAS unsigned*)(lds + (bufoff) + ldsw + _i * 8192), 16, 0, 0); } while (0)
; #define PG8_LDA(dst, b, h) do { _Pragma("unroll") for (int m = 0; m < 4; ++m) _Pragma("unroll") for (int k = 0; k < 2; ++k) dst[m][k] = *(const PG8_LAS bf16x8*)(lds + PG8_SA(b, h) + aoff + m * 2048 + k * 1024); } while (0)
; #define PG8_LDB(dst, b, h) do { _Pragma("unroll") for (int n = 0; n < 2; ++n) _Pragma("unroll") for (int k = 0; k < 2; ++k) dst[n][k] = *(const PG8_LAS bf16x8*)(lds + PG8_SB(b, h) + boff + n * 2048 + k * 1024); } while (0)
; #define PG8_MMA(ai, bj, At, Bt) do { __builtin_amdgcn_s_setprio(1); _Pragma("unroll") for (int m = 0; m < 4; ++m) _Pragma("unroll") for (int n = 0; n < 2; ++n) _Pragma("unroll") for (int k = 0; k < 2; ++k) \
;         acc[ai][bj][m][n] = __builtin_amdgcn_mfma_f32_16x16x32_bf16(Bt[n][k], At[m][k], acc[ai][bj][m][n], 0, 0, 0); __builtin_amdgcn_s_setprio(0); } while (0)
; #define PG8_WAIT_V(n) asm volatile("s_waitcnt vmcnt(" #n ")" ::: "memory")
; #define PG8_WAIT_L(n) asm volatile("s_waitcnt lgkmcnt(" #n ")" ::: "memory")
; #define PG8_BAR __builtin_amdgcn_s_barrier()
; template <class Epi, class Sched, bool ALIGN_EPI = false, bool SP2 = false>
; __device__ __forceinline__ void gemm_phase(PG8_LAS unsigned char* lds, const Gemm g, const Sched& S, const Epi& E) {
;     ...
;             const char* a1 = cA + (size_t)(t + 1) * kstep;
;             const char* a2 = last ? nA : cA + (size_t)(t + 2) * kstep; const char* b2 = last ? nB : cB + (size_t)(t + 2) * kstep;
;             const char* a3 = a2 + kstep; const char* b3 = b2 + kstep;
;             if (last && has_next) S.a_ready(nxt);
;             if constexpr (SP2) {
;             PG8_LDB(B0, 0, 0); PG8_LDB(B1, 0, 1); PG8_SCHED; PG8_LDA(At, 0, 0); PG8_STAGE(PG8_SA(1, 1), a1 + hstepA, voffA);
;             PG8_WAIT_V(8); PG8_WAIT_L(0); PG8_BAR; PG8_MMA(0, 0, At, B0); PG8_MMA(0, 1, At, B1); PG8_BAR; PG8_SCHED;
;             PG8_LDA(At, 0, 1); PG8_STAGE(PG8_SB(0, 0), b2, voffB); PG8_STAGE(PG8_SB(0, 1), b2 + hstepB, voffB); PG8_STAGE(PG8_SA(0, 0), a2, voffA);
;             PG8_WAIT_V(8); PG8_WAIT_L(0); PG8_BAR; PG8_MMA(1, 0, At, B0); PG8_MMA(1, 1, At, B1); PG8_BAR; PG8_SCHED;
.LBB0_632:
	ds_read_b128 v[144:147], v151
	ds_read_b128 v[156:159], v151 offset:1024
	ds_read_b128 v[160:163], v151 offset:2048
	ds_read_b128 v[164:167], v151 offset:3072
	ds_read_b128 v[168:171], v152
	ds_read_b128 v[172:175], v152 offset:1024
	ds_read_b128 v[176:179], v152 offset:2048
	ds_read_b128 v[180:183], v152 offset:3072
	s_add_u32 s28, s26, 0xfffc0080
	s_addc_u32 s29, s27, -1
	s_cmp_eq_u32 s50, 12
	s_cselect_b32 s31, s17, s29
	s_cselect_b32 s30, s23, s28
	s_cselect_b32 s29, s15, s49
	s_cselect_b32 s28, s43, s48
	s_add_i32 m0, s9, 0xc000
	ds_read_b128 v[184:187], v153
	ds_read_b128 v[188:191], v153 offset:1024
	ds_read_b128 v[194:197], v153 offset:2048
	ds_read_b128 v[198:201], v153 offset:3072
	ds_read_b128 v[202:205], v153 offset:4096
	ds_read_b128 v[206:209], v153 offset:5120
	ds_read_b128 v[210:213], v153 offset:6144
	ds_read_b128 v[214:217], v153 offset:7168
	global_load_lds_dwordx4 v136, s[26:27]
	s_add_i32 m0, s9, 0xe000
	s_nop 0
	global_load_lds_dwordx4 v138, s[26:27]
	s_waitcnt vmcnt(8)
	s_waitcnt lgkmcnt(0)
	s_barrier
	s_waitcnt lgkmcnt(0)
	v_mfma_f32_16x16x32_bf16 v[124:127], v[144:147], v[184:187], v[124:127]
	v_mfma_f32_16x16x32_bf16 v[120:123], v[160:163], v[184:187], v[120:123]
	v_mfma_f32_16x16x32_bf16 v[108:111], v[144:147], v[194:197], v[108:111]
	v_mfma_f32_16x16x32_bf16 v[104:107], v[160:163], v[194:197], v[104:107]
	v_mfma_f32_16x16x32_bf16 v[92:95], v[144:147], v[202:205], v[92:95]
	v_mfma_f32_16x16x32_bf16 v[88:91], v[160:163], v[202:205], v[88:91]
	v_mfma_f32_16x16x32_bf16 v[76:79], v[144:147], v[210:213], v[76:79]
	v_mfma_f32_16x16x32_bf16 v[72:75], v[160:163], v[210:213], v[72:75]
	v_mfma_f32_16x16x32_bf16 v[124:127], v[156:159], v[188:191], v[124:127]
	v_mfma_f32_16x16x32_bf16 v[120:123], v[164:167], v[188:191], v[120:123]
	v_mfma_f32_16x16x32_bf16 v[108:111], v[156:159], v[198:201], v[108:111]
	v_mfma_f32_16x16x32_bf16 v[104:107], v[164:167], v[198:201], v[104:107]
	v_mfma_f32_16x16x32_bf16 v[92:95], v[156:159], v[206:209], v[92:95]
	v_mfma_f32_16x16x32_bf16 v[88:91], v[164:167], v[206:209], v[88:91]
	v_mfma_f32_16x16x32_bf16 v[76:79], v[156:159], v[214:217], v[76:79]
	v_mfma_f32_16x16x32_bf16 v[72:75], v[164:167], v[214:217], v[72:75]
	v_mfma_f32_16x16x32_bf16 v[116:119], v[168:171], v[184:187], v[116:119]
	v_mfma_f32_16x16x32_bf16 v[112:115], v[176:179], v[184:187], v[112:115]
	v_mfma_f32_16x16x32_bf16 v[100:103], v[168:171], v[194:197], v[100:103]
	v_mfma_f32_16x16x32_bf16 v[96:99], v[176:179], v[194:197], v[96:99]
	v_mfma_f32_16x16x32_bf16 v[84:87], v[168:171], v[202:205], v[84:87]
	v_mfma_f32_16x16x32_bf16 v[80:83], v[176:179], v[202:205], v[80:83]
	v_mfma_f32_16x16x32_bf16 v[68:71], v[168:171], v[210:213], v[68:71]
	v_mfma_f32_16x16x32_bf16 v[64:67], v[176:179], v[210:213], v[64:67]
	v_mfma_f32_16x16x32_bf16 v[116:119], v[172:175], v[188:191], v[116:119]
	v_mfma_f32_16x16x32_bf16 v[112:115], v[180:183], v[188:191], v[112:115]
	v_mfma_f32_16x16x32_bf16 v[100:103], v[172:175], v[198:201], v[100:103]
	v_mfma_f32_16x16x32_bf16 v[96:99], v[180:183], v[198:201], v[96:99]
	v_mfma_f32_16x16x32_bf16 v[84:87], v[172:175], v[206:209], v[84:87]
	v_mfma_f32_16x16x32_bf16 v[80:83], v[180:183], v[206:209], v[80:83]
	v_mfma_f32_16x16x32_bf16 v[68:71], v[172:175], v[214:217], v[68:71]
	v_mfma_f32_16x16x32_bf16 v[64:67], v[180:183], v[214:217], v[64:67]
	s_barrier
	s_add_i32 s44, s41, s8
	v_lshl_add_u64 v[192:193], s[28:29], 0, v[130:131]
	s_mov_b32 m0, s44
	ds_read_b128 v[184:187], v153 offset:16384
	ds_read_b128 v[188:191], v153 offset:17408
	ds_read_b128 v[194:197], v153 offset:18432
	ds_read_b128 v[198:201], v153 offset:19456
	ds_read_b128 v[202:205], v153 offset:20480
	ds_read_b128 v[206:209], v153 offset:21504
	ds_read_b128 v[210:213], v153 offset:22528
	ds_read_b128 v[214:217], v153 offset:23552
	global_load_lds_dwordx4 v[192:193], off
	s_add_i32 m0, s44, 0x2000
	s_add_u32 s44, s28, 0x40000
	v_lshl_add_u64 v[218:219], s[28:29], 0, v[134:135]
	s_addc_u32 s45, s29, 0
	s_add_i32 s51, s42, s8
	global_load_lds_dwordx4 v[218:219], off
	s_mov_b32 m0, s51
	v_lshl_add_u64 v[222:223], s[30:31], 0, v[132:133]
	global_load_lds_dwordx4 v130, s[44:45]
	s_add_i32 m0, s51, 0x2000
	s_nop 0
	global_load_lds_dwordx4 v134, s[44:45]
	v_lshl_add_u64 v[220:221], s[30:31], 0, v[128:129]
	s_mov_b32 m0, s9
	s_nop 0
	global_load_lds_dwordx4 v[220:221], off
	s_mov_b32 m0, s10
	s_nop 0
	global_load_lds_dwordx4 v[222:223], off
	s_waitcnt vmcnt(8)
	s_waitcnt lgkmcnt(0)
	s_barrier
	s_waitcnt lgkmcnt(0)
	v_mfma_f32_16x16x32_bf16 v[60:63], v[144:147], v[184:187], v[60:63]
	v_mfma_f32_16x16x32_bf16 v[56:59], v[160:163], v[184:187], v[56:59]
	v_mfma_f32_16x16x32_bf16 v[44:47], v[144:147], v[194:197], v[44:47]
	v_mfma_f32_16x16x32_bf16 v[40:43], v[160:163], v[194:197], v[40:43]
	v_mfma_f32_16x16x32_bf16 v[28:31], v[144:147], v[202:205], v[28:31]
	v_mfma_f32_16x16x32_bf16 v[24:27], v[160:163], v[202:205], v[24:27]
	v_mfma_f32_16x16x32_bf16 v[12:15], v[144:147], v[210:213], v[12:15]
	v_mfma_f32_16x16x32_bf16 v[8:11], v[160:163], v[210:213], v[8:11]
	v_mfma_f32_16x16x32_bf16 v[60:63], v[156:159], v[188:191], v[60:63]
	v_mfma_f32_16x16x32_bf16 v[56:59], v[164:167], v[188:191], v[56:59]
	v_mfma_f32_16x16x32_bf16 v[44:47], v[156:159], v[198:201], v[44:47]
	v_mfma_f32_16x16x32_bf16 v[40:43], v[164:167], v[198:201], v[40:43]
	v_mfma_f32_16x16x32_bf16 v[28:31], v[156:159], v[206:209], v[28:31]
	v_mfma_f32_16x16x32_bf16 v[24:27], v[164:167], v[206:209], v[24:27]
	v_mfma_f32_16x16x32_bf16 v[12:15], v[156:159], v[214:217], v[12:15]
	v_mfma_f32_16x16x32_bf16 v[8:11], v[164:167], v[214:217], v[8:11]
	v_mfma_f32_16x16x32_bf16 v[52:55], v[168:171], v[184:187], v[52:55]
	v_mfma_f32_16x16x32_bf16 v[48:51], v[176:179], v[184:187], v[48:51]
	v_mfma_f32_16x16x32_bf16 v[36:39], v[168:171], v[194:197], v[36:39]
	v_mfma_f32_16x16x32_bf16 v[32:35], v[176:179], v[194:197], v[32:35]
	v_mfma_f32_16x16x32_bf16 v[20:23], v[168:171], v[202:205], v[20:23]
	v_mfma_f32_16x16x32_bf16 v[16:19], v[176:179], v[202:205], v[16:19]
	v_mfma_f32_16x16x32_bf16 v[4:7], v[168:171], v[210:213], v[4:7]
	v_mfma_f32_16x16x32_bf16 v[0:3], v[176:179], v[210:213], v[0:3]
	v_mfma_f32_16x16x32_bf16 v[52:55], v[172:175], v[188:191], v[52:55]
	v_mfma_f32_16x16x32_bf16 v[48:51], v[180:183], v[188:191], v[48:51]
	v_mfma_f32_16x16x32_bf16 v[36:39], v[172:175], v[198:201], v[36:39]
	v_mfma_f32_16x16x32_bf16 v[32:35], v[180:183], v[198:201], v[32:35]
	v_mfma_f32_16x16x32_bf16 v[20:23], v[172:175], v[206:209], v[20:23]
	v_mfma_f32_16x16x32_bf16 v[16:19], v[180:183], v[206:209], v[16:19]
	v_mfma_f32_16x16x32_bf16 v[4:7], v[172:175], v[214:217], v[4:7]
	v_mfma_f32_16x16x32_bf16 v[0:3], v[180:183], v[214:217], v[0:3]
	s_barrier
; #define PG8_STAGE(bufoff, gbase, voff) do { _Pragma("unroll") for (int _i = 0; _i < 2; ++_i) \
;         __builtin_amdgcn_global_load_lds((const unsigned*)((const char*)(gbase) + (voff)[_i]), (PG8_LAS unsigned*)(lds + (bufoff) + ldsw + _i * 8192), 16, 0, 0); } while (0)
; #define PG8_LDA(dst, b, h) do { _Pragma("unroll") for (int m = 0; m < 4; ++m) _Pragma("unroll") for (int k = 0; k < 2; ++k) dst[m][k] = *(const PG8_LAS bf16x8*)(lds + PG8_SA(b, h) + aoff + m * 2048 + k * 1024); } while (0)
; #define PG8_LDB(dst, b, h) do { _Pragma("unroll") for (int n = 0; n < 2; ++n) _Pragma("unroll") for (int k = 0; k < 2; ++k) dst[n][k] = *(const PG8_LAS bf16x8*)(lds + PG8_SB(b, h) + boff + n * 2048 + k * 1024); } while (0)
; #define PG8_MMA(ai, bj, At, Bt) do { __builtin_amdgcn_s_setprio(1); _Pragma("unroll") for (int m = 0; m < 4; ++m) _Pragma("unroll") for (int n = 0; n < 2; ++n) _Pragma("unroll") for (int k = 0; k < 2; ++k) \
;         acc[ai][bj][m][n] = __builtin_amdgcn_mfma_f32_16x16x32_bf16(Bt[n][k], At[m][k], acc[ai][bj][m][n], 0, 0, 0); __builtin_amdgcn_s_setprio(0); } while (0)
; #define PG8_WAIT_V(n) asm volatile("s_waitcnt vmcnt(" #n ")" ::: "memory")
; #define PG8_WAIT_L(n) asm volatile("s_waitcnt lgkmcnt(" #n ")" ::: "memory")
; #define PG8_BAR __builtin_amdgcn_s_barrier()
; #define PG8_SCHED __builtin_amdgcn_sched_barrier(0)
; template <class Epi, class Sched, bool ALIGN_EPI = false, bool SP2 = false>
; __device__ __forceinline__ void gemm_phase(PG8_LAS unsigned char* lds, const Gemm g, const Sched& S, const Epi& E) {
;     ...
;             PG8_LDB(B0, 1, 0); PG8_LDB(B1, 1, 1); PG8_SCHED; PG8_LDA(At, 1, 0); PG8_STAGE(PG8_SA(0, 1), a2 + hstepA, voffA);
;             PG8_WAIT_V(8); PG8_WAIT_L(0); PG8_BAR; PG8_MMA(0, 0, At, B0); PG8_MMA(0, 1, At, B1); PG8_BAR; PG8_SCHED;
;             PG8_LDA(At, 1, 1); PG8_STAGE(PG8_SB(1, 0), b3, voffB); PG8_STAGE(PG8_SB(1, 1), b3 + hstepB, voffB); PG8_STAGE(PG8_SA(1, 0), a3, voffA);
;             PG8_WAIT_V(8); PG8_WAIT_L(0); PG8_BAR; PG8_MMA(1, 0, At, B0); PG8_MMA(1, 1, At, B1); PG8_BAR; PG8_SCHED;
	s_add_i32 s44, 0, 0x18000
	v_add_u32_e32 v155, s44, v150
	s_add_i32 s45, 0, 0x1c000
	ds_read_b128 v[144:147], v155
	ds_read_b128 v[156:159], v155 offset:1024
	ds_read_b128 v[160:163], v155 offset:2048
	ds_read_b128 v[164:167], v155 offset:3072
	v_add_u32_e32 v155, s45, v150
	ds_read_b128 v[168:171], v155
	ds_read_b128 v[172:175], v155 offset:1024
	ds_read_b128 v[176:179], v155 offset:2048
	ds_read_b128 v[180:183], v155 offset:3072
	s_add_u32 s30, s30, 0x40000
	s_addc_u32 s31, s31, 0
	s_mov_b32 m0, s11
	ds_read_b128 v[184:187], v153 offset:32768
	ds_read_b128 v[188:191], v153 offset:33792
	ds_read_b128 v[194:197], v153 offset:34816
	ds_read_b128 v[198:201], v153 offset:35840
	ds_read_b128 v[202:205], v153 offset:36864
	ds_read_b128 v[206:209], v153 offset:37888
	ds_read_b128 v[210:213], v153 offset:38912
	ds_read_b128 v[214:217], v153 offset:39936
	global_load_lds_dwordx4 v128, s[30:31]
	s_mov_b32 m0, s25
	s_nop 0
	global_load_lds_dwordx4 v132, s[30:31]
	s_waitcnt vmcnt(8)
	s_waitcnt lgkmcnt(0)
	s_barrier
	s_waitcnt lgkmcnt(0)
	v_mfma_f32_16x16x32_bf16 v[124:127], v[144:147], v[184:187], v[124:127]
	v_mfma_f32_16x16x32_bf16 v[120:123], v[160:163], v[184:187], v[120:123]
	v_mfma_f32_16x16x32_bf16 v[108:111], v[144:147], v[194:197], v[108:111]
	v_mfma_f32_16x16x32_bf16 v[104:107], v[160:163], v[194:197], v[104:107]
	v_mfma_f32_16x16x32_bf16 v[92:95], v[144:147], v[202:205], v[92:95]
	v_mfma_f32_16x16x32_bf16 v[88:91], v[160:163], v[202:205], v[88:91]
	v_mfma_f32_16x16x32_bf16 v[76:79], v[144:147], v[210:213], v[76:79]
	v_mfma_f32_16x16x32_bf16 v[72:75], v[160:163], v[210:213], v[72:75]
	v_mfma_f32_16x16x32_bf16 v[124:127], v[156:159], v[188:191], v[124:127]
	v_mfma_f32_16x16x32_bf16 v[120:123], v[164:167], v[188:191], v[120:123]
	v_mfma_f32_16x16x32_bf16 v[108:111], v[156:159], v[198:201], v[108:111]
	v_mfma_f32_16x16x32_bf16 v[104:107], v[164:167], v[198:201], v[104:107]
	v_mfma_f32_16x16x32_bf16 v[92:95], v[156:159], v[206:209], v[92:95]
	v_mfma_f32_16x16x32_bf16 v[88:91], v[164:167], v[206:209], v[88:91]
	v_mfma_f32_16x16x32_bf16 v[76:79], v[156:159], v[214:217], v[76:79]
	v_mfma_f32_16x16x32_bf16 v[72:75], v[164:167], v[214:217], v[72:75]
	v_mfma_f32_16x16x32_bf16 v[116:119], v[168:171], v[184:187], v[116:119]
	v_mfma_f32_16x16x32_bf16 v[112:115], v[176:179], v[184:187], v[112:115]
	v_mfma_f32_16x16x32_bf16 v[100:103], v[168:171], v[194:197], v[100:103]
	v_mfma_f32_16x16x32_bf16 v[96:99], v[176:179], v[194:197], v[96:99]
	v_mfma_f32_16x16x32_bf16 v[84:87], v[168:171], v[202:205], v[84:87]
	v_mfma_f32_16x16x32_bf16 v[80:83], v[176:179], v[202:205], v[80:83]
	v_mfma_f32_16x16x32_bf16 v[68:71], v[168:171], v[210:213], v[68:71]
	v_mfma_f32_16x16x32_bf16 v[64:67], v[176:179], v[210:213], v[64:67]
	v_mfma_f32_16x16x32_bf16 v[116:119], v[172:175], v[188:191], v[116:119]
	v_mfma_f32_16x16x32_bf16 v[112:115], v[180:183], v[188:191], v[112:115]
	v_mfma_f32_16x16x32_bf16 v[100:103], v[172:175], v[198:201], v[100:103]
	v_mfma_f32_16x16x32_bf16 v[96:99], v[180:183], v[198:201], v[96:99]
	v_mfma_f32_16x16x32_bf16 v[84:87], v[172:175], v[206:209], v[84:87]
	v_mfma_f32_16x16x32_bf16 v[80:83], v[180:183], v[206:209], v[80:83]
	v_mfma_f32_16x16x32_bf16 v[68:71], v[172:175], v[214:217], v[68:71]
	v_mfma_f32_16x16x32_bf16 v[64:67], v[180:183], v[214:217], v[64:67]
	s_barrier
	s_add_i32 s30, s44, s8
	v_lshl_add_u64 v[192:193], v[192:193], 0, s[6:7]
	s_mov_b32 m0, s30
	ds_read_b128 v[184:187], v153 offset:49152
	ds_read_b128 v[188:191], v153 offset:50176
	ds_read_b128 v[194:197], v153 offset:51200
	ds_read_b128 v[198:201], v153 offset:52224
	ds_read_b128 v[202:205], v153 offset:53248
	ds_read_b128 v[206:209], v153 offset:54272
	ds_read_b128 v[210:213], v153 offset:55296
	ds_read_b128 v[214:217], v153 offset:56320
	global_load_lds_dwordx4 v[192:193], off
	s_add_i32 m0, s30, 0x2000
	s_add_u32 s28, s28, 0x40080
	v_lshl_add_u64 v[192:193], v[218:219], 0, s[6:7]
	s_addc_u32 s29, s29, 0
	s_add_i32 s30, s45, s8
	global_load_lds_dwordx4 v[192:193], off
	s_mov_b32 m0, s30
	s_nop 0
	global_load_lds_dwordx4 v130, s[28:29]
	s_add_i32 m0, s30, 0x2000
	s_nop 0
	global_load_lds_dwordx4 v134, s[28:29]
	v_lshl_add_u64 v[192:193], v[220:221], 0, s[6:7]
	s_mov_b32 m0, s36
	s_nop 0
	global_load_lds_dwordx4 v[192:193], off
	v_lshl_add_u64 v[192:193], v[222:223], 0, s[6:7]
	s_mov_b32 m0, s37
	s_nop 0
	global_load_lds_dwordx4 v[192:193], off
	s_waitcnt vmcnt(8)
	s_waitcnt lgkmcnt(0)
	s_barrier
	s_waitcnt lgkmcnt(0)
	v_mfma_f32_16x16x32_bf16 v[60:63], v[144:147], v[184:187], v[60:63]
	v_mfma_f32_16x16x32_bf16 v[56:59], v[160:163], v[184:187], v[56:59]
	v_mfma_f32_16x16x32_bf16 v[44:47], v[144:147], v[194:197], v[44:47]
	v_mfma_f32_16x16x32_bf16 v[40:43], v[160:163], v[194:197], v[40:43]
	v_mfma_f32_16x16x32_bf16 v[28:31], v[144:147], v[202:205], v[28:31]
	v_mfma_f32_16x16x32_bf16 v[24:27], v[160:163], v[202:205], v[24:27]
	v_mfma_f32_16x16x32_bf16 v[12:15], v[144:147], v[210:213], v[12:15]
	v_mfma_f32_16x16x32_bf16 v[8:11], v[160:163], v[210:213], v[8:11]
	v_mfma_f32_16x16x32_bf16 v[60:63], v[156:159], v[188:191], v[60:63]
	v_mfma_f32_16x16x32_bf16 v[56:59], v[164:167], v[188:191], v[56:59]
	v_mfma_f32_16x16x32_bf16 v[44:47], v[156:159], v[198:201], v[44:47]
	v_mfma_f32_16x16x32_bf16 v[40:43], v[164:167], v[198:201], v[40:43]
	v_mfma_f32_16x16x32_bf16 v[28:31], v[156:159], v[206:209], v[28:31]
	v_mfma_f32_16x16x32_bf16 v[24:27], v[164:167], v[206:209], v[24:27]
	v_mfma_f32_16x16x32_bf16 v[12:15], v[156:159], v[214:217], v[12:15]
	v_mfma_f32_16x16x32_bf16 v[8:11], v[164:167], v[214:217], v[8:11]
	v_mfma_f32_16x16x32_bf16 v[52:55], v[168:171], v[184:187], v[52:55]
	v_mfma_f32_16x16x32_bf16 v[48:51], v[176:179], v[184:187], v[48:51]
	v_mfma_f32_16x16x32_bf16 v[36:39], v[168:171], v[194:197], v[36:39]
	v_mfma_f32_16x16x32_bf16 v[32:35], v[176:179], v[194:197], v[32:35]
	v_mfma_f32_16x16x32_bf16 v[20:23], v[168:171], v[202:205], v[20:23]
	v_mfma_f32_16x16x32_bf16 v[16:19], v[176:179], v[202:205], v[16:19]
	v_mfma_f32_16x16x32_bf16 v[4:7], v[168:171], v[210:213], v[4:7]
	v_mfma_f32_16x16x32_bf16 v[0:3], v[176:179], v[210:213], v[0:3]
	v_mfma_f32_16x16x32_bf16 v[52:55], v[172:175], v[188:191], v[52:55]
	v_mfma_f32_16x16x32_bf16 v[48:51], v[180:183], v[188:191], v[48:51]
	v_mfma_f32_16x16x32_bf16 v[36:39], v[172:175], v[198:201], v[36:39]
	v_mfma_f32_16x16x32_bf16 v[32:35], v[180:183], v[198:201], v[32:35]
	v_mfma_f32_16x16x32_bf16 v[20:23], v[172:175], v[206:209], v[20:23]
	v_mfma_f32_16x16x32_bf16 v[16:19], v[180:183], v[206:209], v[16:19]
	v_mfma_f32_16x16x32_bf16 v[4:7], v[172:175], v[214:217], v[4:7]
	v_mfma_f32_16x16x32_bf16 v[0:3], v[180:183], v[214:217], v[0:3]
	s_barrier
	s_add_i32 s50, s50, 2
	s_add_u32 s26, s26, 0x100
	s_addc_u32 s27, s27, 0
	s_add_u32 s48, s48, 0x100
	s_addc_u32 s49, s49, 0
	s_cmp_gt_u32 s50, 13
	s_cbranch_scc0 .LBB0_632
	s_and_b64 vcc, exec, s[12:13]
	s_cbranch_vccz .LBB0_635
	s_barrier

; #define PG8_STAGE(bufoff, gbase, voff) do { _Pragma("unroll") for (int _i = 0; _i < 2; ++_i) \
;         __builtin_amdgcn_global_load_lds((const unsigned*)((const char*)(gbase) + (voff)[_i]), (PG8_LAS unsigned*)(lds + (bufoff) + ldsw + _i * 8192), 16, 0, 0); } while (0)
; #define PG8_LDA(dst, b, h) do { _Pragma("unroll") for (int m = 0; m < 4; ++m) _Pragma("unroll") for (int k = 0; k < 2; ++k) dst[m][k] = *(const PG8_LAS bf16x8*)(lds + PG8_SA(b, h) + aoff + m * 2048 + k * 1024); } while (0)
; #define PG8_LDB(dst, b, h) do { _Pragma("unroll") for (int n = 0; n < 2; ++n) _Pragma("unroll") for (int k = 0; k < 2; ++k) dst[n][k] = *(const PG8_LAS bf16x8*)(lds + PG8_SB(b, h) + boff + n * 2048 + k * 1024); } while (0)
; #define PG8_MMA(ai, bj, At, Bt) do { __builtin_amdgcn_s_setprio(1); _Pragma("unroll") for (int m = 0; m < 4; ++m) _Pragma("unroll") for (int n = 0; n < 2; ++n) _Pragma("unroll") for (int k = 0; k < 2; ++k) \
;         acc[ai][bj][m][n] = __builtin_amdgcn_mfma_f32_16x16x32_bf16(Bt[n][k], At[m][k], acc[ai][bj][m][n], 0, 0, 0); __builtin_amdgcn_s_setprio(0); } while (0)
; #define PG8_WAIT_V(n) asm volatile("s_waitcnt vmcnt(" #n ")" ::: "memory")
; #define PG8_WAIT_L(n) asm volatile("s_waitcnt lgkmcnt(" #n ")" ::: "memory")
; #define PG8_BAR __builtin_amdgcn_s_barrier()
; template <class Epi, class Sched, bool ALIGN_EPI = false, bool SP2 = false>
; __device__ __forceinline__ void gemm_phase(PG8_LAS unsigned char* lds, const Gemm g, const Sched& S, const Epi& E) {
;     ...
;             const char* a1 = cA + (size_t)(t + 1) * kstep;
;             const char* a2 = last ? nA : cA + (size_t)(t + 2) * kstep; const char* b2 = last ? nB : cB + (size_t)(t + 2) * kstep;
;             const char* a3 = a2 + kstep; const char* b3 = b2 + kstep;
;             if (last && has_next) S.a_ready(nxt);
;             if constexpr (SP2) {
;             PG8_LDB(B0, 0, 0); PG8_LDB(B1, 0, 1); PG8_SCHED; PG8_LDA(At, 0, 0); PG8_STAGE(PG8_SA(1, 1), a1 + hstepA, voffA);
;             PG8_WAIT_V(8); PG8_WAIT_L(0); PG8_BAR; PG8_MMA(0, 0, At, B0); PG8_MMA(0, 1, At, B1); PG8_BAR; PG8_SCHED;
;             PG8_LDA(At, 0, 1); PG8_STAGE(PG8_SB(0, 0), b2, voffB); PG8_STAGE(PG8_SB(0, 1), b2 + hstepB, voffB); PG8_STAGE(PG8_SA(0, 0), a2, voffA);
;             PG8_WAIT_V(8); PG8_WAIT_L(0); PG8_BAR; PG8_MMA(1, 0, At, B0); PG8_MMA(1, 1, At, B1); PG8_BAR; PG8_SCHED;
.LBB0_724:
	ds_read_b128 v[144:147], v151
	ds_read_b128 v[156:159], v151 offset:1024
	ds_read_b128 v[160:163], v151 offset:2048
	ds_read_b128 v[164:167], v151 offset:3072
	ds_read_b128 v[168:171], v152
	ds_read_b128 v[172:175], v152 offset:1024
	ds_read_b128 v[176:179], v152 offset:2048
	ds_read_b128 v[180:183], v152 offset:3072
	s_add_u32 s44, s40, 0xfffc0080
	s_addc_u32 s45, s41, -1
	s_cmp_eq_u32 s63, 12
	s_cselect_b32 s49, s8, s45
	s_cselect_b32 s48, s9, s44
	s_cselect_b32 s45, s29, s62
	s_cselect_b32 s44, s31, s42
	s_add_i32 m0, s39, 0xc000
	ds_read_b128 v[184:187], v153
	ds_read_b128 v[188:191], v153 offset:1024
	ds_read_b128 v[194:197], v153 offset:2048
	ds_read_b128 v[198:201], v153 offset:3072
	ds_read_b128 v[202:205], v153 offset:4096
	ds_read_b128 v[206:209], v153 offset:5120
	ds_read_b128 v[210:213], v153 offset:6144
	ds_read_b128 v[214:217], v153 offset:7168
	global_load_lds_dwordx4 v136, s[40:41]
	s_add_i32 m0, s39, 0xe000
	s_nop 0
	global_load_lds_dwordx4 v138, s[40:41]
	s_waitcnt vmcnt(8)
	s_waitcnt lgkmcnt(0)
	s_barrier
	s_waitcnt lgkmcnt(0)
	v_mfma_f32_16x16x32_bf16 v[124:127], v[144:147], v[184:187], v[124:127]
	v_mfma_f32_16x16x32_bf16 v[120:123], v[160:163], v[184:187], v[120:123]
	v_mfma_f32_16x16x32_bf16 v[108:111], v[144:147], v[194:197], v[108:111]
	v_mfma_f32_16x16x32_bf16 v[104:107], v[160:163], v[194:197], v[104:107]
	v_mfma_f32_16x16x32_bf16 v[92:95], v[144:147], v[202:205], v[92:95]
	v_mfma_f32_16x16x32_bf16 v[88:91], v[160:163], v[202:205], v[88:91]
	v_mfma_f32_16x16x32_bf16 v[76:79], v[144:147], v[210:213], v[76:79]
	v_mfma_f32_16x16x32_bf16 v[72:75], v[160:163], v[210:213], v[72:75]
	v_mfma_f32_16x16x32_bf16 v[124:127], v[156:159], v[188:191], v[124:127]
	v_mfma_f32_16x16x32_bf16 v[120:123], v[164:167], v[188:191], v[120:123]
	v_mfma_f32_16x16x32_bf16 v[108:111], v[156:159], v[198:201], v[108:111]
	v_mfma_f32_16x16x32_bf16 v[104:107], v[164:167], v[198:201], v[104:107]
	v_mfma_f32_16x16x32_bf16 v[92:95], v[156:159], v[206:209], v[92:95]
	v_mfma_f32_16x16x32_bf16 v[88:91], v[164:167], v[206:209], v[88:91]
	v_mfma_f32_16x16x32_bf16 v[76:79], v[156:159], v[214:217], v[76:79]
	v_mfma_f32_16x16x32_bf16 v[72:75], v[164:167], v[214:217], v[72:75]
	v_mfma_f32_16x16x32_bf16 v[116:119], v[168:171], v[184:187], v[116:119]
	v_mfma_f32_16x16x32_bf16 v[112:115], v[176:179], v[184:187], v[112:115]
	v_mfma_f32_16x16x32_bf16 v[100:103], v[168:171], v[194:197], v[100:103]
	v_mfma_f32_16x16x32_bf16 v[96:99], v[176:179], v[194:197], v[96:99]
	v_mfma_f32_16x16x32_bf16 v[84:87], v[168:171], v[202:205], v[84:87]
	v_mfma_f32_16x16x32_bf16 v[80:83], v[176:179], v[202:205], v[80:83]
	v_mfma_f32_16x16x32_bf16 v[68:71], v[168:171], v[210:213], v[68:71]
	v_mfma_f32_16x16x32_bf16 v[64:67], v[176:179], v[210:213], v[64:67]
	v_mfma_f32_16x16x32_bf16 v[116:119], v[172:175], v[188:191], v[116:119]
	v_mfma_f32_16x16x32_bf16 v[112:115], v[180:183], v[188:191], v[112:115]
	v_mfma_f32_16x16x32_bf16 v[100:103], v[172:175], v[198:201], v[100:103]
	v_mfma_f32_16x16x32_bf16 v[96:99], v[180:183], v[198:201], v[96:99]
	v_mfma_f32_16x16x32_bf16 v[84:87], v[172:175], v[206:209], v[84:87]
	v_mfma_f32_16x16x32_bf16 v[80:83], v[180:183], v[206:209], v[80:83]
	v_mfma_f32_16x16x32_bf16 v[68:71], v[172:175], v[214:217], v[68:71]
	v_mfma_f32_16x16x32_bf16 v[64:67], v[180:183], v[214:217], v[64:67]
	s_barrier
	s_add_i32 s64, s60, s50
	v_lshl_add_u64 v[192:193], s[44:45], 0, v[130:131]
	s_mov_b32 m0, s64
	ds_read_b128 v[184:187], v153 offset:16384
	ds_read_b128 v[188:191], v153 offset:17408
	ds_read_b128 v[194:197], v153 offset:18432
	ds_read_b128 v[198:201], v153 offset:19456
	ds_read_b128 v[202:205], v153 offset:20480
	ds_read_b128 v[206:209], v153 offset:21504
	ds_read_b128 v[210:213], v153 offset:22528
	ds_read_b128 v[214:217], v153 offset:23552
	global_load_lds_dwordx4 v[192:193], off
	s_add_i32 m0, s64, 0x2000
	s_add_u32 s64, s44, 0x40000
	v_lshl_add_u64 v[218:219], s[44:45], 0, v[134:135]
	s_addc_u32 s65, s45, 0
	s_add_i32 s66, s61, s50
	global_load_lds_dwordx4 v[218:219], off
	s_mov_b32 m0, s66
	v_lshl_add_u64 v[222:223], s[48:49], 0, v[132:133]
	global_load_lds_dwordx4 v130, s[64:65]
	s_add_i32 m0, s66, 0x2000
	s_nop 0
	global_load_lds_dwordx4 v134, s[64:65]
	v_lshl_add_u64 v[220:221], s[48:49], 0, v[128:129]
	s_mov_b32 m0, s39
	s_nop 0
	global_load_lds_dwordx4 v[220:221], off
	s_mov_b32 m0, s51
	s_nop 0
	global_load_lds_dwordx4 v[222:223], off
	s_waitcnt vmcnt(8)
	s_waitcnt lgkmcnt(0)
	s_barrier
	s_waitcnt lgkmcnt(0)
	v_mfma_f32_16x16x32_bf16 v[60:63], v[144:147], v[184:187], v[60:63]
	v_mfma_f32_16x16x32_bf16 v[56:59], v[160:163], v[184:187], v[56:59]
	v_mfma_f32_16x16x32_bf16 v[44:47], v[144:147], v[194:197], v[44:47]
	v_mfma_f32_16x16x32_bf16 v[40:43], v[160:163], v[194:197], v[40:43]
	v_mfma_f32_16x16x32_bf16 v[28:31], v[144:147], v[202:205], v[28:31]
	v_mfma_f32_16x16x32_bf16 v[24:27], v[160:163], v[202:205], v[24:27]
	v_mfma_f32_16x16x32_bf16 v[12:15], v[144:147], v[210:213], v[12:15]
	v_mfma_f32_16x16x32_bf16 v[8:11], v[160:163], v[210:213], v[8:11]
	v_mfma_f32_16x16x32_bf16 v[60:63], v[156:159], v[188:191], v[60:63]
	v_mfma_f32_16x16x32_bf16 v[56:59], v[164:167], v[188:191], v[56:59]
	v_mfma_f32_16x16x32_bf16 v[44:47], v[156:159], v[198:201], v[44:47]
	v_mfma_f32_16x16x32_bf16 v[40:43], v[164:167], v[198:201], v[40:43]
	v_mfma_f32_16x16x32_bf16 v[28:31], v[156:159], v[206:209], v[28:31]
	v_mfma_f32_16x16x32_bf16 v[24:27], v[164:167], v[206:209], v[24:27]
	v_mfma_f32_16x16x32_bf16 v[12:15], v[156:159], v[214:217], v[12:15]
	v_mfma_f32_16x16x32_bf16 v[8:11], v[164:167], v[214:217], v[8:11]
	v_mfma_f32_16x16x32_bf16 v[52:55], v[168:171], v[184:187], v[52:55]
	v_mfma_f32_16x16x32_bf16 v[48:51], v[176:179], v[184:187], v[48:51]
	v_mfma_f32_16x16x32_bf16 v[36:39], v[168:171], v[194:197], v[36:39]
	v_mfma_f32_16x16x32_bf16 v[32:35], v[176:179], v[194:197], v[32:35]
	v_mfma_f32_16x16x32_bf16 v[20:23], v[168:171], v[202:205], v[20:23]
	v_mfma_f32_16x16x32_bf16 v[16:19], v[176:179], v[202:205], v[16:19]
	v_mfma_f32_16x16x32_bf16 v[4:7], v[168:171], v[210:213], v[4:7]
	v_mfma_f32_16x16x32_bf16 v[0:3], v[176:179], v[210:213], v[0:3]
	v_mfma_f32_16x16x32_bf16 v[52:55], v[172:175], v[188:191], v[52:55]
	v_mfma_f32_16x16x32_bf16 v[48:51], v[180:183], v[188:191], v[48:51]
	v_mfma_f32_16x16x32_bf16 v[36:39], v[172:175], v[198:201], v[36:39]
	v_mfma_f32_16x16x32_bf16 v[32:35], v[180:183], v[198:201], v[32:35]
	v_mfma_f32_16x16x32_bf16 v[20:23], v[172:175], v[206:209], v[20:23]
	v_mfma_f32_16x16x32_bf16 v[16:19], v[180:183], v[206:209], v[16:19]
	v_mfma_f32_16x16x32_bf16 v[4:7], v[172:175], v[214:217], v[4:7]
	v_mfma_f32_16x16x32_bf16 v[0:3], v[180:183], v[214:217], v[0:3]
	s_barrier
; #define PG8_STAGE(bufoff, gbase, voff) do { _Pragma("unroll") for (int _i = 0; _i < 2; ++_i) \
;         __builtin_amdgcn_global_load_lds((const unsigned*)((const char*)(gbase) + (voff)[_i]), (PG8_LAS unsigned*)(lds + (bufoff) + ldsw + _i * 8192), 16, 0, 0); } while (0)
; #define PG8_LDA(dst, b, h) do { _Pragma("unroll") for (int m = 0; m < 4; ++m) _Pragma("unroll") for (int k = 0; k < 2; ++k) dst[m][k] = *(const PG8_LAS bf16x8*)(lds + PG8_SA(b, h) + aoff + m * 2048 + k * 1024); } while (0)
; #define PG8_LDB(dst, b, h) do { _Pragma("unroll") for (int n = 0; n < 2; ++n) _Pragma("unroll") for (int k = 0; k < 2; ++k) dst[n][k] = *(const PG8_LAS bf16x8*)(lds + PG8_SB(b, h) + boff + n * 2048 + k * 1024); } while (0)
; #define PG8_MMA(ai, bj, At, Bt) do { __builtin_amdgcn_s_setprio(1); _Pragma("unroll") for (int m = 0; m < 4; ++m) _Pragma("unroll") for (int n = 0; n < 2; ++n) _Pragma("unroll") for (int k = 0; k < 2; ++k) \
;         acc[ai][bj][m][n] = __builtin_amdgcn_mfma_f32_16x16x32_bf16(Bt[n][k], At[m][k], acc[ai][bj][m][n], 0, 0, 0); __builtin_amdgcn_s_setprio(0); } while (0)
; #define PG8_WAIT_V(n) asm volatile("s_waitcnt vmcnt(" #n ")" ::: "memory")
; #define PG8_WAIT_L(n) asm volatile("s_waitcnt lgkmcnt(" #n ")" ::: "memory")
; #define PG8_BAR __builtin_amdgcn_s_barrier()
; #define PG8_SCHED __builtin_amdgcn_sched_barrier(0)
; template <class Epi, class Sched, bool ALIGN_EPI = false, bool SP2 = false>
; __device__ __forceinline__ void gemm_phase(PG8_LAS unsigned char* lds, const Gemm g, const Sched& S, const Epi& E) {
;     ...
;             PG8_LDB(B0, 1, 0); PG8_LDB(B1, 1, 1); PG8_SCHED; PG8_LDA(At, 1, 0); PG8_STAGE(PG8_SA(0, 1), a2 + hstepA, voffA);
;             PG8_WAIT_V(8); PG8_WAIT_L(0); PG8_BAR; PG8_MMA(0, 0, At, B0); PG8_MMA(0, 1, At, B1); PG8_BAR; PG8_SCHED;
;             PG8_LDA(At, 1, 1); PG8_STAGE(PG8_SB(1, 0), b3, voffB); PG8_STAGE(PG8_SB(1, 1), b3 + hstepB, voffB); PG8_STAGE(PG8_SA(1, 0), a3, voffA);
;             PG8_WAIT_V(8); PG8_WAIT_L(0); PG8_BAR; PG8_MMA(1, 0, At, B0); PG8_MMA(1, 1, At, B1); PG8_BAR; PG8_SCHED;
	s_add_i32 s64, 0, 0x18000
	v_add_u32_e32 v155, s64, v150
	s_add_i32 s65, 0, 0x1c000
	ds_read_b128 v[144:147], v155
	ds_read_b128 v[156:159], v155 offset:1024
	ds_read_b128 v[160:163], v155 offset:2048
	ds_read_b128 v[164:167], v155 offset:3072
	v_add_u32_e32 v155, s65, v150
	ds_read_b128 v[168:171], v155
	ds_read_b128 v[172:175], v155 offset:1024
	ds_read_b128 v[176:179], v155 offset:2048
	ds_read_b128 v[180:183], v155 offset:3072
	s_add_u32 s48, s48, 0x40000
	s_addc_u32 s49, s49, 0
	s_mov_b32 m0, s52
	ds_read_b128 v[184:187], v153 offset:32768
	ds_read_b128 v[188:191], v153 offset:33792
	ds_read_b128 v[194:197], v153 offset:34816
	ds_read_b128 v[198:201], v153 offset:35840
	ds_read_b128 v[202:205], v153 offset:36864
	ds_read_b128 v[206:209], v153 offset:37888
	ds_read_b128 v[210:213], v153 offset:38912
	ds_read_b128 v[214:217], v153 offset:39936
	global_load_lds_dwordx4 v128, s[48:49]
	s_mov_b32 m0, s53
	s_nop 0
	global_load_lds_dwordx4 v132, s[48:49]
	s_waitcnt vmcnt(8)
	s_waitcnt lgkmcnt(0)
	s_barrier
	s_waitcnt lgkmcnt(0)
	v_mfma_f32_16x16x32_bf16 v[124:127], v[144:147], v[184:187], v[124:127]
	v_mfma_f32_16x16x32_bf16 v[120:123], v[160:163], v[184:187], v[120:123]
	v_mfma_f32_16x16x32_bf16 v[108:111], v[144:147], v[194:197], v[108:111]
	v_mfma_f32_16x16x32_bf16 v[104:107], v[160:163], v[194:197], v[104:107]
	v_mfma_f32_16x16x32_bf16 v[92:95], v[144:147], v[202:205], v[92:95]
	v_mfma_f32_16x16x32_bf16 v[88:91], v[160:163], v[202:205], v[88:91]
	v_mfma_f32_16x16x32_bf16 v[76:79], v[144:147], v[210:213], v[76:79]
	v_mfma_f32_16x16x32_bf16 v[72:75], v[160:163], v[210:213], v[72:75]
	v_mfma_f32_16x16x32_bf16 v[124:127], v[156:159], v[188:191], v[124:127]
	v_mfma_f32_16x16x32_bf16 v[120:123], v[164:167], v[188:191], v[120:123]
	v_mfma_f32_16x16x32_bf16 v[108:111], v[156:159], v[198:201], v[108:111]
	v_mfma_f32_16x16x32_bf16 v[104:107], v[164:167], v[198:201], v[104:107]
	v_mfma_f32_16x16x32_bf16 v[92:95], v[156:159], v[206:209], v[92:95]
	v_mfma_f32_16x16x32_bf16 v[88:91], v[164:167], v[206:209], v[88:91]
	v_mfma_f32_16x16x32_bf16 v[76:79], v[156:159], v[214:217], v[76:79]
	v_mfma_f32_16x16x32_bf16 v[72:75], v[164:167], v[214:217], v[72:75]
	v_mfma_f32_16x16x32_bf16 v[116:119], v[168:171], v[184:187], v[116:119]
	v_mfma_f32_16x16x32_bf16 v[112:115], v[176:179], v[184:187], v[112:115]
	v_mfma_f32_16x16x32_bf16 v[100:103], v[168:171], v[194:197], v[100:103]
	v_mfma_f32_16x16x32_bf16 v[96:99], v[176:179], v[194:197], v[96:99]
	v_mfma_f32_16x16x32_bf16 v[84:87], v[168:171], v[202:205], v[84:87]
	v_mfma_f32_16x16x32_bf16 v[80:83], v[176:179], v[202:205], v[80:83]
	v_mfma_f32_16x16x32_bf16 v[68:71], v[168:171], v[210:213], v[68:71]
	v_mfma_f32_16x16x32_bf16 v[64:67], v[176:179], v[210:213], v[64:67]
	v_mfma_f32_16x16x32_bf16 v[116:119], v[172:175], v[188:191], v[116:119]
	v_mfma_f32_16x16x32_bf16 v[112:115], v[180:183], v[188:191], v[112:115]
	v_mfma_f32_16x16x32_bf16 v[100:103], v[172:175], v[198:201], v[100:103]
	v_mfma_f32_16x16x32_bf16 v[96:99], v[180:183], v[198:201], v[96:99]
	v_mfma_f32_16x16x32_bf16 v[84:87], v[172:175], v[206:209], v[84:87]
	v_mfma_f32_16x16x32_bf16 v[80:83], v[180:183], v[206:209], v[80:83]
	v_mfma_f32_16x16x32_bf16 v[68:71], v[172:175], v[214:217], v[68:71]
	v_mfma_f32_16x16x32_bf16 v[64:67], v[180:183], v[214:217], v[64:67]
	s_barrier
	s_add_i32 s48, s64, s50
	v_lshl_add_u64 v[192:193], v[192:193], 0, s[10:11]
	s_mov_b32 m0, s48
	ds_read_b128 v[184:187], v153 offset:49152
	ds_read_b128 v[188:191], v153 offset:50176
	ds_read_b128 v[194:197], v153 offset:51200
	ds_read_b128 v[198:201], v153 offset:52224
	ds_read_b128 v[202:205], v153 offset:53248
	ds_read_b128 v[206:209], v153 offset:54272
	ds_read_b128 v[210:213], v153 offset:55296
	ds_read_b128 v[214:217], v153 offset:56320
	global_load_lds_dwordx4 v[192:193], off
	s_add_i32 m0, s48, 0x2000
	s_add_u32 s44, s44, 0x40080
	v_lshl_add_u64 v[192:193], v[218:219], 0, s[10:11]
	s_addc_u32 s45, s45, 0
	s_add_i32 s48, s65, s50
	global_load_lds_dwordx4 v[192:193], off
	s_mov_b32 m0, s48
	s_nop 0
	global_load_lds_dwordx4 v130, s[44:45]
	s_add_i32 m0, s48, 0x2000
	s_nop 0
	global_load_lds_dwordx4 v134, s[44:45]
	v_lshl_add_u64 v[192:193], v[220:221], 0, s[10:11]
	s_mov_b32 m0, s57
	s_nop 0
	global_load_lds_dwordx4 v[192:193], off
	v_lshl_add_u64 v[192:193], v[222:223], 0, s[10:11]
	s_mov_b32 m0, s58
	s_nop 0
	global_load_lds_dwordx4 v[192:193], off
	s_waitcnt vmcnt(8)
	s_waitcnt lgkmcnt(0)
	s_barrier
	s_waitcnt lgkmcnt(0)
	v_mfma_f32_16x16x32_bf16 v[60:63], v[144:147], v[184:187], v[60:63]
	v_mfma_f32_16x16x32_bf16 v[56:59], v[160:163], v[184:187], v[56:59]
	v_mfma_f32_16x16x32_bf16 v[44:47], v[144:147], v[194:197], v[44:47]
	v_mfma_f32_16x16x32_bf16 v[40:43], v[160:163], v[194:197], v[40:43]
	v_mfma_f32_16x16x32_bf16 v[28:31], v[144:147], v[202:205], v[28:31]
	v_mfma_f32_16x16x32_bf16 v[24:27], v[160:163], v[202:205], v[24:27]
	v_mfma_f32_16x16x32_bf16 v[12:15], v[144:147], v[210:213], v[12:15]
	v_mfma_f32_16x16x32_bf16 v[8:11], v[160:163], v[210:213], v[8:11]
	v_mfma_f32_16x16x32_bf16 v[60:63], v[156:159], v[188:191], v[60:63]
	v_mfma_f32_16x16x32_bf16 v[56:59], v[164:167], v[188:191], v[56:59]
	v_mfma_f32_16x16x32_bf16 v[44:47], v[156:159], v[198:201], v[44:47]
	v_mfma_f32_16x16x32_bf16 v[40:43], v[164:167], v[198:201], v[40:43]
	v_mfma_f32_16x16x32_bf16 v[28:31], v[156:159], v[206:209], v[28:31]
	v_mfma_f32_16x16x32_bf16 v[24:27], v[164:167], v[206:209], v[24:27]
	v_mfma_f32_16x16x32_bf16 v[12:15], v[156:159], v[214:217], v[12:15]
	v_mfma_f32_16x16x32_bf16 v[8:11], v[164:167], v[214:217], v[8:11]
	v_mfma_f32_16x16x32_bf16 v[52:55], v[168:171], v[184:187], v[52:55]
	v_mfma_f32_16x16x32_bf16 v[48:51], v[176:179], v[184:187], v[48:51]
	v_mfma_f32_16x16x32_bf16 v[36:39], v[168:171], v[194:197], v[36:39]
	v_mfma_f32_16x16x32_bf16 v[32:35], v[176:179], v[194:197], v[32:35]
	v_mfma_f32_16x16x32_bf16 v[20:23], v[168:171], v[202:205], v[20:23]
	v_mfma_f32_16x16x32_bf16 v[16:19], v[176:179], v[202:205], v[16:19]
	v_mfma_f32_16x16x32_bf16 v[4:7], v[168:171], v[210:213], v[4:7]
	v_mfma_f32_16x16x32_bf16 v[0:3], v[176:179], v[210:213], v[0:3]
	v_mfma_f32_16x16x32_bf16 v[52:55], v[172:175], v[188:191], v[52:55]
	v_mfma_f32_16x16x32_bf16 v[48:51], v[180:183], v[188:191], v[48:51]
	v_mfma_f32_16x16x32_bf16 v[36:39], v[172:175], v[198:201], v[36:39]
	v_mfma_f32_16x16x32_bf16 v[32:35], v[180:183], v[198:201], v[32:35]
	v_mfma_f32_16x16x32_bf16 v[20:23], v[172:175], v[206:209], v[20:23]
	v_mfma_f32_16x16x32_bf16 v[16:19], v[180:183], v[206:209], v[16:19]
	v_mfma_f32_16x16x32_bf16 v[4:7], v[172:175], v[214:217], v[4:7]
	v_mfma_f32_16x16x32_bf16 v[0:3], v[180:183], v[214:217], v[0:3]
	s_barrier
	s_add_i32 s63, s63, 2
	s_add_u32 s40, s40, 0x100
	s_addc_u32 s41, s41, 0
	s_add_u32 s42, s42, 0x100
	s_addc_u32 s62, s62, 0
	s_cmp_gt_u32 s63, 13
	s_cbranch_scc0 .LBB0_724
	s_and_b64 vcc, exec, s[12:13]
	s_cbranch_vccz .LBB0_727
	s_barrier
